# v28 + GATE epilogue: o-tile and row-scale loads of each 8-column block hoisted to the block head (one memory round trip per block instead of two/three)
# speedup vs baseline: 1.0186x; 1.0094x over previous
; DI unsigned pk(float lo, float hi) { f32x2 v = {lo, hi}; bf2_t b = __builtin_convertvector(v, bf2_t); return __builtin_bit_cast(unsigned, b); }
; DI float bflo(unsigned w) { return __uint_as_float(w << 16); }
; DI float bfhi(unsigned w) { return __uint_as_float(w & 0xffff0000u); }
; DI float sigmoidf_(float x) { return 1.0f / (1.0f + __expf(-x)); }
; DI void gemm_epilogue(const GemmDesc& g, f32x4 (&acc)[2][2][4][2], int brow, int bcol, int wr, int wc, int fr, int fq) {
;     ...
;           const int row = rowb + ai * HALF + m * 16;
;           float rs;
;           { const float* sp = g.f0 + (size_t)row * 32 + head * 8;
;             const f32x4 s0 = gld<f32x4>(sp); float ssum = (s0[0] + s0[1]) + (s0[2] + s0[3]);
;             if (g.dvshift == 9) { const f32x4 s1 = gld<f32x4>(sp + 4); ssum += (s1[0] + s1[1]) + (s1[2] + s1[3]); }
;             rs = rsqrtf(ssum * (g.dvshift == 9 ? (1.0f / 512.0f) : (1.0f / 256.0f)) + EPS); }
;           bf16_t* op = g.o0 + (size_t)row * N + col;
;           const u32x4 ow = gld<u32x4>(op);
;           const float ru = gld<float>(g.rowscale + row);
;           const f32x4 v0 = acc[ai][bj][m][0] * ru, v1 = acc[ai][bj][m][1] * ru;
;           float o[8] = {bflo(ow.x), bfhi(ow.x), bflo(ow.y), bfhi(ow.y), bflo(ow.z), bfhi(ow.z), bflo(ow.w), bfhi(ow.w)};
; #pragma unroll
;           for (int j = 0; j < 4; ++j) { o[j] = o[j] * rs * g0[j] * v0[j] * sigmoidf_(v0[j]); o[4 + j] = o[4 + j] * rs * g1[j] * v1[j] * sigmoidf_(v1[j]); }
;           u32x4 w; w.x = pk(o[0], o[1]); w.y = pk(o[2], o[3]); w.z = pk(o[4], o[5]); w.w = pk(o[6], o[7]);
;           gst<u32x4>(op, w);
.LBB0_221:
	v_fma_f32 v136, s27, v138, v204
	v_cmp_gt_f32_e32 vcc, s33, v136
	v_mul_f32_e32 v137, 0x4b800000, v136
	v_ashrrev_i32_e32 v165, 31, v164
	v_cndmask_b32_e32 v136, v136, v137, vcc
	v_rsq_f32_e32 v136, v136
	v_lshl_add_u64 v[140:141], v[166:167], 2, s[22:23]
	global_load_dword v168, v[140:141], off
	v_mul_f32_e32 v137, 0x45800000, v136
	v_cndmask_b32_e32 v148, v136, v137, vcc
	v_mad_u64_u32 v[136:137], vcc, v166, s70, 0
	v_mov_b32_e32 v138, v137
	v_mad_u64_u32 v[138:139], vcc, v167, s70, v[138:139]
	v_mov_b32_e32 v137, v138
	v_lshl_add_u64 v[136:137], v[136:137], 1, s[64:65]
	v_lshl_add_u64 v[142:143], v[164:165], 1, v[136:137]
	global_load_dwordx4 v[136:139], v[142:143], off
	s_waitcnt vmcnt(1)
	v_pk_mul_f32 v[172:173], v[124:125], v[168:169] op_sel_hi:[1,0]
	s_waitcnt vmcnt(0)
	v_lshlrev_b32_e32 v170, 16, v136
	v_and_b32_e32 v171, 0xffff0000, v136
	v_mul_f32_e32 v136, 0xbfb8aa3b, v172
	v_exp_f32_e32 v174, v136
	v_mul_f32_e32 v136, 0xbfb8aa3b, v173
	v_exp_f32_e32 v175, v136
	v_pk_mul_f32 v[170:171], v[148:149], v[170:171] op_sel_hi:[0,1]
	v_pk_mul_f32 v[170:171], v[132:133], v[170:171]
	s_nop 0
	v_pk_mul_f32 v[170:171], v[172:173], v[170:171]
	v_pk_add_f32 v[172:173], v[174:175], 1.0 op_sel_hi:[1,0]
	s_nop 0
	v_div_scale_f32 v136, vcc, v173, v173, 1.0
	v_rcp_f32_e32 v167, v136
	s_nop 0
	v_fma_f32 v169, -v136, v167, 1.0
	v_fmac_f32_e32 v167, v169, v167
	v_div_scale_f32 v169, vcc, 1.0, v173, 1.0
	v_mul_f32_e32 v174, v169, v167
	v_fma_f32 v175, -v136, v174, v169
	v_fmac_f32_e32 v174, v175, v167
	v_fma_f32 v136, -v136, v174, v169
	v_div_fmas_f32 v136, v136, v167, v174
	v_div_fixup_f32 v173, v136, v173, 1.0
	v_div_scale_f32 v136, vcc, v172, v172, 1.0
	v_rcp_f32_e32 v167, v136
	s_nop 0
	v_fma_f32 v169, -v136, v167, 1.0
	v_fmac_f32_e32 v167, v169, v167
	v_div_scale_f32 v169, vcc, 1.0, v172, 1.0
	v_mul_f32_e32 v174, v169, v167
	v_fma_f32 v175, -v136, v174, v169
	v_fmac_f32_e32 v174, v175, v167
	v_fma_f32 v136, -v136, v174, v169
	v_div_fmas_f32 v136, v136, v167, v174
	v_pk_mul_f32 v[174:175], v[120:121], v[168:169] op_sel_hi:[1,0]
	v_div_fixup_f32 v172, v136, v172, 1.0
	v_mul_f32_e32 v136, 0xbfb8aa3b, v174
	v_exp_f32_e32 v176, v136
	v_mul_f32_e32 v136, 0xbfb8aa3b, v175
	v_exp_f32_e32 v177, v136
	v_pk_mul_f32 v[170:171], v[172:173], v[170:171]
	v_lshlrev_b32_e32 v172, 16, v138
	v_and_b32_e32 v173, 0xffff0000, v138
	v_pk_mul_f32 v[172:173], v[148:149], v[172:173] op_sel_hi:[0,1]
	v_pk_mul_f32 v[172:173], v[128:129], v[172:173]
	s_nop 0
	v_pk_mul_f32 v[172:173], v[174:175], v[172:173]
	v_pk_add_f32 v[174:175], v[176:177], 1.0 op_sel_hi:[1,0]
	s_nop 0
	v_div_scale_f32 v136, vcc, v175, v175, 1.0
	v_rcp_f32_e32 v138, v136
	s_nop 0
	v_fma_f32 v167, -v136, v138, 1.0
	v_fmac_f32_e32 v138, v167, v138
	v_div_scale_f32 v167, vcc, 1.0, v175, 1.0
	v_mul_f32_e32 v169, v167, v138
	v_fma_f32 v176, -v136, v169, v167
	v_fmac_f32_e32 v169, v176, v138
	v_fma_f32 v136, -v136, v169, v167
	v_div_fmas_f32 v136, v136, v138, v169
	v_div_fixup_f32 v175, v136, v175, 1.0
	v_div_scale_f32 v136, vcc, v174, v174, 1.0
	v_rcp_f32_e32 v138, v136
	s_nop 0
	v_fma_f32 v167, -v136, v138, 1.0
	v_fmac_f32_e32 v138, v167, v138
	v_div_scale_f32 v167, vcc, 1.0, v174, 1.0
	v_mul_f32_e32 v169, v167, v138
	v_fma_f32 v176, -v136, v169, v167
	v_fmac_f32_e32 v169, v176, v138
	v_fma_f32 v136, -v136, v169, v167
	v_div_fmas_f32 v136, v136, v138, v169
	v_pk_mul_f32 v[176:177], v[126:127], v[168:169] op_sel_hi:[1,0]
	v_div_fixup_f32 v174, v136, v174, 1.0
	v_mul_f32_e32 v138, 0xbfb8aa3b, v176
	v_pk_mul_f32 v[172:173], v[174:175], v[172:173]
	v_exp_f32_e32 v174, v138
	v_mul_f32_e32 v138, 0xbfb8aa3b, v177
	v_exp_f32_e32 v175, v138
	v_lshlrev_b32_e32 v136, 16, v137
	v_and_b32_e32 v137, 0xffff0000, v137
	v_pk_mul_f32 v[136:137], v[148:149], v[136:137] op_sel_hi:[0,1]
	v_pk_add_f32 v[174:175], v[174:175], 1.0 op_sel_hi:[1,0]
	v_pk_mul_f32 v[136:137], v[134:135], v[136:137]
	v_div_scale_f32 v138, vcc, v175, v175, 1.0
	v_rcp_f32_e32 v167, v138
	v_pk_mul_f32 v[136:137], v[176:177], v[136:137]
	v_fma_f32 v169, -v138, v167, 1.0
	v_fmac_f32_e32 v167, v169, v167
	v_div_scale_f32 v169, vcc, 1.0, v175, 1.0
	v_mul_f32_e32 v176, v169, v167
	v_fma_f32 v177, -v138, v176, v169
	v_fmac_f32_e32 v176, v177, v167
	v_fma_f32 v138, -v138, v176, v169
	v_div_fmas_f32 v138, v138, v167, v176
	v_div_fixup_f32 v175, v138, v175, 1.0
	v_div_scale_f32 v138, vcc, v174, v174, 1.0
	v_rcp_f32_e32 v167, v138
	s_nop 0
	v_fma_f32 v169, -v138, v167, 1.0
	v_fmac_f32_e32 v167, v169, v167
	v_div_scale_f32 v169, vcc, 1.0, v174, 1.0
	v_mul_f32_e32 v176, v169, v167
	v_fma_f32 v177, -v138, v176, v169
	v_fmac_f32_e32 v176, v177, v167
	v_fma_f32 v138, -v138, v176, v169
	v_div_fmas_f32 v138, v138, v167, v176
	v_div_fixup_f32 v174, v138, v174, 1.0
	v_pk_mul_f32 v[174:175], v[174:175], v[136:137]
	v_lshlrev_b32_e32 v136, 16, v139
	v_and_b32_e32 v137, 0xffff0000, v139
	v_pk_mul_f32 v[136:137], v[148:149], v[136:137] op_sel_hi:[0,1]
	v_pk_mul_f32 v[138:139], v[122:123], v[168:169] op_sel_hi:[1,0]
	v_pk_mul_f32 v[136:137], v[130:131], v[136:137]
	v_mul_f32_e32 v167, 0xbfb8aa3b, v138
	v_pk_mul_f32 v[136:137], v[138:139], v[136:137]
	v_mul_f32_e32 v138, 0xbfb8aa3b, v139
	v_exp_f32_e32 v168, v167
	v_exp_f32_e32 v169, v138
	s_nop 0
	v_pk_add_f32 v[138:139], v[168:169], 1.0 op_sel_hi:[1,0]
	s_nop 0
	v_div_scale_f32 v148, vcc, v139, v139, 1.0
	v_rcp_f32_e32 v167, v148
	s_nop 0
	v_fma_f32 v168, -v148, v167, 1.0
	v_fmac_f32_e32 v167, v168, v167
	v_div_scale_f32 v168, vcc, 1.0, v139, 1.0
	v_mul_f32_e32 v169, v168, v167
	v_fma_f32 v176, -v148, v169, v168
	v_fmac_f32_e32 v169, v176, v167
	v_fma_f32 v148, -v148, v169, v168
	v_div_fmas_f32 v148, v148, v167, v169
; DI unsigned pk(float lo, float hi) { f32x2 v = {lo, hi}; bf2_t b = __builtin_convertvector(v, bf2_t); return __builtin_bit_cast(unsigned, b); }
; DI float bflo(unsigned w) { return __uint_as_float(w << 16); }
; DI float bfhi(unsigned w) { return __uint_as_float(w & 0xffff0000u); }
; DI float sigmoidf_(float x) { return 1.0f / (1.0f + __expf(-x)); }
; DI void gemm_epilogue(const GemmDesc& g, f32x4 (&acc)[2][2][4][2], int brow, int bcol, int wr, int wc, int fr, int fq) {
;     ...
;           const int row = rowb + ai * HALF + m * 16;
;           float rs;
;           { const float* sp = g.f0 + (size_t)row * 32 + head * 8;
;             const f32x4 s0 = gld<f32x4>(sp); float ssum = (s0[0] + s0[1]) + (s0[2] + s0[3]);
;             if (g.dvshift == 9) { const f32x4 s1 = gld<f32x4>(sp + 4); ssum += (s1[0] + s1[1]) + (s1[2] + s1[3]); }
;             rs = rsqrtf(ssum * (g.dvshift == 9 ? (1.0f / 512.0f) : (1.0f / 256.0f)) + EPS); }
;           bf16_t* op = g.o0 + (size_t)row * N + col;
;           const u32x4 ow = gld<u32x4>(op);
;           const float ru = gld<float>(g.rowscale + row);
;           const f32x4 v0 = acc[ai][bj][m][0] * ru, v1 = acc[ai][bj][m][1] * ru;
;           float o[8] = {bflo(ow.x), bfhi(ow.x), bflo(ow.y), bfhi(ow.y), bflo(ow.z), bfhi(ow.z), bflo(ow.w), bfhi(ow.w)};
; #pragma unroll
;           for (int j = 0; j < 4; ++j) { o[j] = o[j] * rs * g0[j] * v0[j] * sigmoidf_(v0[j]); o[4 + j] = o[4 + j] * rs * g1[j] * v1[j] * sigmoidf_(v1[j]); }
;           u32x4 w; w.x = pk(o[0], o[1]); w.y = pk(o[2], o[3]); w.z = pk(o[4], o[5]); w.w = pk(o[6], o[7]);
;           gst<u32x4>(op, w);
	v_div_fixup_f32 v139, v148, v139, 1.0
	v_div_scale_f32 v148, vcc, v138, v138, 1.0
	v_rcp_f32_e32 v167, v148
	s_nop 0
	v_fma_f32 v168, -v148, v167, 1.0
	v_fmac_f32_e32 v167, v168, v167
	v_div_scale_f32 v168, vcc, 1.0, v138, 1.0
	v_mul_f32_e32 v169, v168, v167
	v_fma_f32 v176, -v148, v169, v168
	v_fmac_f32_e32 v169, v176, v167
	v_fma_f32 v148, -v148, v169, v168
	v_div_fmas_f32 v148, v148, v167, v169
	v_div_fixup_f32 v138, v148, v138, 1.0
	v_pk_mul_f32 v[168:169], v[138:139], v[136:137]
	v_cvt_pk_bf16_f32 v136, v170, v171
	v_cvt_pk_bf16_f32 v137, v174, v175
	v_cvt_pk_bf16_f32 v138, v172, v173
	v_cvt_pk_bf16_f32 v139, v168, v169
	global_store_dwordx4 v[142:143], v[136:139], off
	s_and_b64 vcc, exec, s[44:45]
	s_nop 0
	v_or_b32_e32 v136, 16, v166
	v_ashrrev_i32_e32 v137, 31, v136
	v_lshlrev_b64 v[138:139], 7, v[136:137]
	v_lshl_add_u64 v[184:185], s[66:67], 0, v[138:139]
	v_lshl_add_u64 v[168:169], v[180:181], 2, v[184:185]
	global_load_dwordx4 v[170:173], v[168:169], off
	global_load_dwordx4 v[232:235], v[168:169], off offset:16
	v_mad_u64_u32 v[238:239], s[100:101], v136, s70, 0
	v_mov_b32_e32 v240, v239
	v_mad_u64_u32 v[240:241], s[100:101], v137, s70, v[240:241]
	v_mov_b32_e32 v239, v240
	v_lshl_add_u64 v[238:239], v[238:239], 1, s[64:65]
	v_lshl_add_u64 v[236:237], v[164:165], 1, v[238:239]
	global_load_dwordx4 v[242:245], v[236:237], off
	global_load_dword v246, v[140:141], off offset:64
	s_waitcnt vmcnt(0)
	v_mov_b32_e32 v138, v171
	v_mov_b32_e32 v139, v172
	v_mov_b32_e32 v171, v173
	v_pk_add_f32 v[138:139], v[138:139], v[170:171]
	s_nop 0
	v_pk_add_f32 v[138:139], v[138:139], v[138:139] op_sel:[0,1] op_sel_hi:[1,0]
	s_cbranch_vccnz .LBB0_223
	v_mov_b64_e32 v[168:169], v[232:233]
	v_mov_b64_e32 v[170:171], v[234:235]
	s_mov_b32 s26, 0x3b000000
	v_mov_b32_e32 v172, v169
	v_mov_b32_e32 v173, v170
	v_mov_b32_e32 v169, v171
	v_pk_add_f32 v[168:169], v[172:173], v[168:169]
	s_nop 0
	v_add_f32_e32 v139, v168, v169
	v_add_f32_e32 v138, v138, v139
.LBB0_223:
	v_fma_f32 v138, s26, v138, v204
	v_cmp_gt_f32_e32 vcc, s33, v138
	v_mul_f32_e32 v139, 0x4b800000, v138
	s_nop 0
	v_cndmask_b32_e32 v138, v138, v139, vcc
	v_rsq_f32_e32 v138, v138
	s_nop 0
	v_mul_f32_e32 v139, 0x45800000, v138
	v_cndmask_b32_e32 v148, v138, v139, vcc
	v_mad_u64_u32 v[138:139], s[26:27], v136, s70, 0
	v_mov_b32_e32 v136, v139
	v_mad_u64_u32 v[136:137], s[26:27], v137, s70, v[136:137]
	v_mov_b32_e32 v139, v136
	v_lshl_add_u64 v[136:137], v[138:139], 1, s[64:65]
	v_lshl_add_u64 v[168:169], v[164:165], 1, v[136:137]
	v_mov_b64_e32 v[136:137], v[242:243]
	v_mov_b64_e32 v[138:139], v[244:245]
	v_mov_b32_e32 v170, v246
	v_lshlrev_b32_e32 v172, 16, v136
	v_pk_mul_f32 v[174:175], v[116:117], v[170:171] op_sel_hi:[1,0]
	v_and_b32_e32 v173, 0xffff0000, v136
	v_mul_f32_e32 v136, 0xbfb8aa3b, v174
	v_exp_f32_e32 v176, v136
	v_mul_f32_e32 v136, 0xbfb8aa3b, v175
	v_exp_f32_e32 v177, v136
	v_pk_mul_f32 v[172:173], v[148:149], v[172:173] op_sel_hi:[0,1]
	v_pk_mul_f32 v[172:173], v[132:133], v[172:173]
	s_nop 0
	v_pk_mul_f32 v[172:173], v[174:175], v[172:173]
	v_pk_add_f32 v[174:175], v[176:177], 1.0 op_sel_hi:[1,0]
	s_nop 0
	v_div_scale_f32 v136, s[26:27], v175, v175, 1.0
	v_rcp_f32_e32 v167, v136
	s_nop 0
	v_fma_f32 v171, -v136, v167, 1.0
	v_fmac_f32_e32 v167, v171, v167
	v_div_scale_f32 v171, vcc, 1.0, v175, 1.0
	v_mul_f32_e32 v176, v171, v167
	v_fma_f32 v177, -v136, v176, v171
	v_fmac_f32_e32 v176, v177, v167
	v_fma_f32 v136, -v136, v176, v171
	v_div_fmas_f32 v136, v136, v167, v176
	v_div_fixup_f32 v175, v136, v175, 1.0
	v_div_scale_f32 v136, s[26:27], v174, v174, 1.0
	v_rcp_f32_e32 v167, v136
	s_nop 0
	v_fma_f32 v171, -v136, v167, 1.0
	v_fmac_f32_e32 v167, v171, v167
	v_div_scale_f32 v171, vcc, 1.0, v174, 1.0
	v_mul_f32_e32 v176, v171, v167
	v_fma_f32 v177, -v136, v176, v171
	v_fmac_f32_e32 v176, v177, v167
	v_fma_f32 v136, -v136, v176, v171
	v_div_fmas_f32 v136, v136, v167, v176
	v_pk_mul_f32 v[176:177], v[112:113], v[170:171] op_sel_hi:[1,0]
	v_div_fixup_f32 v174, v136, v174, 1.0
	v_mul_f32_e32 v136, 0xbfb8aa3b, v176
	v_exp_f32_e32 v178, v136
	v_mul_f32_e32 v136, 0xbfb8aa3b, v177
	v_exp_f32_e32 v179, v136
	v_pk_mul_f32 v[172:173], v[174:175], v[172:173]
	v_lshlrev_b32_e32 v174, 16, v138
	v_and_b32_e32 v175, 0xffff0000, v138
	v_pk_mul_f32 v[174:175], v[148:149], v[174:175] op_sel_hi:[0,1]
	v_pk_mul_f32 v[174:175], v[128:129], v[174:175]
	s_nop 0
	v_pk_mul_f32 v[174:175], v[176:177], v[174:175]
	v_pk_add_f32 v[176:177], v[178:179], 1.0 op_sel_hi:[1,0]
	s_nop 0
	v_div_scale_f32 v136, s[26:27], v177, v177, 1.0
	v_rcp_f32_e32 v138, v136
	s_nop 0
	v_fma_f32 v167, -v136, v138, 1.0
	v_fmac_f32_e32 v138, v167, v138
	v_div_scale_f32 v167, vcc, 1.0, v177, 1.0
	v_mul_f32_e32 v171, v167, v138
	v_fma_f32 v178, -v136, v171, v167
	v_fmac_f32_e32 v171, v178, v138
	v_fma_f32 v136, -v136, v171, v167
	v_div_fmas_f32 v136, v136, v138, v171
	v_div_fixup_f32 v177, v136, v177, 1.0
	v_div_scale_f32 v136, s[26:27], v176, v176, 1.0
	v_rcp_f32_e32 v138, v136
	s_nop 0
	v_fma_f32 v167, -v136, v138, 1.0
	v_fmac_f32_e32 v138, v167, v138
	v_div_scale_f32 v167, vcc, 1.0, v176, 1.0
	v_mul_f32_e32 v171, v167, v138
	v_fma_f32 v178, -v136, v171, v167
	v_fmac_f32_e32 v171, v178, v138
	v_fma_f32 v136, -v136, v171, v167
	v_div_fmas_f32 v136, v136, v138, v171
	v_pk_mul_f32 v[178:179], v[118:119], v[170:171] op_sel_hi:[1,0]
	v_div_fixup_f32 v176, v136, v176, 1.0
	v_mul_f32_e32 v138, 0xbfb8aa3b, v178
	v_pk_mul_f32 v[174:175], v[176:177], v[174:175]
	v_exp_f32_e32 v176, v138
	v_mul_f32_e32 v138, 0xbfb8aa3b, v179
	v_exp_f32_e32 v177, v138
	v_lshlrev_b32_e32 v136, 16, v137
	v_and_b32_e32 v137, 0xffff0000, v137
; DI unsigned pk(float lo, float hi) { f32x2 v = {lo, hi}; bf2_t b = __builtin_convertvector(v, bf2_t); return __builtin_bit_cast(unsigned, b); }
; DI float bflo(unsigned w) { return __uint_as_float(w << 16); }
; DI float bfhi(unsigned w) { return __uint_as_float(w & 0xffff0000u); }
; DI float sigmoidf_(float x) { return 1.0f / (1.0f + __expf(-x)); }
; DI void gemm_epilogue(const GemmDesc& g, f32x4 (&acc)[2][2][4][2], int brow, int bcol, int wr, int wc, int fr, int fq) {
;     ...
;           const int row = rowb + ai * HALF + m * 16;
;           float rs;
;           { const float* sp = g.f0 + (size_t)row * 32 + head * 8;
;             const f32x4 s0 = gld<f32x4>(sp); float ssum = (s0[0] + s0[1]) + (s0[2] + s0[3]);
;             if (g.dvshift == 9) { const f32x4 s1 = gld<f32x4>(sp + 4); ssum += (s1[0] + s1[1]) + (s1[2] + s1[3]); }
;             rs = rsqrtf(ssum * (g.dvshift == 9 ? (1.0f / 512.0f) : (1.0f / 256.0f)) + EPS); }
;           bf16_t* op = g.o0 + (size_t)row * N + col;
;           const u32x4 ow = gld<u32x4>(op);
;           const float ru = gld<float>(g.rowscale + row);
;           const f32x4 v0 = acc[ai][bj][m][0] * ru, v1 = acc[ai][bj][m][1] * ru;
;           float o[8] = {bflo(ow.x), bfhi(ow.x), bflo(ow.y), bfhi(ow.y), bflo(ow.z), bfhi(ow.z), bflo(ow.w), bfhi(ow.w)};
; #pragma unroll
;           for (int j = 0; j < 4; ++j) { o[j] = o[j] * rs * g0[j] * v0[j] * sigmoidf_(v0[j]); o[4 + j] = o[4 + j] * rs * g1[j] * v1[j] * sigmoidf_(v1[j]); }
;           u32x4 w; w.x = pk(o[0], o[1]); w.y = pk(o[2], o[3]); w.z = pk(o[4], o[5]); w.w = pk(o[6], o[7]);
;           gst<u32x4>(op, w);
	v_pk_mul_f32 v[136:137], v[148:149], v[136:137] op_sel_hi:[0,1]
	v_pk_add_f32 v[176:177], v[176:177], 1.0 op_sel_hi:[1,0]
	v_pk_mul_f32 v[136:137], v[134:135], v[136:137]
	v_div_scale_f32 v138, s[26:27], v177, v177, 1.0
	v_rcp_f32_e32 v167, v138
	v_pk_mul_f32 v[136:137], v[178:179], v[136:137]
	v_fma_f32 v171, -v138, v167, 1.0
	v_fmac_f32_e32 v167, v171, v167
	v_div_scale_f32 v171, vcc, 1.0, v177, 1.0
	v_mul_f32_e32 v178, v171, v167
	v_fma_f32 v179, -v138, v178, v171
	v_fmac_f32_e32 v178, v179, v167
	v_fma_f32 v138, -v138, v178, v171
	v_div_fmas_f32 v138, v138, v167, v178
	v_div_fixup_f32 v177, v138, v177, 1.0
	v_div_scale_f32 v138, s[26:27], v176, v176, 1.0
	v_rcp_f32_e32 v167, v138
	s_nop 0
	v_fma_f32 v171, -v138, v167, 1.0
	v_fmac_f32_e32 v167, v171, v167
	v_div_scale_f32 v171, vcc, 1.0, v176, 1.0
	v_mul_f32_e32 v178, v171, v167
	v_fma_f32 v179, -v138, v178, v171
	v_fmac_f32_e32 v178, v179, v167
	v_fma_f32 v138, -v138, v178, v171
	v_div_fmas_f32 v138, v138, v167, v178
	v_div_fixup_f32 v176, v138, v176, 1.0
	v_pk_mul_f32 v[176:177], v[176:177], v[136:137]
	v_lshlrev_b32_e32 v136, 16, v139
	v_and_b32_e32 v137, 0xffff0000, v139
	v_pk_mul_f32 v[136:137], v[148:149], v[136:137] op_sel_hi:[0,1]
	v_pk_mul_f32 v[138:139], v[114:115], v[170:171] op_sel_hi:[1,0]
	v_pk_mul_f32 v[136:137], v[130:131], v[136:137]
	v_mul_f32_e32 v167, 0xbfb8aa3b, v138
	v_pk_mul_f32 v[136:137], v[138:139], v[136:137]
	v_mul_f32_e32 v138, 0xbfb8aa3b, v139
	v_exp_f32_e32 v170, v167
	v_exp_f32_e32 v171, v138
	s_nop 0
	v_pk_add_f32 v[138:139], v[170:171], 1.0 op_sel_hi:[1,0]
	s_nop 0
	v_div_scale_f32 v148, s[26:27], v139, v139, 1.0
	v_rcp_f32_e32 v167, v148
	s_nop 0
	v_fma_f32 v170, -v148, v167, 1.0
	v_fmac_f32_e32 v167, v170, v167
	v_div_scale_f32 v170, vcc, 1.0, v139, 1.0
	v_mul_f32_e32 v171, v170, v167
	v_fma_f32 v178, -v148, v171, v170
	v_fmac_f32_e32 v171, v178, v167
	v_fma_f32 v148, -v148, v171, v170
	v_div_fmas_f32 v148, v148, v167, v171
	v_div_fixup_f32 v139, v148, v139, 1.0
	v_div_scale_f32 v148, s[26:27], v138, v138, 1.0
	v_rcp_f32_e32 v167, v148
	s_mov_b32 s26, 0x3b800000
	s_mov_b32 s27, 0x3b800000
	v_fma_f32 v170, -v148, v167, 1.0
	v_fmac_f32_e32 v167, v170, v167
	v_div_scale_f32 v170, vcc, 1.0, v138, 1.0
	v_mul_f32_e32 v171, v170, v167
	v_fma_f32 v178, -v148, v171, v170
	v_fmac_f32_e32 v171, v178, v167
	v_fma_f32 v148, -v148, v171, v170
	v_div_fmas_f32 v148, v148, v167, v171
	v_div_fixup_f32 v138, v148, v138, 1.0
	v_pk_mul_f32 v[170:171], v[138:139], v[136:137]
	v_cvt_pk_bf16_f32 v136, v172, v173
	v_cvt_pk_bf16_f32 v137, v176, v177
	v_cvt_pk_bf16_f32 v138, v174, v175
	v_cvt_pk_bf16_f32 v139, v170, v171
	global_store_dwordx4 v[168:169], v[136:139], off
	s_and_b64 vcc, exec, s[44:45]
	s_nop 0
	v_or_b32_e32 v136, 32, v166
	v_ashrrev_i32_e32 v137, 31, v136
	v_lshlrev_b64 v[138:139], 7, v[136:137]
	v_lshl_add_u64 v[186:187], s[66:67], 0, v[138:139]
	v_lshl_add_u64 v[170:171], v[180:181], 2, v[186:187]
	global_load_dwordx4 v[172:175], v[170:171], off
	global_load_dwordx4 v[232:235], v[170:171], off offset:16
	v_mad_u64_u32 v[238:239], s[100:101], v136, s70, 0
	v_mov_b32_e32 v240, v239
	v_mad_u64_u32 v[240:241], s[100:101], v137, s70, v[240:241]
	v_mov_b32_e32 v239, v240
	v_lshl_add_u64 v[238:239], v[238:239], 1, s[64:65]
	v_lshl_add_u64 v[236:237], v[164:165], 1, v[238:239]
	global_load_dwordx4 v[242:245], v[236:237], off
	global_load_dword v246, v[140:141], off offset:128
	s_waitcnt vmcnt(0)
	v_mov_b32_e32 v138, v173
	v_mov_b32_e32 v139, v174
	v_mov_b32_e32 v173, v175
	v_pk_add_f32 v[138:139], v[138:139], v[172:173]
	s_nop 0
	v_pk_add_f32 v[138:139], v[138:139], v[138:139] op_sel:[0,1] op_sel_hi:[1,0]
	s_cbranch_vccnz .LBB0_225
	v_mov_b64_e32 v[170:171], v[232:233]
	v_mov_b64_e32 v[172:173], v[234:235]
	s_mov_b32 s27, 0x3b000000
	v_mov_b32_e32 v174, v171
	v_mov_b32_e32 v175, v172
	v_mov_b32_e32 v171, v173
	v_pk_add_f32 v[170:171], v[174:175], v[170:171]
	s_nop 0
	v_add_f32_e32 v139, v170, v171
	v_add_f32_e32 v138, v138, v139
.LBB0_225:
	v_fma_f32 v138, s27, v138, v204
	v_cmp_gt_f32_e32 vcc, s33, v138
	v_mul_f32_e32 v139, 0x4b800000, v138
	s_nop 0
	v_cndmask_b32_e32 v138, v138, v139, vcc
	v_rsq_f32_e32 v138, v138
	s_nop 0
	v_mul_f32_e32 v139, 0x45800000, v138
	v_cndmask_b32_e32 v148, v138, v139, vcc
	v_mad_u64_u32 v[138:139], vcc, v136, s70, 0
	v_mov_b32_e32 v136, v139
	v_mad_u64_u32 v[136:137], vcc, v137, s70, v[136:137]
	v_mov_b32_e32 v139, v136
	v_lshl_add_u64 v[136:137], v[138:139], 1, s[64:65]
	v_lshl_add_u64 v[170:171], v[164:165], 1, v[136:137]
	v_mov_b64_e32 v[136:137], v[242:243]
	v_mov_b64_e32 v[138:139], v[244:245]
	v_mov_b32_e32 v172, v246
	v_lshlrev_b32_e32 v174, 16, v136
	v_pk_mul_f32 v[176:177], v[108:109], v[172:173] op_sel_hi:[1,0]
	v_and_b32_e32 v175, 0xffff0000, v136
	v_mul_f32_e32 v136, 0xbfb8aa3b, v176
	v_exp_f32_e32 v178, v136
	v_mul_f32_e32 v136, 0xbfb8aa3b, v177
	v_exp_f32_e32 v179, v136
	v_pk_mul_f32 v[174:175], v[148:149], v[174:175] op_sel_hi:[0,1]
	v_pk_mul_f32 v[174:175], v[132:133], v[174:175]
	s_nop 0
	v_pk_mul_f32 v[174:175], v[176:177], v[174:175]
	v_pk_add_f32 v[176:177], v[178:179], 1.0 op_sel_hi:[1,0]
	s_nop 0
	v_div_scale_f32 v136, vcc, v177, v177, 1.0
	v_rcp_f32_e32 v167, v136
	s_nop 0
	v_fma_f32 v173, -v136, v167, 1.0
	v_fmac_f32_e32 v167, v173, v167
	v_div_scale_f32 v173, vcc, 1.0, v177, 1.0
	v_mul_f32_e32 v178, v173, v167
	v_fma_f32 v179, -v136, v178, v173
	v_fmac_f32_e32 v178, v179, v167
	v_fma_f32 v136, -v136, v178, v173
	v_div_fmas_f32 v136, v136, v167, v178
	v_div_fixup_f32 v177, v136, v177, 1.0
	v_div_scale_f32 v136, vcc, v176, v176, 1.0
	v_rcp_f32_e32 v167, v136
	s_nop 0
	v_fma_f32 v173, -v136, v167, 1.0
; DI unsigned pk(float lo, float hi) { f32x2 v = {lo, hi}; bf2_t b = __builtin_convertvector(v, bf2_t); return __builtin_bit_cast(unsigned, b); }
; DI float bflo(unsigned w) { return __uint_as_float(w << 16); }
; DI float bfhi(unsigned w) { return __uint_as_float(w & 0xffff0000u); }
; DI float sigmoidf_(float x) { return 1.0f / (1.0f + __expf(-x)); }
; DI void gemm_epilogue(const GemmDesc& g, f32x4 (&acc)[2][2][4][2], int brow, int bcol, int wr, int wc, int fr, int fq) {
;     ...
;           const int row = rowb + ai * HALF + m * 16;
;           float rs;
;           { const float* sp = g.f0 + (size_t)row * 32 + head * 8;
;             const f32x4 s0 = gld<f32x4>(sp); float ssum = (s0[0] + s0[1]) + (s0[2] + s0[3]);
;             if (g.dvshift == 9) { const f32x4 s1 = gld<f32x4>(sp + 4); ssum += (s1[0] + s1[1]) + (s1[2] + s1[3]); }
;             rs = rsqrtf(ssum * (g.dvshift == 9 ? (1.0f / 512.0f) : (1.0f / 256.0f)) + EPS); }
;           bf16_t* op = g.o0 + (size_t)row * N + col;
;           const u32x4 ow = gld<u32x4>(op);
;           const float ru = gld<float>(g.rowscale + row);
;           const f32x4 v0 = acc[ai][bj][m][0] * ru, v1 = acc[ai][bj][m][1] * ru;
;           float o[8] = {bflo(ow.x), bfhi(ow.x), bflo(ow.y), bfhi(ow.y), bflo(ow.z), bfhi(ow.z), bflo(ow.w), bfhi(ow.w)};
; #pragma unroll
;           for (int j = 0; j < 4; ++j) { o[j] = o[j] * rs * g0[j] * v0[j] * sigmoidf_(v0[j]); o[4 + j] = o[4 + j] * rs * g1[j] * v1[j] * sigmoidf_(v1[j]); }
;           u32x4 w; w.x = pk(o[0], o[1]); w.y = pk(o[2], o[3]); w.z = pk(o[4], o[5]); w.w = pk(o[6], o[7]);
;           gst<u32x4>(op, w);
;         }
	v_fmac_f32_e32 v167, v173, v167
	v_div_scale_f32 v173, vcc, 1.0, v176, 1.0
	v_mul_f32_e32 v178, v173, v167
	v_fma_f32 v179, -v136, v178, v173
	v_fmac_f32_e32 v178, v179, v167
	v_fma_f32 v136, -v136, v178, v173
	v_div_fmas_f32 v136, v136, v167, v178
	v_pk_mul_f32 v[178:179], v[104:105], v[172:173] op_sel_hi:[1,0]
	v_div_fixup_f32 v176, v136, v176, 1.0
	v_mul_f32_e32 v136, 0xbfb8aa3b, v178
	v_exp_f32_e32 v188, v136
	v_mul_f32_e32 v136, 0xbfb8aa3b, v179
	v_exp_f32_e32 v189, v136
	v_pk_mul_f32 v[174:175], v[176:177], v[174:175]
	v_lshlrev_b32_e32 v176, 16, v138
	v_and_b32_e32 v177, 0xffff0000, v138
	v_pk_mul_f32 v[176:177], v[148:149], v[176:177] op_sel_hi:[0,1]
	v_pk_mul_f32 v[176:177], v[128:129], v[176:177]
	s_nop 0
	v_pk_mul_f32 v[176:177], v[178:179], v[176:177]
	v_pk_add_f32 v[178:179], v[188:189], 1.0 op_sel_hi:[1,0]
	s_nop 0
	v_div_scale_f32 v136, vcc, v179, v179, 1.0
	v_rcp_f32_e32 v138, v136
	s_nop 0
	v_fma_f32 v167, -v136, v138, 1.0
	v_fmac_f32_e32 v138, v167, v138
	v_div_scale_f32 v167, vcc, 1.0, v179, 1.0
	v_mul_f32_e32 v173, v167, v138
	v_fma_f32 v188, -v136, v173, v167
	v_fmac_f32_e32 v173, v188, v138
	v_fma_f32 v136, -v136, v173, v167
	v_div_fmas_f32 v136, v136, v138, v173
	v_div_fixup_f32 v179, v136, v179, 1.0
	v_div_scale_f32 v136, vcc, v178, v178, 1.0
	v_rcp_f32_e32 v138, v136
	s_nop 0
	v_fma_f32 v167, -v136, v138, 1.0
	v_fmac_f32_e32 v138, v167, v138
	v_div_scale_f32 v167, vcc, 1.0, v178, 1.0
	v_mul_f32_e32 v173, v167, v138
	v_fma_f32 v188, -v136, v173, v167
	v_fmac_f32_e32 v173, v188, v138
	v_fma_f32 v136, -v136, v173, v167
	v_div_fmas_f32 v136, v136, v138, v173
	v_pk_mul_f32 v[188:189], v[110:111], v[172:173] op_sel_hi:[1,0]
	v_div_fixup_f32 v178, v136, v178, 1.0
	v_mul_f32_e32 v138, 0xbfb8aa3b, v188
	v_pk_mul_f32 v[176:177], v[178:179], v[176:177]
	v_exp_f32_e32 v178, v138
	v_mul_f32_e32 v138, 0xbfb8aa3b, v189
	v_exp_f32_e32 v179, v138
	v_lshlrev_b32_e32 v136, 16, v137
	v_and_b32_e32 v137, 0xffff0000, v137
	v_pk_mul_f32 v[136:137], v[148:149], v[136:137] op_sel_hi:[0,1]
	v_pk_add_f32 v[178:179], v[178:179], 1.0 op_sel_hi:[1,0]
	v_pk_mul_f32 v[136:137], v[134:135], v[136:137]
	v_div_scale_f32 v138, vcc, v179, v179, 1.0
	v_rcp_f32_e32 v167, v138
	v_pk_mul_f32 v[136:137], v[188:189], v[136:137]
	v_fma_f32 v173, -v138, v167, 1.0
	v_fmac_f32_e32 v167, v173, v167
	v_div_scale_f32 v173, vcc, 1.0, v179, 1.0
	v_mul_f32_e32 v188, v173, v167
	v_fma_f32 v189, -v138, v188, v173
	v_fmac_f32_e32 v188, v189, v167
	v_fma_f32 v138, -v138, v188, v173
	v_div_fmas_f32 v138, v138, v167, v188
	v_div_fixup_f32 v179, v138, v179, 1.0
	v_div_scale_f32 v138, vcc, v178, v178, 1.0
	v_rcp_f32_e32 v167, v138
	s_nop 0
	v_fma_f32 v173, -v138, v167, 1.0
	v_fmac_f32_e32 v167, v173, v167
	v_div_scale_f32 v173, vcc, 1.0, v178, 1.0
	v_mul_f32_e32 v188, v173, v167
	v_fma_f32 v189, -v138, v188, v173
	v_fmac_f32_e32 v188, v189, v167
	v_fma_f32 v138, -v138, v188, v173
	v_div_fmas_f32 v138, v138, v167, v188
	v_div_fixup_f32 v178, v138, v178, 1.0
	v_pk_mul_f32 v[178:179], v[178:179], v[136:137]
	v_lshlrev_b32_e32 v136, 16, v139
	v_and_b32_e32 v137, 0xffff0000, v139
	v_pk_mul_f32 v[136:137], v[148:149], v[136:137] op_sel_hi:[0,1]
	v_pk_mul_f32 v[138:139], v[106:107], v[172:173] op_sel_hi:[1,0]
	v_pk_mul_f32 v[136:137], v[130:131], v[136:137]
	v_mul_f32_e32 v167, 0xbfb8aa3b, v138
	v_pk_mul_f32 v[136:137], v[138:139], v[136:137]
	v_mul_f32_e32 v138, 0xbfb8aa3b, v139
	v_exp_f32_e32 v172, v167
	v_exp_f32_e32 v173, v138
	s_nop 0
	v_pk_add_f32 v[138:139], v[172:173], 1.0 op_sel_hi:[1,0]
	s_nop 0
	v_div_scale_f32 v148, vcc, v139, v139, 1.0
	v_rcp_f32_e32 v167, v148
	s_nop 0
	v_fma_f32 v172, -v148, v167, 1.0
	v_fmac_f32_e32 v167, v172, v167
	v_div_scale_f32 v172, vcc, 1.0, v139, 1.0
	v_mul_f32_e32 v173, v172, v167
	v_fma_f32 v188, -v148, v173, v172
	v_fmac_f32_e32 v173, v188, v167
	v_fma_f32 v148, -v148, v173, v172
	v_div_fmas_f32 v148, v148, v167, v173
	v_div_fixup_f32 v139, v148, v139, 1.0
	v_div_scale_f32 v148, vcc, v138, v138, 1.0
	v_rcp_f32_e32 v167, v148
	s_nop 0
	v_fma_f32 v172, -v148, v167, 1.0
	v_fmac_f32_e32 v167, v172, v167
	v_div_scale_f32 v172, vcc, 1.0, v138, 1.0
	v_mul_f32_e32 v173, v172, v167
	v_fma_f32 v188, -v148, v173, v172
	v_fmac_f32_e32 v173, v188, v167
	v_fma_f32 v148, -v148, v173, v172
	v_div_fmas_f32 v148, v148, v167, v173
	v_div_fixup_f32 v138, v148, v138, 1.0
	v_pk_mul_f32 v[172:173], v[138:139], v[136:137]
	v_cvt_pk_bf16_f32 v136, v174, v175
	v_cvt_pk_bf16_f32 v137, v178, v179
	v_cvt_pk_bf16_f32 v138, v176, v177
	v_cvt_pk_bf16_f32 v139, v172, v173
	global_store_dwordx4 v[170:171], v[136:139], off
	s_and_b64 vcc, exec, s[44:45]
	s_nop 0
	v_or_b32_e32 v136, 48, v166
	v_ashrrev_i32_e32 v137, 31, v136
	v_lshlrev_b64 v[138:139], 7, v[136:137]
	v_lshl_add_u64 v[188:189], s[66:67], 0, v[138:139]
	v_lshl_add_u64 v[172:173], v[180:181], 2, v[188:189]
	global_load_dwordx4 v[174:177], v[172:173], off
	global_load_dwordx4 v[232:235], v[172:173], off offset:16
	v_mad_u64_u32 v[238:239], s[100:101], v136, s70, 0
	v_mov_b32_e32 v240, v239
	v_mad_u64_u32 v[240:241], s[100:101], v137, s70, v[240:241]
	v_mov_b32_e32 v239, v240
	v_lshl_add_u64 v[238:239], v[238:239], 1, s[64:65]
	v_lshl_add_u64 v[236:237], v[164:165], 1, v[238:239]
	global_load_dwordx4 v[242:245], v[236:237], off
	global_load_dword v246, v[140:141], off offset:192
	s_waitcnt vmcnt(0)
	v_mov_b32_e32 v138, v175
	v_mov_b32_e32 v139, v176
	v_mov_b32_e32 v175, v177
	v_pk_add_f32 v[138:139], v[138:139], v[174:175]
	s_nop 0
	v_pk_add_f32 v[138:139], v[138:139], v[138:139] op_sel:[0,1] op_sel_hi:[1,0]
	s_cbranch_vccnz .LBB0_227
	v_mov_b64_e32 v[172:173], v[232:233]
	v_mov_b64_e32 v[174:175], v[234:235]
	s_mov_b32 s26, 0x3b000000
	v_mov_b32_e32 v176, v173
	v_mov_b32_e32 v177, v174
	v_mov_b32_e32 v173, v175
	v_pk_add_f32 v[172:173], v[176:177], v[172:173]
	s_nop 0
	v_add_f32_e32 v139, v172, v173
	v_add_f32_e32 v138, v138, v139
; DI unsigned pk(float lo, float hi) { f32x2 v = {lo, hi}; bf2_t b = __builtin_convertvector(v, bf2_t); return __builtin_bit_cast(unsigned, b); }
; DI float bflo(unsigned w) { return __uint_as_float(w << 16); }
; DI float bfhi(unsigned w) { return __uint_as_float(w & 0xffff0000u); }
; DI float sigmoidf_(float x) { return 1.0f / (1.0f + __expf(-x)); }
; DI void gemm_epilogue(const GemmDesc& g, f32x4 (&acc)[2][2][4][2], int brow, int bcol, int wr, int wc, int fr, int fq) {
;     ...
;           const int row = rowb + ai * HALF + m * 16;
;           float rs;
;           { const float* sp = g.f0 + (size_t)row * 32 + head * 8;
;             const f32x4 s0 = gld<f32x4>(sp); float ssum = (s0[0] + s0[1]) + (s0[2] + s0[3]);
;             if (g.dvshift == 9) { const f32x4 s1 = gld<f32x4>(sp + 4); ssum += (s1[0] + s1[1]) + (s1[2] + s1[3]); }
;             rs = rsqrtf(ssum * (g.dvshift == 9 ? (1.0f / 512.0f) : (1.0f / 256.0f)) + EPS); }
;           bf16_t* op = g.o0 + (size_t)row * N + col;
;           const u32x4 ow = gld<u32x4>(op);
;           const float ru = gld<float>(g.rowscale + row);
;           const f32x4 v0 = acc[ai][bj][m][0] * ru, v1 = acc[ai][bj][m][1] * ru;
;           float o[8] = {bflo(ow.x), bfhi(ow.x), bflo(ow.y), bfhi(ow.y), bflo(ow.z), bfhi(ow.z), bflo(ow.w), bfhi(ow.w)};
; #pragma unroll
;           for (int j = 0; j < 4; ++j) { o[j] = o[j] * rs * g0[j] * v0[j] * sigmoidf_(v0[j]); o[4 + j] = o[4 + j] * rs * g1[j] * v1[j] * sigmoidf_(v1[j]); }
;           u32x4 w; w.x = pk(o[0], o[1]); w.y = pk(o[2], o[3]); w.z = pk(o[4], o[5]); w.w = pk(o[6], o[7]);
;           gst<u32x4>(op, w);
;         }
.LBB0_227:
	v_fma_f32 v138, s26, v138, v204
	v_cmp_gt_f32_e32 vcc, s33, v138
	v_mul_f32_e32 v139, 0x4b800000, v138
	s_nop 0
	v_cndmask_b32_e32 v138, v138, v139, vcc
	v_rsq_f32_e32 v138, v138
	s_nop 0
	v_mul_f32_e32 v139, 0x45800000, v138
	v_cndmask_b32_e32 v148, v138, v139, vcc
	v_mad_u64_u32 v[138:139], s[26:27], v136, s70, 0
	v_mov_b32_e32 v136, v139
	v_mad_u64_u32 v[136:137], s[26:27], v137, s70, v[136:137]
	v_mov_b32_e32 v139, v136
	v_lshl_add_u64 v[136:137], v[138:139], 1, s[64:65]
	v_lshl_add_u64 v[172:173], v[164:165], 1, v[136:137]
	v_mov_b64_e32 v[136:137], v[242:243]
	v_mov_b64_e32 v[138:139], v[244:245]
	v_mov_b32_e32 v174, v246
	v_lshlrev_b32_e32 v176, 16, v136
	v_pk_mul_f32 v[178:179], v[100:101], v[174:175] op_sel_hi:[1,0]
	v_and_b32_e32 v177, 0xffff0000, v136
	v_mul_f32_e32 v136, 0xbfb8aa3b, v178
	v_exp_f32_e32 v190, v136
	v_mul_f32_e32 v136, 0xbfb8aa3b, v179
	v_exp_f32_e32 v191, v136
	v_pk_mul_f32 v[176:177], v[148:149], v[176:177] op_sel_hi:[0,1]
	v_pk_mul_f32 v[176:177], v[132:133], v[176:177]
	s_nop 0
	v_pk_mul_f32 v[176:177], v[178:179], v[176:177]
	v_pk_add_f32 v[178:179], v[190:191], 1.0 op_sel_hi:[1,0]
	s_nop 0
	v_div_scale_f32 v136, s[26:27], v179, v179, 1.0
	v_rcp_f32_e32 v167, v136
	s_nop 0
	v_fma_f32 v175, -v136, v167, 1.0
	v_fmac_f32_e32 v167, v175, v167
	v_div_scale_f32 v175, vcc, 1.0, v179, 1.0
	v_mul_f32_e32 v190, v175, v167
	v_fma_f32 v191, -v136, v190, v175
	v_fmac_f32_e32 v190, v191, v167
	v_fma_f32 v136, -v136, v190, v175
	v_div_fmas_f32 v136, v136, v167, v190
	v_div_fixup_f32 v179, v136, v179, 1.0
	v_div_scale_f32 v136, s[26:27], v178, v178, 1.0
	v_rcp_f32_e32 v167, v136
	s_nop 0
	v_fma_f32 v175, -v136, v167, 1.0
	v_fmac_f32_e32 v167, v175, v167
	v_div_scale_f32 v175, vcc, 1.0, v178, 1.0
	v_mul_f32_e32 v190, v175, v167
	v_fma_f32 v191, -v136, v190, v175
	v_fmac_f32_e32 v190, v191, v167
	v_fma_f32 v136, -v136, v190, v175
	v_div_fmas_f32 v136, v136, v167, v190
	v_pk_mul_f32 v[190:191], v[96:97], v[174:175] op_sel_hi:[1,0]
	v_div_fixup_f32 v178, v136, v178, 1.0
	v_mul_f32_e32 v136, 0xbfb8aa3b, v190
	v_exp_f32_e32 v192, v136
	v_mul_f32_e32 v136, 0xbfb8aa3b, v191
	v_exp_f32_e32 v193, v136
	v_pk_mul_f32 v[176:177], v[178:179], v[176:177]
	v_lshlrev_b32_e32 v178, 16, v138
	v_and_b32_e32 v179, 0xffff0000, v138
	v_pk_mul_f32 v[178:179], v[148:149], v[178:179] op_sel_hi:[0,1]
	v_pk_mul_f32 v[178:179], v[128:129], v[178:179]
	s_nop 0
	v_pk_mul_f32 v[178:179], v[190:191], v[178:179]
	v_pk_add_f32 v[190:191], v[192:193], 1.0 op_sel_hi:[1,0]
	s_nop 0
	v_div_scale_f32 v136, s[26:27], v191, v191, 1.0
	v_rcp_f32_e32 v138, v136
	s_nop 0
	v_fma_f32 v167, -v136, v138, 1.0
	v_fmac_f32_e32 v138, v167, v138
	v_div_scale_f32 v167, vcc, 1.0, v191, 1.0
	v_mul_f32_e32 v175, v167, v138
	v_fma_f32 v192, -v136, v175, v167
	v_fmac_f32_e32 v175, v192, v138
	v_fma_f32 v136, -v136, v175, v167
	v_div_fmas_f32 v136, v136, v138, v175
	v_div_fixup_f32 v191, v136, v191, 1.0
	v_div_scale_f32 v136, s[26:27], v190, v190, 1.0
	v_rcp_f32_e32 v138, v136
	s_nop 0
	v_fma_f32 v167, -v136, v138, 1.0
	v_fmac_f32_e32 v138, v167, v138
	v_div_scale_f32 v167, vcc, 1.0, v190, 1.0
	v_mul_f32_e32 v175, v167, v138
	v_fma_f32 v192, -v136, v175, v167
	v_fmac_f32_e32 v175, v192, v138
	v_fma_f32 v136, -v136, v175, v167
	v_div_fmas_f32 v136, v136, v138, v175
	v_pk_mul_f32 v[192:193], v[102:103], v[174:175] op_sel_hi:[1,0]
	v_div_fixup_f32 v190, v136, v190, 1.0
	v_mul_f32_e32 v138, 0xbfb8aa3b, v192
	v_pk_mul_f32 v[178:179], v[190:191], v[178:179]
	v_exp_f32_e32 v190, v138
	v_mul_f32_e32 v138, 0xbfb8aa3b, v193
	v_exp_f32_e32 v191, v138
	v_lshlrev_b32_e32 v136, 16, v137
	v_and_b32_e32 v137, 0xffff0000, v137
	v_pk_mul_f32 v[136:137], v[148:149], v[136:137] op_sel_hi:[0,1]
	v_pk_add_f32 v[190:191], v[190:191], 1.0 op_sel_hi:[1,0]
	v_pk_mul_f32 v[136:137], v[134:135], v[136:137]
	v_div_scale_f32 v138, s[26:27], v191, v191, 1.0
	v_rcp_f32_e32 v167, v138
	v_pk_mul_f32 v[136:137], v[192:193], v[136:137]
	v_fma_f32 v175, -v138, v167, 1.0
	v_fmac_f32_e32 v167, v175, v167
	v_div_scale_f32 v175, vcc, 1.0, v191, 1.0
	v_mul_f32_e32 v192, v175, v167
	v_fma_f32 v193, -v138, v192, v175
	v_fmac_f32_e32 v192, v193, v167
	v_fma_f32 v138, -v138, v192, v175
	v_div_fmas_f32 v138, v138, v167, v192
	v_div_fixup_f32 v191, v138, v191, 1.0
	v_div_scale_f32 v138, s[26:27], v190, v190, 1.0
	v_rcp_f32_e32 v167, v138
	s_nop 0
	v_fma_f32 v175, -v138, v167, 1.0
	v_fmac_f32_e32 v167, v175, v167
	v_div_scale_f32 v175, vcc, 1.0, v190, 1.0
	v_mul_f32_e32 v192, v175, v167
	v_fma_f32 v193, -v138, v192, v175
	v_fmac_f32_e32 v192, v193, v167
	v_fma_f32 v138, -v138, v192, v175
	v_div_fmas_f32 v138, v138, v167, v192
	v_div_fixup_f32 v190, v138, v190, 1.0
	v_pk_mul_f32 v[190:191], v[190:191], v[136:137]
	v_lshlrev_b32_e32 v136, 16, v139
	v_and_b32_e32 v137, 0xffff0000, v139
	v_pk_mul_f32 v[136:137], v[148:149], v[136:137] op_sel_hi:[0,1]
	v_pk_mul_f32 v[138:139], v[98:99], v[174:175] op_sel_hi:[1,0]
	v_pk_mul_f32 v[136:137], v[130:131], v[136:137]
	v_mul_f32_e32 v167, 0xbfb8aa3b, v138
	v_pk_mul_f32 v[136:137], v[138:139], v[136:137]
	v_mul_f32_e32 v138, 0xbfb8aa3b, v139
	v_exp_f32_e32 v174, v167
	v_exp_f32_e32 v175, v138
	s_nop 0
	v_pk_add_f32 v[138:139], v[174:175], 1.0 op_sel_hi:[1,0]
	s_nop 0
	v_div_scale_f32 v148, s[26:27], v139, v139, 1.0
	v_rcp_f32_e32 v167, v148
	s_nop 0
	v_fma_f32 v174, -v148, v167, 1.0
	v_fmac_f32_e32 v167, v174, v167
	v_div_scale_f32 v174, vcc, 1.0, v139, 1.0
	v_mul_f32_e32 v175, v174, v167
	v_fma_f32 v192, -v148, v175, v174
	v_fmac_f32_e32 v175, v192, v167
	v_fma_f32 v148, -v148, v175, v174
	v_div_fmas_f32 v148, v148, v167, v175
	v_div_fixup_f32 v139, v148, v139, 1.0
; DI unsigned pk(float lo, float hi) { f32x2 v = {lo, hi}; bf2_t b = __builtin_convertvector(v, bf2_t); return __builtin_bit_cast(unsigned, b); }
; DI float bflo(unsigned w) { return __uint_as_float(w << 16); }
; DI float bfhi(unsigned w) { return __uint_as_float(w & 0xffff0000u); }
; DI float sigmoidf_(float x) { return 1.0f / (1.0f + __expf(-x)); }
; DI void gemm_epilogue(const GemmDesc& g, f32x4 (&acc)[2][2][4][2], int brow, int bcol, int wr, int wc, int fr, int fq) {
;     ...
;           const int row = rowb + ai * HALF + m * 16;
;           float rs;
;           { const float* sp = g.f0 + (size_t)row * 32 + head * 8;
;             const f32x4 s0 = gld<f32x4>(sp); float ssum = (s0[0] + s0[1]) + (s0[2] + s0[3]);
;             if (g.dvshift == 9) { const f32x4 s1 = gld<f32x4>(sp + 4); ssum += (s1[0] + s1[1]) + (s1[2] + s1[3]); }
;             rs = rsqrtf(ssum * (g.dvshift == 9 ? (1.0f / 512.0f) : (1.0f / 256.0f)) + EPS); }
;           bf16_t* op = g.o0 + (size_t)row * N + col;
;           const u32x4 ow = gld<u32x4>(op);
;           const float ru = gld<float>(g.rowscale + row);
;           const f32x4 v0 = acc[ai][bj][m][0] * ru, v1 = acc[ai][bj][m][1] * ru;
;           float o[8] = {bflo(ow.x), bfhi(ow.x), bflo(ow.y), bfhi(ow.y), bflo(ow.z), bfhi(ow.z), bflo(ow.w), bfhi(ow.w)};
; #pragma unroll
;           for (int j = 0; j < 4; ++j) { o[j] = o[j] * rs * g0[j] * v0[j] * sigmoidf_(v0[j]); o[4 + j] = o[4 + j] * rs * g1[j] * v1[j] * sigmoidf_(v1[j]); }
;           u32x4 w; w.x = pk(o[0], o[1]); w.y = pk(o[2], o[3]); w.z = pk(o[4], o[5]); w.w = pk(o[6], o[7]);
;           gst<u32x4>(op, w);
;         }
	v_div_scale_f32 v148, s[26:27], v138, v138, 1.0
	v_rcp_f32_e32 v167, v148
	s_mov_b32 s26, 0x3b800000
	s_mov_b32 s27, 0x3b800000
	v_fma_f32 v174, -v148, v167, 1.0
	v_fmac_f32_e32 v167, v174, v167
	v_div_scale_f32 v174, vcc, 1.0, v138, 1.0
	v_mul_f32_e32 v175, v174, v167
	v_fma_f32 v192, -v148, v175, v174
	v_fmac_f32_e32 v175, v192, v167
	v_fma_f32 v148, -v148, v175, v174
	v_div_fmas_f32 v148, v148, v167, v175
	v_div_fixup_f32 v138, v148, v138, 1.0
	v_pk_mul_f32 v[174:175], v[138:139], v[136:137]
	v_cvt_pk_bf16_f32 v136, v176, v177
	v_cvt_pk_bf16_f32 v137, v190, v191
	v_cvt_pk_bf16_f32 v138, v178, v179
	v_cvt_pk_bf16_f32 v139, v174, v175
	global_store_dwordx4 v[172:173], v[136:139], off
	s_and_b64 vcc, exec, s[44:45]
	s_nop 0
	v_add_u32_e32 v136, 0x80, v166
	v_ashrrev_i32_e32 v137, 31, v136
	v_lshlrev_b64 v[138:139], 7, v[136:137]
	v_lshl_add_u64 v[190:191], s[66:67], 0, v[138:139]
	v_lshl_add_u64 v[174:175], v[180:181], 2, v[190:191]
	global_load_dwordx4 v[176:179], v[174:175], off
	global_load_dwordx4 v[232:235], v[174:175], off offset:16
	v_mad_u64_u32 v[238:239], s[100:101], v136, s70, 0
	v_mov_b32_e32 v240, v239
	v_mad_u64_u32 v[240:241], s[100:101], v137, s70, v[240:241]
	v_mov_b32_e32 v239, v240
	v_lshl_add_u64 v[238:239], v[238:239], 1, s[64:65]
	v_lshl_add_u64 v[236:237], v[164:165], 1, v[238:239]
	global_load_dwordx4 v[242:245], v[236:237], off
	global_load_dword v246, v[140:141], off offset:512
	s_waitcnt vmcnt(0)
	v_mov_b32_e32 v138, v177
	v_mov_b32_e32 v139, v178
	v_mov_b32_e32 v177, v179
	v_pk_add_f32 v[138:139], v[138:139], v[176:177]
	s_nop 0
	v_pk_add_f32 v[138:139], v[138:139], v[138:139] op_sel:[0,1] op_sel_hi:[1,0]
	s_cbranch_vccnz .LBB0_229
	v_mov_b64_e32 v[174:175], v[232:233]
	v_mov_b64_e32 v[176:177], v[234:235]
	s_mov_b32 s27, 0x3b000000
	v_mov_b32_e32 v178, v175
	v_mov_b32_e32 v179, v176
	v_mov_b32_e32 v175, v177
	v_pk_add_f32 v[174:175], v[178:179], v[174:175]
	s_nop 0
	v_add_f32_e32 v139, v174, v175
	v_add_f32_e32 v138, v138, v139
.LBB0_229:
	v_fma_f32 v138, s27, v138, v204
	v_cmp_gt_f32_e32 vcc, s33, v138
	v_mul_f32_e32 v139, 0x4b800000, v138
	s_nop 0
	v_cndmask_b32_e32 v138, v138, v139, vcc
	v_rsq_f32_e32 v138, v138
	s_nop 0
	v_mul_f32_e32 v139, 0x45800000, v138
	v_cndmask_b32_e32 v148, v138, v139, vcc
	v_mad_u64_u32 v[138:139], vcc, v136, s70, 0
	v_mov_b32_e32 v136, v139
	v_mad_u64_u32 v[136:137], vcc, v137, s70, v[136:137]
	v_mov_b32_e32 v139, v136
	v_lshl_add_u64 v[136:137], v[138:139], 1, s[64:65]
	v_lshl_add_u64 v[174:175], v[164:165], 1, v[136:137]
	v_mov_b64_e32 v[136:137], v[242:243]
	v_mov_b64_e32 v[138:139], v[244:245]
	v_mov_b32_e32 v176, v246
	v_lshlrev_b32_e32 v178, 16, v136
	v_pk_mul_f32 v[192:193], v[92:93], v[176:177] op_sel_hi:[1,0]
	v_and_b32_e32 v179, 0xffff0000, v136
	v_mul_f32_e32 v136, 0xbfb8aa3b, v192
	v_exp_f32_e32 v194, v136
	v_mul_f32_e32 v136, 0xbfb8aa3b, v193
	v_exp_f32_e32 v195, v136
	v_pk_mul_f32 v[178:179], v[148:149], v[178:179] op_sel_hi:[0,1]
	v_pk_mul_f32 v[178:179], v[132:133], v[178:179]
	s_nop 0
	v_pk_mul_f32 v[178:179], v[192:193], v[178:179]
	v_pk_add_f32 v[192:193], v[194:195], 1.0 op_sel_hi:[1,0]
	s_nop 0
	v_div_scale_f32 v136, vcc, v193, v193, 1.0
	v_rcp_f32_e32 v167, v136
	s_nop 0
	v_fma_f32 v177, -v136, v167, 1.0
	v_fmac_f32_e32 v167, v177, v167
	v_div_scale_f32 v177, vcc, 1.0, v193, 1.0
	v_mul_f32_e32 v194, v177, v167
	v_fma_f32 v195, -v136, v194, v177
	v_fmac_f32_e32 v194, v195, v167
	v_fma_f32 v136, -v136, v194, v177
	v_div_fmas_f32 v136, v136, v167, v194
	v_div_fixup_f32 v193, v136, v193, 1.0
	v_div_scale_f32 v136, vcc, v192, v192, 1.0
	v_rcp_f32_e32 v167, v136
	s_nop 0
	v_fma_f32 v177, -v136, v167, 1.0
	v_fmac_f32_e32 v167, v177, v167
	v_div_scale_f32 v177, vcc, 1.0, v192, 1.0
	v_mul_f32_e32 v194, v177, v167
	v_fma_f32 v195, -v136, v194, v177
	v_fmac_f32_e32 v194, v195, v167
	v_fma_f32 v136, -v136, v194, v177
	v_div_fmas_f32 v136, v136, v167, v194
	v_pk_mul_f32 v[194:195], v[88:89], v[176:177] op_sel_hi:[1,0]
	v_div_fixup_f32 v192, v136, v192, 1.0
	v_mul_f32_e32 v136, 0xbfb8aa3b, v194
	v_exp_f32_e32 v196, v136
	v_mul_f32_e32 v136, 0xbfb8aa3b, v195
	v_exp_f32_e32 v197, v136
	v_pk_mul_f32 v[178:179], v[192:193], v[178:179]
	v_lshlrev_b32_e32 v192, 16, v138
	v_and_b32_e32 v193, 0xffff0000, v138
	v_pk_mul_f32 v[192:193], v[148:149], v[192:193] op_sel_hi:[0,1]
	v_pk_mul_f32 v[192:193], v[128:129], v[192:193]
	s_nop 0
	v_pk_mul_f32 v[192:193], v[194:195], v[192:193]
	v_pk_add_f32 v[194:195], v[196:197], 1.0 op_sel_hi:[1,0]
	s_nop 0
	v_div_scale_f32 v136, vcc, v195, v195, 1.0
	v_rcp_f32_e32 v138, v136
	s_nop 0
	v_fma_f32 v167, -v136, v138, 1.0
	v_fmac_f32_e32 v138, v167, v138
	v_div_scale_f32 v167, vcc, 1.0, v195, 1.0
	v_mul_f32_e32 v177, v167, v138
	v_fma_f32 v196, -v136, v177, v167
	v_fmac_f32_e32 v177, v196, v138
	v_fma_f32 v136, -v136, v177, v167
	v_div_fmas_f32 v136, v136, v138, v177
	v_div_fixup_f32 v195, v136, v195, 1.0
	v_div_scale_f32 v136, vcc, v194, v194, 1.0
	v_rcp_f32_e32 v138, v136
	s_nop 0
	v_fma_f32 v167, -v136, v138, 1.0
	v_fmac_f32_e32 v138, v167, v138
	v_div_scale_f32 v167, vcc, 1.0, v194, 1.0
	v_mul_f32_e32 v177, v167, v138
	v_fma_f32 v196, -v136, v177, v167
	v_fmac_f32_e32 v177, v196, v138
	v_fma_f32 v136, -v136, v177, v167
	v_div_fmas_f32 v136, v136, v138, v177
	v_pk_mul_f32 v[196:197], v[94:95], v[176:177] op_sel_hi:[1,0]
	v_div_fixup_f32 v194, v136, v194, 1.0
	v_mul_f32_e32 v138, 0xbfb8aa3b, v196
	v_pk_mul_f32 v[192:193], v[194:195], v[192:193]
	v_exp_f32_e32 v194, v138
	v_mul_f32_e32 v138, 0xbfb8aa3b, v197
	v_exp_f32_e32 v195, v138
	v_lshlrev_b32_e32 v136, 16, v137
	v_and_b32_e32 v137, 0xffff0000, v137
	v_pk_mul_f32 v[136:137], v[148:149], v[136:137] op_sel_hi:[0,1]
; DI unsigned pk(float lo, float hi) { f32x2 v = {lo, hi}; bf2_t b = __builtin_convertvector(v, bf2_t); return __builtin_bit_cast(unsigned, b); }
; DI float bflo(unsigned w) { return __uint_as_float(w << 16); }
; DI float bfhi(unsigned w) { return __uint_as_float(w & 0xffff0000u); }
; DI float sigmoidf_(float x) { return 1.0f / (1.0f + __expf(-x)); }
; DI void gemm_epilogue(const GemmDesc& g, f32x4 (&acc)[2][2][4][2], int brow, int bcol, int wr, int wc, int fr, int fq) {
;     ...
;           const int row = rowb + ai * HALF + m * 16;
;           float rs;
;           { const float* sp = g.f0 + (size_t)row * 32 + head * 8;
;             const f32x4 s0 = gld<f32x4>(sp); float ssum = (s0[0] + s0[1]) + (s0[2] + s0[3]);
;             if (g.dvshift == 9) { const f32x4 s1 = gld<f32x4>(sp + 4); ssum += (s1[0] + s1[1]) + (s1[2] + s1[3]); }
;             rs = rsqrtf(ssum * (g.dvshift == 9 ? (1.0f / 512.0f) : (1.0f / 256.0f)) + EPS); }
;           bf16_t* op = g.o0 + (size_t)row * N + col;
;           const u32x4 ow = gld<u32x4>(op);
;           const float ru = gld<float>(g.rowscale + row);
;           const f32x4 v0 = acc[ai][bj][m][0] * ru, v1 = acc[ai][bj][m][1] * ru;
;           float o[8] = {bflo(ow.x), bfhi(ow.x), bflo(ow.y), bfhi(ow.y), bflo(ow.z), bfhi(ow.z), bflo(ow.w), bfhi(ow.w)};
; #pragma unroll
;           for (int j = 0; j < 4; ++j) { o[j] = o[j] * rs * g0[j] * v0[j] * sigmoidf_(v0[j]); o[4 + j] = o[4 + j] * rs * g1[j] * v1[j] * sigmoidf_(v1[j]); }
;           u32x4 w; w.x = pk(o[0], o[1]); w.y = pk(o[2], o[3]); w.z = pk(o[4], o[5]); w.w = pk(o[6], o[7]);
;           gst<u32x4>(op, w);
;         }
	v_pk_add_f32 v[194:195], v[194:195], 1.0 op_sel_hi:[1,0]
	v_pk_mul_f32 v[136:137], v[134:135], v[136:137]
	v_div_scale_f32 v138, vcc, v195, v195, 1.0
	v_rcp_f32_e32 v167, v138
	v_pk_mul_f32 v[136:137], v[196:197], v[136:137]
	v_fma_f32 v177, -v138, v167, 1.0
	v_fmac_f32_e32 v167, v177, v167
	v_div_scale_f32 v177, vcc, 1.0, v195, 1.0
	v_mul_f32_e32 v196, v177, v167
	v_fma_f32 v197, -v138, v196, v177
	v_fmac_f32_e32 v196, v197, v167
	v_fma_f32 v138, -v138, v196, v177
	v_div_fmas_f32 v138, v138, v167, v196
	v_div_fixup_f32 v195, v138, v195, 1.0
	v_div_scale_f32 v138, vcc, v194, v194, 1.0
	v_rcp_f32_e32 v167, v138
	s_nop 0
	v_fma_f32 v177, -v138, v167, 1.0
	v_fmac_f32_e32 v167, v177, v167
	v_div_scale_f32 v177, vcc, 1.0, v194, 1.0
	v_mul_f32_e32 v196, v177, v167
	v_fma_f32 v197, -v138, v196, v177
	v_fmac_f32_e32 v196, v197, v167
	v_fma_f32 v138, -v138, v196, v177
	v_div_fmas_f32 v138, v138, v167, v196
	v_div_fixup_f32 v194, v138, v194, 1.0
	v_pk_mul_f32 v[194:195], v[194:195], v[136:137]
	v_lshlrev_b32_e32 v136, 16, v139
	v_and_b32_e32 v137, 0xffff0000, v139
	v_pk_mul_f32 v[136:137], v[148:149], v[136:137] op_sel_hi:[0,1]
	v_pk_mul_f32 v[138:139], v[90:91], v[176:177] op_sel_hi:[1,0]
	v_pk_mul_f32 v[136:137], v[130:131], v[136:137]
	v_mul_f32_e32 v167, 0xbfb8aa3b, v138
	v_pk_mul_f32 v[136:137], v[138:139], v[136:137]
	v_mul_f32_e32 v138, 0xbfb8aa3b, v139
	v_exp_f32_e32 v176, v167
	v_exp_f32_e32 v177, v138
	s_nop 0
	v_pk_add_f32 v[138:139], v[176:177], 1.0 op_sel_hi:[1,0]
	s_nop 0
	v_div_scale_f32 v148, vcc, v139, v139, 1.0
	v_rcp_f32_e32 v167, v148
	s_nop 0
	v_fma_f32 v176, -v148, v167, 1.0
	v_fmac_f32_e32 v167, v176, v167
	v_div_scale_f32 v176, vcc, 1.0, v139, 1.0
	v_mul_f32_e32 v177, v176, v167
	v_fma_f32 v196, -v148, v177, v176
	v_fmac_f32_e32 v177, v196, v167
	v_fma_f32 v148, -v148, v177, v176
	v_div_fmas_f32 v148, v148, v167, v177
	v_div_fixup_f32 v139, v148, v139, 1.0
	v_div_scale_f32 v148, vcc, v138, v138, 1.0
	v_rcp_f32_e32 v167, v148
	s_nop 0
	v_fma_f32 v176, -v148, v167, 1.0
	v_fmac_f32_e32 v167, v176, v167
	v_div_scale_f32 v176, vcc, 1.0, v138, 1.0
	v_mul_f32_e32 v177, v176, v167
	v_fma_f32 v196, -v148, v177, v176
	v_fmac_f32_e32 v177, v196, v167
	v_fma_f32 v148, -v148, v177, v176
	v_div_fmas_f32 v148, v148, v167, v177
	v_div_fixup_f32 v138, v148, v138, 1.0
	v_pk_mul_f32 v[176:177], v[138:139], v[136:137]
	v_cvt_pk_bf16_f32 v136, v178, v179
	v_cvt_pk_bf16_f32 v137, v194, v195
	v_cvt_pk_bf16_f32 v138, v192, v193
	v_cvt_pk_bf16_f32 v139, v176, v177
	global_store_dwordx4 v[174:175], v[136:139], off
	s_and_b64 vcc, exec, s[44:45]
	s_nop 0
	v_add_u32_e32 v136, 0x90, v166
	v_ashrrev_i32_e32 v137, 31, v136
	v_lshlrev_b64 v[138:139], 7, v[136:137]
	v_lshl_add_u64 v[192:193], s[66:67], 0, v[138:139]
	v_lshl_add_u64 v[176:177], v[180:181], 2, v[192:193]
	global_load_dwordx4 v[194:197], v[176:177], off
	global_load_dwordx4 v[232:235], v[176:177], off offset:16
	v_mad_u64_u32 v[238:239], s[100:101], v136, s70, 0
	v_mov_b32_e32 v240, v239
	v_mad_u64_u32 v[240:241], s[100:101], v137, s70, v[240:241]
	v_mov_b32_e32 v239, v240
	v_lshl_add_u64 v[238:239], v[238:239], 1, s[64:65]
	v_lshl_add_u64 v[236:237], v[164:165], 1, v[238:239]
	global_load_dwordx4 v[242:245], v[236:237], off
	global_load_dword v246, v[140:141], off offset:576
	s_waitcnt vmcnt(0)
	v_mov_b32_e32 v138, v195
	v_mov_b32_e32 v139, v196
	v_mov_b32_e32 v195, v197
	v_pk_add_f32 v[138:139], v[138:139], v[194:195]
	s_nop 0
	v_pk_add_f32 v[138:139], v[138:139], v[138:139] op_sel:[0,1] op_sel_hi:[1,0]
	s_cbranch_vccnz .LBB0_231
	v_mov_b64_e32 v[176:177], v[232:233]
	v_mov_b64_e32 v[178:179], v[234:235]
	s_mov_b32 s26, 0x3b000000
	v_mov_b32_e32 v194, v177
	v_mov_b32_e32 v195, v178
	v_mov_b32_e32 v177, v179
	v_pk_add_f32 v[176:177], v[194:195], v[176:177]
	s_nop 0
	v_add_f32_e32 v139, v176, v177
	v_add_f32_e32 v138, v138, v139
.LBB0_231:
	v_fma_f32 v138, s26, v138, v204
	v_cmp_gt_f32_e32 vcc, s33, v138
	v_mul_f32_e32 v139, 0x4b800000, v138
	s_nop 0
	v_cndmask_b32_e32 v138, v138, v139, vcc
	v_rsq_f32_e32 v138, v138
	s_nop 0
	v_mul_f32_e32 v139, 0x45800000, v138
	v_cndmask_b32_e32 v148, v138, v139, vcc
	v_mad_u64_u32 v[138:139], s[26:27], v136, s70, 0
	v_mov_b32_e32 v136, v139
	v_mad_u64_u32 v[136:137], s[26:27], v137, s70, v[136:137]
	v_mov_b32_e32 v139, v136
	v_lshl_add_u64 v[136:137], v[138:139], 1, s[64:65]
	v_lshl_add_u64 v[176:177], v[164:165], 1, v[136:137]
	v_mov_b64_e32 v[136:137], v[242:243]
	v_mov_b64_e32 v[138:139], v[244:245]
	v_mov_b32_e32 v178, v246
	v_lshlrev_b32_e32 v194, 16, v136
	v_pk_mul_f32 v[196:197], v[84:85], v[178:179] op_sel_hi:[1,0]
	v_and_b32_e32 v195, 0xffff0000, v136
	v_mul_f32_e32 v136, 0xbfb8aa3b, v196
	v_exp_f32_e32 v198, v136
	v_mul_f32_e32 v136, 0xbfb8aa3b, v197
	v_exp_f32_e32 v199, v136
	v_pk_mul_f32 v[194:195], v[148:149], v[194:195] op_sel_hi:[0,1]
	v_pk_mul_f32 v[194:195], v[132:133], v[194:195]
	s_nop 0
	v_pk_mul_f32 v[194:195], v[196:197], v[194:195]
	v_pk_add_f32 v[196:197], v[198:199], 1.0 op_sel_hi:[1,0]
	s_nop 0
	v_div_scale_f32 v136, s[26:27], v197, v197, 1.0
	v_rcp_f32_e32 v167, v136
	s_nop 0
	v_fma_f32 v179, -v136, v167, 1.0
	v_fmac_f32_e32 v167, v179, v167
	v_div_scale_f32 v179, vcc, 1.0, v197, 1.0
	v_mul_f32_e32 v198, v179, v167
	v_fma_f32 v199, -v136, v198, v179
	v_fmac_f32_e32 v198, v199, v167
	v_fma_f32 v136, -v136, v198, v179
	v_div_fmas_f32 v136, v136, v167, v198
	v_div_fixup_f32 v197, v136, v197, 1.0
	v_div_scale_f32 v136, s[26:27], v196, v196, 1.0
	v_rcp_f32_e32 v167, v136
	s_nop 0
	v_fma_f32 v179, -v136, v167, 1.0
	v_fmac_f32_e32 v167, v179, v167
	v_div_scale_f32 v179, vcc, 1.0, v196, 1.0
	v_mul_f32_e32 v198, v179, v167
; DI unsigned pk(float lo, float hi) { f32x2 v = {lo, hi}; bf2_t b = __builtin_convertvector(v, bf2_t); return __builtin_bit_cast(unsigned, b); }
; DI float bflo(unsigned w) { return __uint_as_float(w << 16); }
; DI float bfhi(unsigned w) { return __uint_as_float(w & 0xffff0000u); }
; DI float sigmoidf_(float x) { return 1.0f / (1.0f + __expf(-x)); }
; DI void gemm_epilogue(const GemmDesc& g, f32x4 (&acc)[2][2][4][2], int brow, int bcol, int wr, int wc, int fr, int fq) {
;     ...
;           const int row = rowb + ai * HALF + m * 16;
;           float rs;
;           { const float* sp = g.f0 + (size_t)row * 32 + head * 8;
;             const f32x4 s0 = gld<f32x4>(sp); float ssum = (s0[0] + s0[1]) + (s0[2] + s0[3]);
;             if (g.dvshift == 9) { const f32x4 s1 = gld<f32x4>(sp + 4); ssum += (s1[0] + s1[1]) + (s1[2] + s1[3]); }
;             rs = rsqrtf(ssum * (g.dvshift == 9 ? (1.0f / 512.0f) : (1.0f / 256.0f)) + EPS); }
;           bf16_t* op = g.o0 + (size_t)row * N + col;
;           const u32x4 ow = gld<u32x4>(op);
;           const float ru = gld<float>(g.rowscale + row);
;           const f32x4 v0 = acc[ai][bj][m][0] * ru, v1 = acc[ai][bj][m][1] * ru;
;           float o[8] = {bflo(ow.x), bfhi(ow.x), bflo(ow.y), bfhi(ow.y), bflo(ow.z), bfhi(ow.z), bflo(ow.w), bfhi(ow.w)};
; #pragma unroll
;           for (int j = 0; j < 4; ++j) { o[j] = o[j] * rs * g0[j] * v0[j] * sigmoidf_(v0[j]); o[4 + j] = o[4 + j] * rs * g1[j] * v1[j] * sigmoidf_(v1[j]); }
;           u32x4 w; w.x = pk(o[0], o[1]); w.y = pk(o[2], o[3]); w.z = pk(o[4], o[5]); w.w = pk(o[6], o[7]);
;           gst<u32x4>(op, w);
;         }
	v_fma_f32 v199, -v136, v198, v179
	v_fmac_f32_e32 v198, v199, v167
	v_fma_f32 v136, -v136, v198, v179
	v_div_fmas_f32 v136, v136, v167, v198
	v_pk_mul_f32 v[198:199], v[80:81], v[178:179] op_sel_hi:[1,0]
	v_div_fixup_f32 v196, v136, v196, 1.0
	v_mul_f32_e32 v136, 0xbfb8aa3b, v198
	v_exp_f32_e32 v200, v136
	v_mul_f32_e32 v136, 0xbfb8aa3b, v199
	v_exp_f32_e32 v201, v136
	v_pk_mul_f32 v[194:195], v[196:197], v[194:195]
	v_lshlrev_b32_e32 v196, 16, v138
	v_and_b32_e32 v197, 0xffff0000, v138
	v_pk_mul_f32 v[196:197], v[148:149], v[196:197] op_sel_hi:[0,1]
	v_pk_mul_f32 v[196:197], v[128:129], v[196:197]
	s_nop 0
	v_pk_mul_f32 v[196:197], v[198:199], v[196:197]
	v_pk_add_f32 v[198:199], v[200:201], 1.0 op_sel_hi:[1,0]
	s_nop 0
	v_div_scale_f32 v136, s[26:27], v199, v199, 1.0
	v_rcp_f32_e32 v138, v136
	s_nop 0
	v_fma_f32 v167, -v136, v138, 1.0
	v_fmac_f32_e32 v138, v167, v138
	v_div_scale_f32 v167, vcc, 1.0, v199, 1.0
	v_mul_f32_e32 v179, v167, v138
	v_fma_f32 v200, -v136, v179, v167
	v_fmac_f32_e32 v179, v200, v138
	v_fma_f32 v136, -v136, v179, v167
	v_div_fmas_f32 v136, v136, v138, v179
	v_div_fixup_f32 v199, v136, v199, 1.0
	v_div_scale_f32 v136, s[26:27], v198, v198, 1.0
	v_rcp_f32_e32 v138, v136
	s_nop 0
	v_fma_f32 v167, -v136, v138, 1.0
	v_fmac_f32_e32 v138, v167, v138
	v_div_scale_f32 v167, vcc, 1.0, v198, 1.0
	v_mul_f32_e32 v179, v167, v138
	v_fma_f32 v200, -v136, v179, v167
	v_fmac_f32_e32 v179, v200, v138
	v_fma_f32 v136, -v136, v179, v167
	v_div_fmas_f32 v136, v136, v138, v179
	v_pk_mul_f32 v[200:201], v[86:87], v[178:179] op_sel_hi:[1,0]
	v_div_fixup_f32 v198, v136, v198, 1.0
	v_mul_f32_e32 v138, 0xbfb8aa3b, v200
	v_pk_mul_f32 v[196:197], v[198:199], v[196:197]
	v_exp_f32_e32 v198, v138
	v_mul_f32_e32 v138, 0xbfb8aa3b, v201
	v_exp_f32_e32 v199, v138
	v_lshlrev_b32_e32 v136, 16, v137
	v_and_b32_e32 v137, 0xffff0000, v137
	v_pk_mul_f32 v[136:137], v[148:149], v[136:137] op_sel_hi:[0,1]
	v_pk_add_f32 v[198:199], v[198:199], 1.0 op_sel_hi:[1,0]
	v_pk_mul_f32 v[136:137], v[134:135], v[136:137]
	v_div_scale_f32 v138, s[26:27], v199, v199, 1.0
	v_rcp_f32_e32 v167, v138
	v_pk_mul_f32 v[136:137], v[200:201], v[136:137]
	v_fma_f32 v179, -v138, v167, 1.0
	v_fmac_f32_e32 v167, v179, v167
	v_div_scale_f32 v179, vcc, 1.0, v199, 1.0
	v_mul_f32_e32 v200, v179, v167
	v_fma_f32 v201, -v138, v200, v179
	v_fmac_f32_e32 v200, v201, v167
	v_fma_f32 v138, -v138, v200, v179
	v_div_fmas_f32 v138, v138, v167, v200
	v_div_fixup_f32 v199, v138, v199, 1.0
	v_div_scale_f32 v138, s[26:27], v198, v198, 1.0
	v_rcp_f32_e32 v167, v138
	s_nop 0
	v_fma_f32 v179, -v138, v167, 1.0
	v_fmac_f32_e32 v167, v179, v167
	v_div_scale_f32 v179, vcc, 1.0, v198, 1.0
	v_mul_f32_e32 v200, v179, v167
	v_fma_f32 v201, -v138, v200, v179
	v_fmac_f32_e32 v200, v201, v167
	v_fma_f32 v138, -v138, v200, v179
	v_div_fmas_f32 v138, v138, v167, v200
	v_div_fixup_f32 v198, v138, v198, 1.0
	v_pk_mul_f32 v[198:199], v[198:199], v[136:137]
	v_lshlrev_b32_e32 v136, 16, v139
	v_and_b32_e32 v137, 0xffff0000, v139
	v_pk_mul_f32 v[136:137], v[148:149], v[136:137] op_sel_hi:[0,1]
	v_pk_mul_f32 v[138:139], v[82:83], v[178:179] op_sel_hi:[1,0]
	v_pk_mul_f32 v[136:137], v[130:131], v[136:137]
	v_mul_f32_e32 v167, 0xbfb8aa3b, v138
	v_pk_mul_f32 v[136:137], v[138:139], v[136:137]
	v_mul_f32_e32 v138, 0xbfb8aa3b, v139
	v_exp_f32_e32 v178, v167
	v_exp_f32_e32 v179, v138
	s_nop 0
	v_pk_add_f32 v[138:139], v[178:179], 1.0 op_sel_hi:[1,0]
	s_nop 0
	v_div_scale_f32 v148, s[26:27], v139, v139, 1.0
	v_rcp_f32_e32 v167, v148
	s_nop 0
	v_fma_f32 v178, -v148, v167, 1.0
	v_fmac_f32_e32 v167, v178, v167
	v_div_scale_f32 v178, vcc, 1.0, v139, 1.0
	v_mul_f32_e32 v179, v178, v167
	v_fma_f32 v200, -v148, v179, v178
	v_fmac_f32_e32 v179, v200, v167
	v_fma_f32 v148, -v148, v179, v178
	v_div_fmas_f32 v148, v148, v167, v179
	v_div_fixup_f32 v139, v148, v139, 1.0
	v_div_scale_f32 v148, s[26:27], v138, v138, 1.0
	v_rcp_f32_e32 v167, v148
	s_mov_b32 s26, 0x3b800000
	s_mov_b32 s27, 0x3b800000
	v_fma_f32 v178, -v148, v167, 1.0
	v_fmac_f32_e32 v167, v178, v167
	v_div_scale_f32 v178, vcc, 1.0, v138, 1.0
	v_mul_f32_e32 v179, v178, v167
	v_fma_f32 v200, -v148, v179, v178
	v_fmac_f32_e32 v179, v200, v167
	v_fma_f32 v148, -v148, v179, v178
	v_div_fmas_f32 v148, v148, v167, v179
	v_div_fixup_f32 v138, v148, v138, 1.0
	v_pk_mul_f32 v[178:179], v[138:139], v[136:137]
	v_cvt_pk_bf16_f32 v136, v194, v195
	v_cvt_pk_bf16_f32 v137, v198, v199
	v_cvt_pk_bf16_f32 v138, v196, v197
	v_cvt_pk_bf16_f32 v139, v178, v179
	global_store_dwordx4 v[176:177], v[136:139], off
	s_and_b64 vcc, exec, s[44:45]
	s_nop 0
	v_add_u32_e32 v136, 0xa0, v166
	v_ashrrev_i32_e32 v137, 31, v136
	v_lshlrev_b64 v[138:139], 7, v[136:137]
	v_lshl_add_u64 v[194:195], s[66:67], 0, v[138:139]
	v_lshl_add_u64 v[178:179], v[180:181], 2, v[194:195]
	global_load_dwordx4 v[196:199], v[178:179], off
	global_load_dwordx4 v[232:235], v[178:179], off offset:16
	v_mad_u64_u32 v[238:239], s[100:101], v136, s70, 0
	v_mov_b32_e32 v240, v239
	v_mad_u64_u32 v[240:241], s[100:101], v137, s70, v[240:241]
	v_mov_b32_e32 v239, v240
	v_lshl_add_u64 v[238:239], v[238:239], 1, s[64:65]
	v_lshl_add_u64 v[236:237], v[164:165], 1, v[238:239]
	global_load_dwordx4 v[242:245], v[236:237], off
	global_load_dword v246, v[140:141], off offset:640
	s_waitcnt vmcnt(0)
	v_mov_b32_e32 v138, v197
	v_mov_b32_e32 v139, v198
	v_mov_b32_e32 v197, v199
	v_pk_add_f32 v[138:139], v[138:139], v[196:197]
	s_nop 0
	v_pk_add_f32 v[138:139], v[138:139], v[138:139] op_sel:[0,1] op_sel_hi:[1,0]
	s_cbranch_vccnz .LBB0_233
	v_mov_b64_e32 v[196:197], v[232:233]
	v_mov_b64_e32 v[198:199], v[234:235]
	s_mov_b32 s27, 0x3b000000
	v_mov_b32_e32 v178, v197
	v_mov_b32_e32 v179, v198
	v_mov_b32_e32 v197, v199
	v_pk_add_f32 v[178:179], v[178:179], v[196:197]
	s_nop 0
	v_add_f32_e32 v139, v178, v179
	v_add_f32_e32 v138, v138, v139
; DI unsigned pk(float lo, float hi) { f32x2 v = {lo, hi}; bf2_t b = __builtin_convertvector(v, bf2_t); return __builtin_bit_cast(unsigned, b); }
; DI float bflo(unsigned w) { return __uint_as_float(w << 16); }
; DI float bfhi(unsigned w) { return __uint_as_float(w & 0xffff0000u); }
; DI float sigmoidf_(float x) { return 1.0f / (1.0f + __expf(-x)); }
; DI void gemm_epilogue(const GemmDesc& g, f32x4 (&acc)[2][2][4][2], int brow, int bcol, int wr, int wc, int fr, int fq) {
;     ...
;           const int row = rowb + ai * HALF + m * 16;
;           float rs;
;           { const float* sp = g.f0 + (size_t)row * 32 + head * 8;
;             const f32x4 s0 = gld<f32x4>(sp); float ssum = (s0[0] + s0[1]) + (s0[2] + s0[3]);
;             if (g.dvshift == 9) { const f32x4 s1 = gld<f32x4>(sp + 4); ssum += (s1[0] + s1[1]) + (s1[2] + s1[3]); }
;             rs = rsqrtf(ssum * (g.dvshift == 9 ? (1.0f / 512.0f) : (1.0f / 256.0f)) + EPS); }
;           bf16_t* op = g.o0 + (size_t)row * N + col;
;           const u32x4 ow = gld<u32x4>(op);
;           const float ru = gld<float>(g.rowscale + row);
;           const f32x4 v0 = acc[ai][bj][m][0] * ru, v1 = acc[ai][bj][m][1] * ru;
;           float o[8] = {bflo(ow.x), bfhi(ow.x), bflo(ow.y), bfhi(ow.y), bflo(ow.z), bfhi(ow.z), bflo(ow.w), bfhi(ow.w)};
; #pragma unroll
;           for (int j = 0; j < 4; ++j) { o[j] = o[j] * rs * g0[j] * v0[j] * sigmoidf_(v0[j]); o[4 + j] = o[4 + j] * rs * g1[j] * v1[j] * sigmoidf_(v1[j]); }
;           u32x4 w; w.x = pk(o[0], o[1]); w.y = pk(o[2], o[3]); w.z = pk(o[4], o[5]); w.w = pk(o[6], o[7]);
;           gst<u32x4>(op, w);
;         }
.LBB0_233:
	v_fma_f32 v138, s27, v138, v204
	v_cmp_gt_f32_e32 vcc, s33, v138
	v_mul_f32_e32 v139, 0x4b800000, v138
	s_nop 0
	v_cndmask_b32_e32 v138, v138, v139, vcc
	v_rsq_f32_e32 v138, v138
	s_nop 0
	v_mul_f32_e32 v139, 0x45800000, v138
	v_cndmask_b32_e32 v148, v138, v139, vcc
	v_mad_u64_u32 v[138:139], vcc, v136, s70, 0
	v_mov_b32_e32 v136, v139
	v_mad_u64_u32 v[136:137], vcc, v137, s70, v[136:137]
	v_mov_b32_e32 v139, v136
	v_lshl_add_u64 v[136:137], v[138:139], 1, s[64:65]
	v_lshl_add_u64 v[178:179], v[164:165], 1, v[136:137]
	v_mov_b64_e32 v[136:137], v[242:243]
	v_mov_b64_e32 v[138:139], v[244:245]
	v_mov_b32_e32 v196, v246
	v_lshlrev_b32_e32 v198, 16, v136
	v_pk_mul_f32 v[200:201], v[76:77], v[196:197] op_sel_hi:[1,0]
	v_and_b32_e32 v199, 0xffff0000, v136
	v_mul_f32_e32 v136, 0xbfb8aa3b, v200
	v_exp_f32_e32 v202, v136
	v_mul_f32_e32 v136, 0xbfb8aa3b, v201
	v_exp_f32_e32 v203, v136
	v_pk_mul_f32 v[198:199], v[148:149], v[198:199] op_sel_hi:[0,1]
	v_pk_mul_f32 v[198:199], v[132:133], v[198:199]
	s_nop 0
	v_pk_mul_f32 v[198:199], v[200:201], v[198:199]
	v_pk_add_f32 v[200:201], v[202:203], 1.0 op_sel_hi:[1,0]
	s_nop 0
	v_div_scale_f32 v136, vcc, v201, v201, 1.0
	v_rcp_f32_e32 v167, v136
	s_nop 0
	v_fma_f32 v197, -v136, v167, 1.0
	v_fmac_f32_e32 v167, v197, v167
	v_div_scale_f32 v197, vcc, 1.0, v201, 1.0
	v_mul_f32_e32 v202, v197, v167
	v_fma_f32 v203, -v136, v202, v197
	v_fmac_f32_e32 v202, v203, v167
	v_fma_f32 v136, -v136, v202, v197
	v_div_fmas_f32 v136, v136, v167, v202
	v_div_fixup_f32 v201, v136, v201, 1.0
	v_div_scale_f32 v136, vcc, v200, v200, 1.0
	v_rcp_f32_e32 v167, v136
	s_nop 0
	v_fma_f32 v197, -v136, v167, 1.0
	v_fmac_f32_e32 v167, v197, v167
	v_div_scale_f32 v197, vcc, 1.0, v200, 1.0
	v_mul_f32_e32 v202, v197, v167
	v_fma_f32 v203, -v136, v202, v197
	v_fmac_f32_e32 v202, v203, v167
	v_fma_f32 v136, -v136, v202, v197
	v_div_fmas_f32 v136, v136, v167, v202
	v_pk_mul_f32 v[202:203], v[72:73], v[196:197] op_sel_hi:[1,0]
	v_div_fixup_f32 v200, v136, v200, 1.0
	v_mul_f32_e32 v136, 0xbfb8aa3b, v202
	v_exp_f32_e32 v212, v136
	v_mul_f32_e32 v136, 0xbfb8aa3b, v203
	v_exp_f32_e32 v213, v136
	v_pk_mul_f32 v[198:199], v[200:201], v[198:199]
	v_lshlrev_b32_e32 v200, 16, v138
	v_and_b32_e32 v201, 0xffff0000, v138
	v_pk_mul_f32 v[200:201], v[148:149], v[200:201] op_sel_hi:[0,1]
	v_pk_mul_f32 v[200:201], v[128:129], v[200:201]
	s_nop 0
	v_pk_mul_f32 v[200:201], v[202:203], v[200:201]
	v_pk_add_f32 v[202:203], v[212:213], 1.0 op_sel_hi:[1,0]
	s_nop 0
	v_div_scale_f32 v136, vcc, v203, v203, 1.0
	v_rcp_f32_e32 v138, v136
	s_nop 0
	v_fma_f32 v167, -v136, v138, 1.0
	v_fmac_f32_e32 v138, v167, v138
	v_div_scale_f32 v167, vcc, 1.0, v203, 1.0
	v_mul_f32_e32 v197, v167, v138
	v_fma_f32 v212, -v136, v197, v167
	v_fmac_f32_e32 v197, v212, v138
	v_fma_f32 v136, -v136, v197, v167
	v_div_fmas_f32 v136, v136, v138, v197
	v_div_fixup_f32 v203, v136, v203, 1.0
	v_div_scale_f32 v136, vcc, v202, v202, 1.0
	v_rcp_f32_e32 v138, v136
	s_nop 0
	v_fma_f32 v167, -v136, v138, 1.0
	v_fmac_f32_e32 v138, v167, v138
	v_div_scale_f32 v167, vcc, 1.0, v202, 1.0
	v_mul_f32_e32 v197, v167, v138
	v_fma_f32 v212, -v136, v197, v167
	v_fmac_f32_e32 v197, v212, v138
	v_fma_f32 v136, -v136, v197, v167
	v_div_fmas_f32 v136, v136, v138, v197
	v_pk_mul_f32 v[212:213], v[78:79], v[196:197] op_sel_hi:[1,0]
	v_div_fixup_f32 v202, v136, v202, 1.0
	v_mul_f32_e32 v138, 0xbfb8aa3b, v212
	v_pk_mul_f32 v[200:201], v[202:203], v[200:201]
	v_exp_f32_e32 v202, v138
	v_mul_f32_e32 v138, 0xbfb8aa3b, v213
	v_exp_f32_e32 v203, v138
	v_lshlrev_b32_e32 v136, 16, v137
	v_and_b32_e32 v137, 0xffff0000, v137
	v_pk_mul_f32 v[136:137], v[148:149], v[136:137] op_sel_hi:[0,1]
	v_pk_add_f32 v[202:203], v[202:203], 1.0 op_sel_hi:[1,0]
	v_pk_mul_f32 v[136:137], v[134:135], v[136:137]
	v_div_scale_f32 v138, vcc, v203, v203, 1.0
	v_rcp_f32_e32 v167, v138
	v_pk_mul_f32 v[136:137], v[212:213], v[136:137]
	v_fma_f32 v197, -v138, v167, 1.0
	v_fmac_f32_e32 v167, v197, v167
	v_div_scale_f32 v197, vcc, 1.0, v203, 1.0
	v_mul_f32_e32 v212, v197, v167
	v_fma_f32 v213, -v138, v212, v197
	v_fmac_f32_e32 v212, v213, v167
	v_fma_f32 v138, -v138, v212, v197
	v_div_fmas_f32 v138, v138, v167, v212
	v_div_fixup_f32 v203, v138, v203, 1.0
	v_div_scale_f32 v138, vcc, v202, v202, 1.0
	v_rcp_f32_e32 v167, v138
	s_nop 0
	v_fma_f32 v197, -v138, v167, 1.0
	v_fmac_f32_e32 v167, v197, v167
	v_div_scale_f32 v197, vcc, 1.0, v202, 1.0
	v_mul_f32_e32 v212, v197, v167
	v_fma_f32 v213, -v138, v212, v197
	v_fmac_f32_e32 v212, v213, v167
	v_fma_f32 v138, -v138, v212, v197
	v_div_fmas_f32 v138, v138, v167, v212
	v_div_fixup_f32 v202, v138, v202, 1.0
	v_pk_mul_f32 v[202:203], v[202:203], v[136:137]
	v_lshlrev_b32_e32 v136, 16, v139
	v_and_b32_e32 v137, 0xffff0000, v139
	v_pk_mul_f32 v[136:137], v[148:149], v[136:137] op_sel_hi:[0,1]
	v_pk_mul_f32 v[138:139], v[74:75], v[196:197] op_sel_hi:[1,0]
	v_pk_mul_f32 v[136:137], v[130:131], v[136:137]
	v_mul_f32_e32 v167, 0xbfb8aa3b, v138
	v_pk_mul_f32 v[136:137], v[138:139], v[136:137]
	v_mul_f32_e32 v138, 0xbfb8aa3b, v139
	v_exp_f32_e32 v196, v167
	v_exp_f32_e32 v197, v138
	s_nop 0
	v_pk_add_f32 v[138:139], v[196:197], 1.0 op_sel_hi:[1,0]
	s_nop 0
	v_div_scale_f32 v148, vcc, v139, v139, 1.0
	v_rcp_f32_e32 v167, v148
	s_nop 0
	v_fma_f32 v196, -v148, v167, 1.0
	v_fmac_f32_e32 v167, v196, v167
	v_div_scale_f32 v196, vcc, 1.0, v139, 1.0
	v_mul_f32_e32 v197, v196, v167
	v_fma_f32 v212, -v148, v197, v196
	v_fmac_f32_e32 v197, v212, v167
	v_fma_f32 v148, -v148, v197, v196
	v_div_fmas_f32 v148, v148, v167, v197
	v_div_fixup_f32 v139, v148, v139, 1.0
	v_div_scale_f32 v148, vcc, v138, v138, 1.0
	v_rcp_f32_e32 v167, v148
	s_nop 0
	v_fma_f32 v196, -v148, v167, 1.0
	v_fmac_f32_e32 v167, v196, v167
	v_div_scale_f32 v196, vcc, 1.0, v138, 1.0
	v_mul_f32_e32 v197, v196, v167
	v_fma_f32 v212, -v148, v197, v196
	v_fmac_f32_e32 v197, v212, v167
	v_fma_f32 v148, -v148, v197, v196
	v_div_fmas_f32 v148, v148, v167, v197
	v_div_fixup_f32 v138, v148, v138, 1.0
	v_pk_mul_f32 v[196:197], v[138:139], v[136:137]
	v_cvt_pk_bf16_f32 v136, v198, v199
	v_cvt_pk_bf16_f32 v137, v202, v203
	v_cvt_pk_bf16_f32 v138, v200, v201
	v_cvt_pk_bf16_f32 v139, v196, v197
	global_store_dwordx4 v[178:179], v[136:139], off
	s_and_b64 vcc, exec, s[44:45]
	s_nop 0
	v_add_u32_e32 v136, 0xb0, v166
	v_ashrrev_i32_e32 v137, 31, v136
	v_lshlrev_b64 v[138:139], 7, v[136:137]
	v_lshl_add_u64 v[196:197], s[66:67], 0, v[138:139]
	v_lshl_add_u64 v[180:181], v[180:181], 2, v[196:197]
	global_load_dwordx4 v[198:201], v[180:181], off
	global_load_dwordx4 v[232:235], v[180:181], off offset:16
	v_mad_u64_u32 v[238:239], s[100:101], v136, s70, 0
	v_mov_b32_e32 v240, v239
	v_mad_u64_u32 v[240:241], s[100:101], v137, s70, v[240:241]
	v_mov_b32_e32 v239, v240
	v_lshl_add_u64 v[238:239], v[238:239], 1, s[64:65]
	v_lshl_add_u64 v[236:237], v[164:165], 1, v[238:239]
	global_load_dwordx4 v[242:245], v[236:237], off
	global_load_dword v246, v[140:141], off offset:704
	s_waitcnt vmcnt(0)
; DI void gemm_epilogue(const GemmDesc& g, f32x4 (&acc)[2][2][4][2], int brow, int bcol, int wr, int wc, int fr, int fq) {
;     ...
;           { const float* sp = g.f0 + (size_t)row * 32 + head * 8;
;             const f32x4 s0 = gld<f32x4>(sp); float ssum = (s0[0] + s0[1]) + (s0[2] + s0[3]);
;             if (g.dvshift == 9) { const f32x4 s1 = gld<f32x4>(sp + 4); ssum += (s1[0] + s1[1]) + (s1[2] + s1[3]); }
;             rs = rsqrtf(ssum * (g.dvshift == 9 ? (1.0f / 512.0f) : (1.0f / 256.0f)) + EPS); }
	v_mov_b32_e32 v138, v199
	v_mov_b32_e32 v139, v200
	v_mov_b32_e32 v199, v201
	v_pk_add_f32 v[138:139], v[138:139], v[198:199]
	s_nop 0
	v_pk_add_f32 v[138:139], v[138:139], v[138:139] op_sel:[0,1] op_sel_hi:[1,0]
	s_cbranch_vccnz .LBB0_235
	v_mov_b64_e32 v[198:199], v[232:233]
	v_mov_b64_e32 v[200:201], v[234:235]
	s_mov_b32 s26, 0x3b000000
	v_mov_b32_e32 v180, v199
	v_mov_b32_e32 v181, v200
	v_mov_b32_e32 v199, v201
	v_pk_add_f32 v[180:181], v[180:181], v[198:199]
	s_nop 0
	v_add_f32_e32 v139, v180, v181
	v_add_f32_e32 v138, v138, v139
; DI unsigned pk(float lo, float hi) { f32x2 v = {lo, hi}; bf2_t b = __builtin_convertvector(v, bf2_t); return __builtin_bit_cast(unsigned, b); }
; DI float bflo(unsigned w) { return __uint_as_float(w << 16); }
; DI float bfhi(unsigned w) { return __uint_as_float(w & 0xffff0000u); }
; DI float sigmoidf_(float x) { return 1.0f / (1.0f + __expf(-x)); }
; DI void gemm_epilogue(const GemmDesc& g, f32x4 (&acc)[2][2][4][2], int brow, int bcol, int wr, int wc, int fr, int fq) {
;     ...
;     for (int bj = 0; bj < 2; ++bj) {
;       const int col = colb + bj * HALF;
;       f32x4 g0 = {1.f, 1.f, 1.f, 1.f}, g1 = g0;
;       if (g.c0) { g0 = gld<f32x4>(g.c0 + (col & dvm)); g1 = gld<f32x4>(g.c0 + (col & dvm) + 4); }
;       const int head = col >> g.dvshift;
; #pragma unroll
;       for (int ai = 0; ai < 2; ++ai)
; #pragma unroll
;         for (int m = 0; m < 4; ++m) {
;           const int row = rowb + ai * HALF + m * 16;
;           float rs;
;           { const float* sp = g.f0 + (size_t)row * 32 + head * 8;
;             const f32x4 s0 = gld<f32x4>(sp); float ssum = (s0[0] + s0[1]) + (s0[2] + s0[3]);
;             if (g.dvshift == 9) { const f32x4 s1 = gld<f32x4>(sp + 4); ssum += (s1[0] + s1[1]) + (s1[2] + s1[3]); }
;             rs = rsqrtf(ssum * (g.dvshift == 9 ? (1.0f / 512.0f) : (1.0f / 256.0f)) + EPS); }
;           bf16_t* op = g.o0 + (size_t)row * N + col;
;           const u32x4 ow = gld<u32x4>(op);
;           const float ru = gld<float>(g.rowscale + row);
;           const f32x4 v0 = acc[ai][bj][m][0] * ru, v1 = acc[ai][bj][m][1] * ru;
;           float o[8] = {bflo(ow.x), bfhi(ow.x), bflo(ow.y), bfhi(ow.y), bflo(ow.z), bfhi(ow.z), bflo(ow.w), bfhi(ow.w)};
; #pragma unroll
;           for (int j = 0; j < 4; ++j) { o[j] = o[j] * rs * g0[j] * v0[j] * sigmoidf_(v0[j]); o[4 + j] = o[4 + j] * rs * g1[j] * v1[j] * sigmoidf_(v1[j]); }
;           u32x4 w; w.x = pk(o[0], o[1]); w.y = pk(o[2], o[3]); w.z = pk(o[4], o[5]); w.w = pk(o[6], o[7]);
;           gst<u32x4>(op, w);
;         }
.LBB0_235:
	v_fma_f32 v138, s26, v138, v204
	v_cmp_gt_f32_e32 vcc, s33, v138
	v_mul_f32_e32 v139, 0x4b800000, v138
	s_nop 0
	v_cndmask_b32_e32 v138, v138, v139, vcc
	v_rsq_f32_e32 v138, v138
	s_nop 0
	v_mul_f32_e32 v139, 0x45800000, v138
	v_cndmask_b32_e32 v148, v138, v139, vcc
	v_mad_u64_u32 v[138:139], s[26:27], v136, s70, 0
	v_mov_b32_e32 v136, v139
	v_mad_u64_u32 v[136:137], s[26:27], v137, s70, v[136:137]
	v_mov_b32_e32 v139, v136
	v_lshl_add_u64 v[136:137], v[138:139], 1, s[64:65]
	v_lshl_add_u64 v[180:181], v[164:165], 1, v[136:137]
	v_mov_b64_e32 v[136:137], v[242:243]
	v_mov_b64_e32 v[138:139], v[244:245]
	v_mov_b32_e32 v198, v246
	v_lshlrev_b32_e32 v200, 16, v136
	v_pk_mul_f32 v[202:203], v[68:69], v[198:199] op_sel_hi:[1,0]
	v_and_b32_e32 v201, 0xffff0000, v136
	v_mul_f32_e32 v136, 0xbfb8aa3b, v202
	v_exp_f32_e32 v212, v136
	v_mul_f32_e32 v136, 0xbfb8aa3b, v203
	v_exp_f32_e32 v213, v136
	v_pk_mul_f32 v[200:201], v[148:149], v[200:201] op_sel_hi:[0,1]
	v_pk_mul_f32 v[132:133], v[132:133], v[200:201]
	v_pk_add_f32 v[200:201], v[212:213], 1.0 op_sel_hi:[1,0]
	s_nop 0
	v_div_scale_f32 v136, s[26:27], v201, v201, 1.0
	v_rcp_f32_e32 v165, v136
	v_pk_mul_f32 v[132:133], v[202:203], v[132:133]
	v_fma_f32 v167, -v136, v165, 1.0
	v_fmac_f32_e32 v165, v167, v165
	v_div_scale_f32 v167, vcc, 1.0, v201, 1.0
	v_mul_f32_e32 v199, v167, v165
	v_fma_f32 v202, -v136, v199, v167
	v_fmac_f32_e32 v199, v202, v165
	v_fma_f32 v136, -v136, v199, v167
	v_div_fmas_f32 v136, v136, v165, v199
	v_div_fixup_f32 v201, v136, v201, 1.0
	v_div_scale_f32 v136, s[26:27], v200, v200, 1.0
	v_rcp_f32_e32 v165, v136
	s_nop 0
	v_fma_f32 v167, -v136, v165, 1.0
	v_fmac_f32_e32 v165, v167, v165
	v_div_scale_f32 v167, vcc, 1.0, v200, 1.0
	v_mul_f32_e32 v199, v167, v165
	v_fma_f32 v202, -v136, v199, v167
	v_fmac_f32_e32 v199, v202, v165
	v_fma_f32 v136, -v136, v199, v167
	v_div_fmas_f32 v136, v136, v165, v199
	v_pk_mul_f32 v[202:203], v[64:65], v[198:199] op_sel_hi:[1,0]
	v_div_fixup_f32 v200, v136, v200, 1.0
	v_mul_f32_e32 v136, 0xbfb8aa3b, v202
	v_exp_f32_e32 v212, v136
	v_mul_f32_e32 v136, 0xbfb8aa3b, v203
	v_exp_f32_e32 v213, v136
	v_pk_mul_f32 v[132:133], v[200:201], v[132:133]
	v_lshlrev_b32_e32 v200, 16, v138
	v_and_b32_e32 v201, 0xffff0000, v138
	v_pk_mul_f32 v[200:201], v[148:149], v[200:201] op_sel_hi:[0,1]
	v_pk_mul_f32 v[128:129], v[128:129], v[200:201]
	v_pk_add_f32 v[200:201], v[212:213], 1.0 op_sel_hi:[1,0]
	v_pk_mul_f32 v[128:129], v[202:203], v[128:129]
	v_div_scale_f32 v136, s[26:27], v201, v201, 1.0
	v_rcp_f32_e32 v138, v136
	s_nop 0
	v_fma_f32 v165, -v136, v138, 1.0
	v_fmac_f32_e32 v138, v165, v138
	v_div_scale_f32 v165, vcc, 1.0, v201, 1.0
	v_mul_f32_e32 v167, v165, v138
	v_fma_f32 v199, -v136, v167, v165
	v_fmac_f32_e32 v167, v199, v138
	v_fma_f32 v136, -v136, v167, v165
	v_div_fmas_f32 v136, v136, v138, v167
	v_div_fixup_f32 v201, v136, v201, 1.0
	v_div_scale_f32 v136, s[26:27], v200, v200, 1.0
	v_rcp_f32_e32 v138, v136
	s_nop 0
	v_fma_f32 v165, -v136, v138, 1.0
	v_fmac_f32_e32 v138, v165, v138
	v_div_scale_f32 v165, vcc, 1.0, v200, 1.0
	v_mul_f32_e32 v167, v165, v138
	v_fma_f32 v199, -v136, v167, v165
	v_fmac_f32_e32 v167, v199, v138
	v_fma_f32 v136, -v136, v167, v165
	v_div_fmas_f32 v136, v136, v138, v167
	v_div_fixup_f32 v200, v136, v200, 1.0
	v_pk_mul_f32 v[202:203], v[70:71], v[198:199] op_sel_hi:[1,0]
	v_pk_mul_f32 v[128:129], v[200:201], v[128:129]
	v_lshlrev_b32_e32 v200, 16, v137
	v_and_b32_e32 v201, 0xffff0000, v137
	v_mul_f32_e32 v136, 0xbfb8aa3b, v202
	v_mul_f32_e32 v137, 0xbfb8aa3b, v203
	v_exp_f32_e32 v136, v136
	v_exp_f32_e32 v137, v137
	v_pk_mul_f32 v[200:201], v[148:149], v[200:201] op_sel_hi:[0,1]
	v_pk_mul_f32 v[134:135], v[134:135], v[200:201]
	v_pk_add_f32 v[136:137], v[136:137], 1.0 op_sel_hi:[1,0]
	s_nop 0
	v_div_scale_f32 v138, s[26:27], v137, v137, 1.0
	v_rcp_f32_e32 v165, v138
	v_pk_mul_f32 v[134:135], v[202:203], v[134:135]
	v_fma_f32 v167, -v138, v165, 1.0
	v_fmac_f32_e32 v165, v167, v165
	v_div_scale_f32 v167, vcc, 1.0, v137, 1.0
	v_mul_f32_e32 v199, v167, v165
	v_fma_f32 v200, -v138, v199, v167
	v_fmac_f32_e32 v199, v200, v165
	v_fma_f32 v138, -v138, v199, v167
	v_div_fmas_f32 v138, v138, v165, v199
	v_div_fixup_f32 v137, v138, v137, 1.0
	v_div_scale_f32 v138, s[26:27], v136, v136, 1.0
	v_rcp_f32_e32 v165, v138
	s_nop 0
	v_fma_f32 v167, -v138, v165, 1.0
	v_fmac_f32_e32 v165, v167, v165
	v_div_scale_f32 v167, vcc, 1.0, v136, 1.0
	v_mul_f32_e32 v199, v167, v165
	v_fma_f32 v200, -v138, v199, v167
	v_fmac_f32_e32 v199, v200, v165
	v_fma_f32 v138, -v138, v199, v167
	v_div_fmas_f32 v138, v138, v165, v199
	v_div_fixup_f32 v136, v138, v136, 1.0
	v_pk_mul_f32 v[134:135], v[136:137], v[134:135]
	v_lshlrev_b32_e32 v136, 16, v139
	v_and_b32_e32 v137, 0xffff0000, v139
	v_pk_mul_f32 v[138:139], v[66:67], v[198:199] op_sel_hi:[1,0]
	v_pk_mul_f32 v[136:137], v[148:149], v[136:137] op_sel_hi:[0,1]
	v_mul_f32_e32 v165, 0xbfb8aa3b, v138
	v_pk_mul_f32 v[130:131], v[130:131], v[136:137]
	v_mul_f32_e32 v136, 0xbfb8aa3b, v139
	v_exp_f32_e32 v198, v165
	v_exp_f32_e32 v199, v136
	v_pk_mul_f32 v[130:131], v[138:139], v[130:131]
	v_pk_add_f32 v[136:137], v[198:199], 1.0 op_sel_hi:[1,0]
	s_nop 0
	v_div_scale_f32 v138, s[26:27], v137, v137, 1.0
	v_rcp_f32_e32 v139, v138
	s_nop 0
	v_fma_f32 v148, -v138, v139, 1.0
	v_fmac_f32_e32 v139, v148, v139
	v_div_scale_f32 v148, vcc, 1.0, v137, 1.0
	v_mul_f32_e32 v165, v148, v139
	v_fma_f32 v167, -v138, v165, v148
	v_fmac_f32_e32 v165, v167, v139
	v_fma_f32 v138, -v138, v165, v148
	v_div_fmas_f32 v138, v138, v139, v165
	v_div_fixup_f32 v137, v138, v137, 1.0
	v_div_scale_f32 v138, s[26:27], v136, v136, 1.0
	v_rcp_f32_e32 v139, v138
	s_nop 0
	v_fma_f32 v148, -v138, v139, 1.0
	v_fmac_f32_e32 v139, v148, v139
	v_div_scale_f32 v148, vcc, 1.0, v136, 1.0
	v_mul_f32_e32 v165, v148, v139
	v_fma_f32 v167, -v138, v165, v148
	v_fmac_f32_e32 v165, v167, v139
	v_fma_f32 v138, -v138, v165, v148
	v_div_fmas_f32 v138, v138, v139, v165
	v_div_fixup_f32 v136, v138, v136, 1.0
	v_pk_mul_f32 v[136:137], v[136:137], v[130:131]
	v_cvt_pk_bf16_f32 v130, v132, v133
	v_cvt_pk_bf16_f32 v131, v134, v135
	v_cvt_pk_bf16_f32 v132, v128, v129
	v_cvt_pk_bf16_f32 v133, v136, v137
	v_or_b32_e32 v136, 0x80, v164
	s_and_b64 vcc, exec, s[46:47]
	global_store_dwordx4 v[180:181], v[130:133], off
	s_cbranch_vccnz .LBB0_237
	v_readlane_b32 s26, v255, 35
	s_nop 1
	v_and_b32_e32 v148, s26, v136
	v_readlane_b32 s26, v255, 33
	v_readlane_b32 s27, v255, 34
	s_nop 1
	v_lshl_add_u64 v[132:133], v[148:149], 2, s[26:27]
	global_load_dwordx4 v[128:131], v[132:133], off offset:16
	s_nop 0
	global_load_dwordx4 v[132:135], v[132:133], off
	s_branch .LBB0_238

; DI unsigned pk(float lo, float hi) { f32x2 v = {lo, hi}; bf2_t b = __builtin_convertvector(v, bf2_t); return __builtin_bit_cast(unsigned, b); }
; DI float bflo(unsigned w) { return __uint_as_float(w << 16); }
; DI float bfhi(unsigned w) { return __uint_as_float(w & 0xffff0000u); }
; DI float sigmoidf_(float x) { return 1.0f / (1.0f + __expf(-x)); }
; DI void gemm_epilogue(const GemmDesc& g, f32x4 (&acc)[2][2][4][2], int brow, int bcol, int wr, int wc, int fr, int fq) {
;     ...
;       if (g.c0) { g0 = gld<f32x4>(g.c0 + (col & dvm)); g1 = gld<f32x4>(g.c0 + (col & dvm) + 4); }
;       const int head = col >> g.dvshift;
; #pragma unroll
;       for (int ai = 0; ai < 2; ++ai)
; #pragma unroll
;         for (int m = 0; m < 4; ++m) {
;           const int row = rowb + ai * HALF + m * 16;
;           float rs;
;           { const float* sp = g.f0 + (size_t)row * 32 + head * 8;
;             const f32x4 s0 = gld<f32x4>(sp); float ssum = (s0[0] + s0[1]) + (s0[2] + s0[3]);
;             if (g.dvshift == 9) { const f32x4 s1 = gld<f32x4>(sp + 4); ssum += (s1[0] + s1[1]) + (s1[2] + s1[3]); }
;             rs = rsqrtf(ssum * (g.dvshift == 9 ? (1.0f / 512.0f) : (1.0f / 256.0f)) + EPS); }
;           bf16_t* op = g.o0 + (size_t)row * N + col;
;           const u32x4 ow = gld<u32x4>(op);
;           const float ru = gld<float>(g.rowscale + row);
;           const f32x4 v0 = acc[ai][bj][m][0] * ru, v1 = acc[ai][bj][m][1] * ru;
;           float o[8] = {bflo(ow.x), bfhi(ow.x), bflo(ow.y), bfhi(ow.y), bflo(ow.z), bfhi(ow.z), bflo(ow.w), bfhi(ow.w)};
; #pragma unroll
;           for (int j = 0; j < 4; ++j) { o[j] = o[j] * rs * g0[j] * v0[j] * sigmoidf_(v0[j]); o[4 + j] = o[4 + j] * rs * g1[j] * v1[j] * sigmoidf_(v1[j]); }
;           u32x4 w; w.x = pk(o[0], o[1]); w.y = pk(o[2], o[3]); w.z = pk(o[4], o[5]); w.w = pk(o[6], o[7]);
;           gst<u32x4>(op, w);
;         }
.LBB0_238:
	v_readlane_b32 s26, v255, 29
	s_and_b64 vcc, exec, s[44:45]
	s_mov_b32 s27, 0x3b800000
	v_ashrrev_i32_e32 v136, s26, v136
	v_lshlrev_b32_e32 v198, 3, v136
	v_ashrrev_i32_e32 v199, 31, v198
	v_lshl_add_u64 v[136:137], v[198:199], 2, v[182:183]
	global_load_dwordx4 v[200:203], v[136:137], off
	global_load_dwordx4 v[232:235], v[136:137], off offset:16
	global_load_dwordx4 v[242:245], v[142:143], off offset:256
	global_load_dword v246, v[140:141], off
	s_mov_b32 s26, 0x3b800000
	s_waitcnt vmcnt(0)
	v_mov_b32_e32 v138, v201
	v_mov_b32_e32 v139, v202
	v_mov_b32_e32 v201, v203
	v_pk_add_f32 v[138:139], v[138:139], v[200:201]
	s_nop 0
	v_pk_add_f32 v[138:139], v[138:139], v[138:139] op_sel:[0,1] op_sel_hi:[1,0]
	s_cbranch_vccnz .LBB0_240
	v_mov_b64_e32 v[200:201], v[232:233]
	v_mov_b64_e32 v[202:203], v[234:235]
	s_mov_b32 s27, 0x3b000000
	v_mov_b32_e32 v136, v201
	v_mov_b32_e32 v137, v202
	v_mov_b32_e32 v201, v203
	v_pk_add_f32 v[136:137], v[136:137], v[200:201]
	s_nop 0
	v_add_f32_e32 v136, v136, v137
	v_add_f32_e32 v138, v138, v136
.LBB0_240:
	v_fma_f32 v136, s27, v138, v204
	v_cmp_gt_f32_e32 vcc, s33, v136
	v_mul_f32_e32 v137, 0x4b800000, v136
	s_nop 0
	v_cndmask_b32_e32 v136, v136, v137, vcc
	v_rsq_f32_e32 v136, v136
	s_nop 0
	v_mul_f32_e32 v137, 0x45800000, v136
	v_cndmask_b32_e32 v148, v136, v137, vcc
	v_mov_b64_e32 v[136:137], v[242:243]
	v_mov_b64_e32 v[138:139], v[244:245]
	v_mov_b32_e32 v200, v246
	v_lshlrev_b32_e32 v182, 16, v136
	v_pk_mul_f32 v[202:203], v[60:61], v[200:201] op_sel_hi:[1,0]
	v_and_b32_e32 v183, 0xffff0000, v136
	v_mul_f32_e32 v136, 0xbfb8aa3b, v202
	v_exp_f32_e32 v212, v136
	v_mul_f32_e32 v136, 0xbfb8aa3b, v203
	v_exp_f32_e32 v213, v136
	v_pk_mul_f32 v[182:183], v[148:149], v[182:183] op_sel_hi:[0,1]
	v_pk_mul_f32 v[182:183], v[132:133], v[182:183]
	s_nop 0
	v_pk_mul_f32 v[182:183], v[202:203], v[182:183]
	v_pk_add_f32 v[202:203], v[212:213], 1.0 op_sel_hi:[1,0]
	s_nop 0
	v_div_scale_f32 v136, s[46:47], v203, v203, 1.0
	v_rcp_f32_e32 v165, v136
	s_nop 0
	v_fma_f32 v167, -v136, v165, 1.0
	v_fmac_f32_e32 v165, v167, v165
	v_div_scale_f32 v167, vcc, 1.0, v203, 1.0
	v_mul_f32_e32 v201, v167, v165
	v_fma_f32 v212, -v136, v201, v167
	v_fmac_f32_e32 v201, v212, v165
	v_fma_f32 v136, -v136, v201, v167
	v_div_fmas_f32 v136, v136, v165, v201
	v_div_fixup_f32 v203, v136, v203, 1.0
	v_div_scale_f32 v136, s[46:47], v202, v202, 1.0
	v_rcp_f32_e32 v165, v136
	s_nop 0
	v_fma_f32 v167, -v136, v165, 1.0
	v_fmac_f32_e32 v165, v167, v165
	v_div_scale_f32 v167, vcc, 1.0, v202, 1.0
	v_mul_f32_e32 v201, v167, v165
	v_fma_f32 v212, -v136, v201, v167
	v_fmac_f32_e32 v201, v212, v165
	v_fma_f32 v136, -v136, v201, v167
	v_div_fmas_f32 v136, v136, v165, v201
	v_pk_mul_f32 v[212:213], v[56:57], v[200:201] op_sel_hi:[1,0]
	v_div_fixup_f32 v202, v136, v202, 1.0
	v_mul_f32_e32 v136, 0xbfb8aa3b, v212
	v_exp_f32_e32 v230, v136
	v_mul_f32_e32 v136, 0xbfb8aa3b, v213
	v_exp_f32_e32 v231, v136
	v_pk_mul_f32 v[182:183], v[202:203], v[182:183]
	v_lshlrev_b32_e32 v202, 16, v138
	v_and_b32_e32 v203, 0xffff0000, v138
	v_pk_mul_f32 v[202:203], v[148:149], v[202:203] op_sel_hi:[0,1]
	v_pk_mul_f32 v[202:203], v[128:129], v[202:203]
	s_nop 0
	v_pk_mul_f32 v[202:203], v[212:213], v[202:203]
	v_pk_add_f32 v[212:213], v[230:231], 1.0 op_sel_hi:[1,0]
	s_nop 0
	v_div_scale_f32 v136, s[46:47], v213, v213, 1.0
	v_rcp_f32_e32 v138, v136
	s_nop 0
	v_fma_f32 v165, -v136, v138, 1.0
	v_fmac_f32_e32 v138, v165, v138
	v_div_scale_f32 v165, vcc, 1.0, v213, 1.0
	v_mul_f32_e32 v167, v165, v138
	v_fma_f32 v201, -v136, v167, v165
	v_fmac_f32_e32 v167, v201, v138
	v_fma_f32 v136, -v136, v167, v165
	v_div_fmas_f32 v136, v136, v138, v167
	v_div_fixup_f32 v213, v136, v213, 1.0
	v_div_scale_f32 v136, s[46:47], v212, v212, 1.0
	v_rcp_f32_e32 v138, v136
	s_nop 0
	v_fma_f32 v165, -v136, v138, 1.0
	v_fmac_f32_e32 v138, v165, v138
	v_div_scale_f32 v165, vcc, 1.0, v212, 1.0
	v_mul_f32_e32 v167, v165, v138
	v_fma_f32 v201, -v136, v167, v165
	v_fmac_f32_e32 v167, v201, v138
	v_fma_f32 v136, -v136, v167, v165
	v_div_fmas_f32 v136, v136, v138, v167
	v_div_fixup_f32 v212, v136, v212, 1.0
	v_pk_mul_f32 v[202:203], v[212:213], v[202:203]
	v_pk_mul_f32 v[212:213], v[62:63], v[200:201] op_sel_hi:[1,0]
	v_lshlrev_b32_e32 v136, 16, v137
	v_mul_f32_e32 v138, 0xbfb8aa3b, v212
	v_exp_f32_e32 v230, v138
	v_mul_f32_e32 v138, 0xbfb8aa3b, v213
	v_exp_f32_e32 v231, v138
	v_and_b32_e32 v137, 0xffff0000, v137
	v_pk_mul_f32 v[136:137], v[148:149], v[136:137] op_sel_hi:[0,1]
	v_pk_mul_f32 v[136:137], v[134:135], v[136:137]
	s_nop 0
	v_pk_mul_f32 v[136:137], v[212:213], v[136:137]
	v_pk_add_f32 v[212:213], v[230:231], 1.0 op_sel_hi:[1,0]
	s_nop 0
	v_div_scale_f32 v138, s[46:47], v213, v213, 1.0
	v_rcp_f32_e32 v165, v138
	s_nop 0
	v_fma_f32 v167, -v138, v165, 1.0
	v_fmac_f32_e32 v165, v167, v165
	v_div_scale_f32 v167, vcc, 1.0, v213, 1.0
	v_mul_f32_e32 v201, v167, v165
	v_fma_f32 v229, -v138, v201, v167
	v_fmac_f32_e32 v201, v229, v165
	v_fma_f32 v138, -v138, v201, v167
	v_div_fmas_f32 v138, v138, v165, v201
	v_div_fixup_f32 v213, v138, v213, 1.0
	v_div_scale_f32 v138, s[46:47], v212, v212, 1.0
	v_rcp_f32_e32 v165, v138
	s_nop 0
	v_fma_f32 v167, -v138, v165, 1.0
	v_fmac_f32_e32 v165, v167, v165
	v_div_scale_f32 v167, vcc, 1.0, v212, 1.0
	v_mul_f32_e32 v201, v167, v165
	v_fma_f32 v229, -v138, v201, v167
	v_fmac_f32_e32 v201, v229, v165
	v_fma_f32 v138, -v138, v201, v167
	v_div_fmas_f32 v138, v138, v165, v201
	v_div_fixup_f32 v212, v138, v212, 1.0
	v_pk_mul_f32 v[212:213], v[212:213], v[136:137]
	v_lshlrev_b32_e32 v136, 16, v139
	v_and_b32_e32 v137, 0xffff0000, v139
	v_pk_mul_f32 v[136:137], v[148:149], v[136:137] op_sel_hi:[0,1]
; DI unsigned pk(float lo, float hi) { f32x2 v = {lo, hi}; bf2_t b = __builtin_convertvector(v, bf2_t); return __builtin_bit_cast(unsigned, b); }
; DI float bflo(unsigned w) { return __uint_as_float(w << 16); }
; DI float bfhi(unsigned w) { return __uint_as_float(w & 0xffff0000u); }
; DI float sigmoidf_(float x) { return 1.0f / (1.0f + __expf(-x)); }
; DI void gemm_epilogue(const GemmDesc& g, f32x4 (&acc)[2][2][4][2], int brow, int bcol, int wr, int wc, int fr, int fq) {
;     ...
;           const int row = rowb + ai * HALF + m * 16;
;           float rs;
;           { const float* sp = g.f0 + (size_t)row * 32 + head * 8;
;             const f32x4 s0 = gld<f32x4>(sp); float ssum = (s0[0] + s0[1]) + (s0[2] + s0[3]);
;             if (g.dvshift == 9) { const f32x4 s1 = gld<f32x4>(sp + 4); ssum += (s1[0] + s1[1]) + (s1[2] + s1[3]); }
;             rs = rsqrtf(ssum * (g.dvshift == 9 ? (1.0f / 512.0f) : (1.0f / 256.0f)) + EPS); }
;           bf16_t* op = g.o0 + (size_t)row * N + col;
;           const u32x4 ow = gld<u32x4>(op);
;           const float ru = gld<float>(g.rowscale + row);
;           const f32x4 v0 = acc[ai][bj][m][0] * ru, v1 = acc[ai][bj][m][1] * ru;
;           float o[8] = {bflo(ow.x), bfhi(ow.x), bflo(ow.y), bfhi(ow.y), bflo(ow.z), bfhi(ow.z), bflo(ow.w), bfhi(ow.w)};
; #pragma unroll
;           for (int j = 0; j < 4; ++j) { o[j] = o[j] * rs * g0[j] * v0[j] * sigmoidf_(v0[j]); o[4 + j] = o[4 + j] * rs * g1[j] * v1[j] * sigmoidf_(v1[j]); }
;           u32x4 w; w.x = pk(o[0], o[1]); w.y = pk(o[2], o[3]); w.z = pk(o[4], o[5]); w.w = pk(o[6], o[7]);
;           gst<u32x4>(op, w);
;         }
	v_pk_mul_f32 v[138:139], v[58:59], v[200:201] op_sel_hi:[1,0]
	v_pk_mul_f32 v[136:137], v[130:131], v[136:137]
	v_mul_f32_e32 v165, 0xbfb8aa3b, v138
	v_pk_mul_f32 v[136:137], v[138:139], v[136:137]
	v_mul_f32_e32 v138, 0xbfb8aa3b, v139
	v_exp_f32_e32 v200, v165
	v_exp_f32_e32 v201, v138
	s_nop 0
	v_pk_add_f32 v[138:139], v[200:201], 1.0 op_sel_hi:[1,0]
	s_nop 0
	v_div_scale_f32 v148, s[46:47], v139, v139, 1.0
	v_rcp_f32_e32 v165, v148
	s_nop 0
	v_fma_f32 v167, -v148, v165, 1.0
	v_fmac_f32_e32 v165, v167, v165
	v_div_scale_f32 v167, vcc, 1.0, v139, 1.0
	v_mul_f32_e32 v200, v167, v165
	v_fma_f32 v201, -v148, v200, v167
	v_fmac_f32_e32 v200, v201, v165
	v_fma_f32 v148, -v148, v200, v167
	v_div_fmas_f32 v148, v148, v165, v200
	v_div_fixup_f32 v139, v148, v139, 1.0
	v_div_scale_f32 v148, s[46:47], v138, v138, 1.0
	v_rcp_f32_e32 v165, v148
	s_nop 0
	v_fma_f32 v167, -v148, v165, 1.0
	v_fmac_f32_e32 v165, v167, v165
	v_div_scale_f32 v167, vcc, 1.0, v138, 1.0
	v_mul_f32_e32 v200, v167, v165
	v_fma_f32 v201, -v148, v200, v167
	v_fmac_f32_e32 v200, v201, v165
	v_fma_f32 v148, -v148, v200, v167
	v_div_fmas_f32 v148, v148, v165, v200
	v_div_fixup_f32 v138, v148, v138, 1.0
	v_pk_mul_f32 v[200:201], v[138:139], v[136:137]
	v_cvt_pk_bf16_f32 v136, v182, v183
	v_cvt_pk_bf16_f32 v137, v212, v213
	v_cvt_pk_bf16_f32 v138, v202, v203
	v_cvt_pk_bf16_f32 v139, v200, v201
	global_store_dwordx4 v[142:143], v[136:139], off offset:256
	s_and_b64 vcc, exec, s[44:45]
	s_nop 0
	v_lshl_add_u64 v[138:139], v[198:199], 2, v[184:185]
	global_load_dwordx4 v[182:185], v[138:139], off
	global_load_dwordx4 v[232:235], v[138:139], off offset:16
	global_load_dwordx4 v[242:245], v[168:169], off offset:256
	global_load_dword v246, v[140:141], off offset:64
	s_waitcnt vmcnt(0)
	v_mov_b32_e32 v136, v183
	v_mov_b32_e32 v137, v184
	v_mov_b32_e32 v183, v185
	v_pk_add_f32 v[136:137], v[136:137], v[182:183]
	s_nop 0
	v_pk_add_f32 v[136:137], v[136:137], v[136:137] op_sel:[0,1] op_sel_hi:[1,0]
	s_cbranch_vccnz .LBB0_242
	v_mov_b64_e32 v[182:183], v[232:233]
	v_mov_b64_e32 v[184:185], v[234:235]
	s_mov_b32 s26, 0x3b000000
	v_mov_b32_e32 v138, v183
	v_mov_b32_e32 v139, v184
	v_mov_b32_e32 v183, v185
	v_pk_add_f32 v[138:139], v[138:139], v[182:183]
	s_nop 0
	v_add_f32_e32 v137, v138, v139
	v_add_f32_e32 v136, v136, v137
.LBB0_242:
	v_fma_f32 v136, s26, v136, v204
	v_cmp_gt_f32_e32 vcc, s33, v136
	v_mul_f32_e32 v137, 0x4b800000, v136
	s_nop 0
	v_cndmask_b32_e32 v136, v136, v137, vcc
	v_rsq_f32_e32 v136, v136
	s_nop 0
	v_mul_f32_e32 v137, 0x45800000, v136
	v_cndmask_b32_e32 v142, v136, v137, vcc
	v_mov_b64_e32 v[136:137], v[242:243]
	v_mov_b64_e32 v[138:139], v[244:245]
	v_mov_b32_e32 v148, v246
	v_lshlrev_b32_e32 v182, 16, v136
	v_pk_mul_f32 v[184:185], v[52:53], v[148:149] op_sel_hi:[1,0]
	v_and_b32_e32 v183, 0xffff0000, v136
	v_mul_f32_e32 v136, 0xbfb8aa3b, v184
	v_exp_f32_e32 v200, v136
	v_mul_f32_e32 v136, 0xbfb8aa3b, v185
	v_exp_f32_e32 v201, v136
	v_pk_mul_f32 v[182:183], v[142:143], v[182:183] op_sel_hi:[0,1]
	v_pk_mul_f32 v[182:183], v[132:133], v[182:183]
	s_nop 0
	v_pk_mul_f32 v[182:183], v[184:185], v[182:183]
	v_pk_add_f32 v[184:185], v[200:201], 1.0 op_sel_hi:[1,0]
	s_nop 0
	v_div_scale_f32 v136, s[26:27], v185, v185, 1.0
	v_rcp_f32_e32 v143, v136
	s_nop 0
	v_fma_f32 v165, -v136, v143, 1.0
	v_fmac_f32_e32 v143, v165, v143
	v_div_scale_f32 v165, vcc, 1.0, v185, 1.0
	v_mul_f32_e32 v167, v165, v143
	v_fma_f32 v200, -v136, v167, v165
	v_fmac_f32_e32 v167, v200, v143
	v_fma_f32 v136, -v136, v167, v165
	v_div_fmas_f32 v136, v136, v143, v167
	v_div_fixup_f32 v185, v136, v185, 1.0
	v_div_scale_f32 v136, s[26:27], v184, v184, 1.0
	v_rcp_f32_e32 v143, v136
	s_nop 0
	v_fma_f32 v165, -v136, v143, 1.0
	v_fmac_f32_e32 v143, v165, v143
	v_div_scale_f32 v165, vcc, 1.0, v184, 1.0
	v_mul_f32_e32 v167, v165, v143
	v_fma_f32 v200, -v136, v167, v165
	v_fmac_f32_e32 v167, v200, v143
	v_fma_f32 v136, -v136, v167, v165
	v_div_fmas_f32 v136, v136, v143, v167
	v_pk_mul_f32 v[200:201], v[48:49], v[148:149] op_sel_hi:[1,0]
	v_div_fixup_f32 v184, v136, v184, 1.0
	v_mul_f32_e32 v136, 0xbfb8aa3b, v200
	v_exp_f32_e32 v202, v136
	v_mul_f32_e32 v136, 0xbfb8aa3b, v201
	v_exp_f32_e32 v203, v136
	v_pk_mul_f32 v[182:183], v[184:185], v[182:183]
	v_lshlrev_b32_e32 v184, 16, v138
	v_and_b32_e32 v185, 0xffff0000, v138
	v_pk_mul_f32 v[184:185], v[142:143], v[184:185] op_sel_hi:[0,1]
	v_pk_mul_f32 v[184:185], v[128:129], v[184:185]
	s_nop 0
	v_pk_mul_f32 v[184:185], v[200:201], v[184:185]
	v_pk_add_f32 v[200:201], v[202:203], 1.0 op_sel_hi:[1,0]
	s_nop 0
	v_div_scale_f32 v136, s[26:27], v201, v201, 1.0
	v_rcp_f32_e32 v138, v136
	s_nop 0
	v_fma_f32 v143, -v136, v138, 1.0
	v_fmac_f32_e32 v138, v143, v138
	v_div_scale_f32 v143, vcc, 1.0, v201, 1.0
	v_mul_f32_e32 v165, v143, v138
	v_fma_f32 v167, -v136, v165, v143
	v_fmac_f32_e32 v165, v167, v138
	v_fma_f32 v136, -v136, v165, v143
	v_div_fmas_f32 v136, v136, v138, v165
	v_div_fixup_f32 v201, v136, v201, 1.0
	v_div_scale_f32 v136, s[26:27], v200, v200, 1.0
	v_rcp_f32_e32 v138, v136
	s_nop 0
	v_fma_f32 v143, -v136, v138, 1.0
	v_fmac_f32_e32 v138, v143, v138
	v_div_scale_f32 v143, vcc, 1.0, v200, 1.0
	v_mul_f32_e32 v165, v143, v138
	v_fma_f32 v167, -v136, v165, v143
	v_fmac_f32_e32 v165, v167, v138
	v_fma_f32 v136, -v136, v165, v143
	v_div_fmas_f32 v136, v136, v138, v165
	v_div_fixup_f32 v200, v136, v200, 1.0
	v_pk_mul_f32 v[184:185], v[200:201], v[184:185]
	v_pk_mul_f32 v[200:201], v[54:55], v[148:149] op_sel_hi:[1,0]
	v_lshlrev_b32_e32 v136, 16, v137
	v_mul_f32_e32 v138, 0xbfb8aa3b, v200
	v_exp_f32_e32 v202, v138
	v_mul_f32_e32 v138, 0xbfb8aa3b, v201
	v_exp_f32_e32 v203, v138
; DI unsigned pk(float lo, float hi) { f32x2 v = {lo, hi}; bf2_t b = __builtin_convertvector(v, bf2_t); return __builtin_bit_cast(unsigned, b); }
; DI float bflo(unsigned w) { return __uint_as_float(w << 16); }
; DI float bfhi(unsigned w) { return __uint_as_float(w & 0xffff0000u); }
; DI float sigmoidf_(float x) { return 1.0f / (1.0f + __expf(-x)); }
; DI void gemm_epilogue(const GemmDesc& g, f32x4 (&acc)[2][2][4][2], int brow, int bcol, int wr, int wc, int fr, int fq) {
;     ...
;           const int row = rowb + ai * HALF + m * 16;
;           float rs;
;           { const float* sp = g.f0 + (size_t)row * 32 + head * 8;
;             const f32x4 s0 = gld<f32x4>(sp); float ssum = (s0[0] + s0[1]) + (s0[2] + s0[3]);
;             if (g.dvshift == 9) { const f32x4 s1 = gld<f32x4>(sp + 4); ssum += (s1[0] + s1[1]) + (s1[2] + s1[3]); }
;             rs = rsqrtf(ssum * (g.dvshift == 9 ? (1.0f / 512.0f) : (1.0f / 256.0f)) + EPS); }
;           bf16_t* op = g.o0 + (size_t)row * N + col;
;           const u32x4 ow = gld<u32x4>(op);
;           const float ru = gld<float>(g.rowscale + row);
;           const f32x4 v0 = acc[ai][bj][m][0] * ru, v1 = acc[ai][bj][m][1] * ru;
;           float o[8] = {bflo(ow.x), bfhi(ow.x), bflo(ow.y), bfhi(ow.y), bflo(ow.z), bfhi(ow.z), bflo(ow.w), bfhi(ow.w)};
; #pragma unroll
;           for (int j = 0; j < 4; ++j) { o[j] = o[j] * rs * g0[j] * v0[j] * sigmoidf_(v0[j]); o[4 + j] = o[4 + j] * rs * g1[j] * v1[j] * sigmoidf_(v1[j]); }
;           u32x4 w; w.x = pk(o[0], o[1]); w.y = pk(o[2], o[3]); w.z = pk(o[4], o[5]); w.w = pk(o[6], o[7]);
;           gst<u32x4>(op, w);
;         }
	v_and_b32_e32 v137, 0xffff0000, v137
	v_pk_mul_f32 v[136:137], v[142:143], v[136:137] op_sel_hi:[0,1]
	v_pk_mul_f32 v[136:137], v[134:135], v[136:137]
	s_nop 0
	v_pk_mul_f32 v[136:137], v[200:201], v[136:137]
	v_pk_add_f32 v[200:201], v[202:203], 1.0 op_sel_hi:[1,0]
	s_nop 0
	v_div_scale_f32 v138, s[26:27], v201, v201, 1.0
	v_rcp_f32_e32 v143, v138
	s_nop 0
	v_fma_f32 v165, -v138, v143, 1.0
	v_fmac_f32_e32 v143, v165, v143
	v_div_scale_f32 v165, vcc, 1.0, v201, 1.0
	v_mul_f32_e32 v167, v165, v143
	v_fma_f32 v202, -v138, v167, v165
	v_fmac_f32_e32 v167, v202, v143
	v_fma_f32 v138, -v138, v167, v165
	v_div_fmas_f32 v138, v138, v143, v167
	v_div_fixup_f32 v201, v138, v201, 1.0
	v_div_scale_f32 v138, s[26:27], v200, v200, 1.0
	v_rcp_f32_e32 v143, v138
	s_nop 0
	v_fma_f32 v165, -v138, v143, 1.0
	v_fmac_f32_e32 v143, v165, v143
	v_div_scale_f32 v165, vcc, 1.0, v200, 1.0
	v_mul_f32_e32 v167, v165, v143
	v_fma_f32 v202, -v138, v167, v165
	v_fmac_f32_e32 v167, v202, v143
	v_fma_f32 v138, -v138, v167, v165
	v_div_fmas_f32 v138, v138, v143, v167
	v_div_fixup_f32 v200, v138, v200, 1.0
	v_pk_mul_f32 v[200:201], v[200:201], v[136:137]
	v_lshlrev_b32_e32 v136, 16, v139
	v_and_b32_e32 v137, 0xffff0000, v139
	v_pk_mul_f32 v[138:139], v[50:51], v[148:149] op_sel_hi:[1,0]
	s_nop 0
	v_mul_f32_e32 v143, 0xbfb8aa3b, v138
	v_pk_mul_f32 v[136:137], v[142:143], v[136:137] op_sel_hi:[0,1]
	v_pk_mul_f32 v[136:137], v[130:131], v[136:137]
	v_exp_f32_e32 v202, v143
	v_pk_mul_f32 v[136:137], v[138:139], v[136:137]
	v_mul_f32_e32 v138, 0xbfb8aa3b, v139
	v_exp_f32_e32 v203, v138
	s_nop 0
	v_pk_add_f32 v[138:139], v[202:203], 1.0 op_sel_hi:[1,0]
	s_nop 0
	v_div_scale_f32 v142, s[26:27], v139, v139, 1.0
	v_rcp_f32_e32 v143, v142
	s_nop 0
	v_fma_f32 v148, -v142, v143, 1.0
	v_fmac_f32_e32 v143, v148, v143
	v_div_scale_f32 v148, vcc, 1.0, v139, 1.0
	v_mul_f32_e32 v165, v148, v143
	v_fma_f32 v167, -v142, v165, v148
	v_fmac_f32_e32 v165, v167, v143
	v_fma_f32 v142, -v142, v165, v148
	v_div_fmas_f32 v142, v142, v143, v165
	v_div_fixup_f32 v139, v142, v139, 1.0
	v_div_scale_f32 v142, s[26:27], v138, v138, 1.0
	v_rcp_f32_e32 v143, v142
	s_mov_b32 s26, 0x3b800000
	s_mov_b32 s27, 0x3b800000
	v_fma_f32 v148, -v142, v143, 1.0
	v_fmac_f32_e32 v143, v148, v143
	v_div_scale_f32 v148, vcc, 1.0, v138, 1.0
	v_mul_f32_e32 v165, v148, v143
	v_fma_f32 v167, -v142, v165, v148
	v_fmac_f32_e32 v165, v167, v143
	v_fma_f32 v142, -v142, v165, v148
	v_div_fmas_f32 v142, v142, v143, v165
	v_div_fixup_f32 v138, v142, v138, 1.0
	v_pk_mul_f32 v[142:143], v[138:139], v[136:137]
	v_cvt_pk_bf16_f32 v136, v182, v183
	v_cvt_pk_bf16_f32 v137, v200, v201
	v_cvt_pk_bf16_f32 v138, v184, v185
	v_cvt_pk_bf16_f32 v139, v142, v143
	global_store_dwordx4 v[168:169], v[136:139], off offset:256
	s_and_b64 vcc, exec, s[44:45]
	s_nop 0
	v_lshl_add_u64 v[138:139], v[198:199], 2, v[186:187]
	global_load_dwordx4 v[182:185], v[138:139], off
	global_load_dwordx4 v[232:235], v[138:139], off offset:16
	global_load_dwordx4 v[242:245], v[170:171], off offset:256
	global_load_dword v246, v[140:141], off offset:128
	s_waitcnt vmcnt(0)
	v_mov_b32_e32 v136, v183
	v_mov_b32_e32 v137, v184
	v_mov_b32_e32 v183, v185
	v_pk_add_f32 v[136:137], v[136:137], v[182:183]
	s_nop 0
	v_pk_add_f32 v[136:137], v[136:137], v[136:137] op_sel:[0,1] op_sel_hi:[1,0]
	s_cbranch_vccnz .LBB0_244
	v_mov_b64_e32 v[182:183], v[232:233]
	v_mov_b64_e32 v[184:185], v[234:235]
	s_mov_b32 s27, 0x3b000000
	v_mov_b32_e32 v138, v183
	v_mov_b32_e32 v139, v184
	v_mov_b32_e32 v183, v185
	v_pk_add_f32 v[138:139], v[138:139], v[182:183]
	s_nop 0
	v_add_f32_e32 v137, v138, v139
	v_add_f32_e32 v136, v136, v137
.LBB0_244:
	v_fma_f32 v136, s27, v136, v204
	v_cmp_gt_f32_e32 vcc, s33, v136
	v_mul_f32_e32 v137, 0x4b800000, v136
	s_nop 0
	v_cndmask_b32_e32 v136, v136, v137, vcc
	v_rsq_f32_e32 v136, v136
	s_nop 0
	v_mul_f32_e32 v137, 0x45800000, v136
	v_cndmask_b32_e32 v142, v136, v137, vcc
	v_mov_b64_e32 v[136:137], v[242:243]
	v_mov_b64_e32 v[138:139], v[244:245]
	v_mov_b32_e32 v148, v246
	v_lshlrev_b32_e32 v168, 16, v136
	v_pk_mul_f32 v[182:183], v[44:45], v[148:149] op_sel_hi:[1,0]
	v_and_b32_e32 v169, 0xffff0000, v136
	v_mul_f32_e32 v136, 0xbfb8aa3b, v182
	v_exp_f32_e32 v184, v136
	v_mul_f32_e32 v136, 0xbfb8aa3b, v183
	v_exp_f32_e32 v185, v136
	v_pk_mul_f32 v[168:169], v[142:143], v[168:169] op_sel_hi:[0,1]
	v_pk_mul_f32 v[168:169], v[132:133], v[168:169]
	s_nop 0
	v_pk_mul_f32 v[168:169], v[182:183], v[168:169]
	v_pk_add_f32 v[182:183], v[184:185], 1.0 op_sel_hi:[1,0]
	s_nop 0
	v_div_scale_f32 v136, s[46:47], v183, v183, 1.0
	v_rcp_f32_e32 v143, v136
	s_nop 0
	v_fma_f32 v165, -v136, v143, 1.0
	v_fmac_f32_e32 v143, v165, v143
	v_div_scale_f32 v165, vcc, 1.0, v183, 1.0
	v_mul_f32_e32 v167, v165, v143
	v_fma_f32 v184, -v136, v167, v165
	v_fmac_f32_e32 v167, v184, v143
	v_fma_f32 v136, -v136, v167, v165
	v_div_fmas_f32 v136, v136, v143, v167
	v_div_fixup_f32 v183, v136, v183, 1.0
	v_div_scale_f32 v136, s[46:47], v182, v182, 1.0
	v_rcp_f32_e32 v143, v136
	s_nop 0
	v_fma_f32 v165, -v136, v143, 1.0
	v_fmac_f32_e32 v143, v165, v143
	v_div_scale_f32 v165, vcc, 1.0, v182, 1.0
	v_mul_f32_e32 v167, v165, v143
	v_fma_f32 v184, -v136, v167, v165
	v_fmac_f32_e32 v167, v184, v143
	v_fma_f32 v136, -v136, v167, v165
	v_div_fmas_f32 v136, v136, v143, v167
	v_pk_mul_f32 v[184:185], v[40:41], v[148:149] op_sel_hi:[1,0]
	v_div_fixup_f32 v182, v136, v182, 1.0
	v_mul_f32_e32 v136, 0xbfb8aa3b, v184
	v_exp_f32_e32 v186, v136
	v_mul_f32_e32 v136, 0xbfb8aa3b, v185
	v_exp_f32_e32 v187, v136
	v_pk_mul_f32 v[168:169], v[182:183], v[168:169]
	v_lshlrev_b32_e32 v182, 16, v138
	v_and_b32_e32 v183, 0xffff0000, v138
; DI unsigned pk(float lo, float hi) { f32x2 v = {lo, hi}; bf2_t b = __builtin_convertvector(v, bf2_t); return __builtin_bit_cast(unsigned, b); }
; DI float bflo(unsigned w) { return __uint_as_float(w << 16); }
; DI float bfhi(unsigned w) { return __uint_as_float(w & 0xffff0000u); }
; DI float sigmoidf_(float x) { return 1.0f / (1.0f + __expf(-x)); }
; DI void gemm_epilogue(const GemmDesc& g, f32x4 (&acc)[2][2][4][2], int brow, int bcol, int wr, int wc, int fr, int fq) {
;     ...
;           const int row = rowb + ai * HALF + m * 16;
;           float rs;
;           { const float* sp = g.f0 + (size_t)row * 32 + head * 8;
;             const f32x4 s0 = gld<f32x4>(sp); float ssum = (s0[0] + s0[1]) + (s0[2] + s0[3]);
;             if (g.dvshift == 9) { const f32x4 s1 = gld<f32x4>(sp + 4); ssum += (s1[0] + s1[1]) + (s1[2] + s1[3]); }
;             rs = rsqrtf(ssum * (g.dvshift == 9 ? (1.0f / 512.0f) : (1.0f / 256.0f)) + EPS); }
;           bf16_t* op = g.o0 + (size_t)row * N + col;
;           const u32x4 ow = gld<u32x4>(op);
;           const float ru = gld<float>(g.rowscale + row);
;           const f32x4 v0 = acc[ai][bj][m][0] * ru, v1 = acc[ai][bj][m][1] * ru;
;           float o[8] = {bflo(ow.x), bfhi(ow.x), bflo(ow.y), bfhi(ow.y), bflo(ow.z), bfhi(ow.z), bflo(ow.w), bfhi(ow.w)};
; #pragma unroll
;           for (int j = 0; j < 4; ++j) { o[j] = o[j] * rs * g0[j] * v0[j] * sigmoidf_(v0[j]); o[4 + j] = o[4 + j] * rs * g1[j] * v1[j] * sigmoidf_(v1[j]); }
;           u32x4 w; w.x = pk(o[0], o[1]); w.y = pk(o[2], o[3]); w.z = pk(o[4], o[5]); w.w = pk(o[6], o[7]);
;           gst<u32x4>(op, w);
;         }
	v_pk_mul_f32 v[182:183], v[142:143], v[182:183] op_sel_hi:[0,1]
	v_pk_mul_f32 v[182:183], v[128:129], v[182:183]
	s_nop 0
	v_pk_mul_f32 v[182:183], v[184:185], v[182:183]
	v_pk_add_f32 v[184:185], v[186:187], 1.0 op_sel_hi:[1,0]
	s_nop 0
	v_div_scale_f32 v136, s[46:47], v185, v185, 1.0
	v_rcp_f32_e32 v138, v136
	s_nop 0
	v_fma_f32 v143, -v136, v138, 1.0
	v_fmac_f32_e32 v138, v143, v138
	v_div_scale_f32 v143, vcc, 1.0, v185, 1.0
	v_mul_f32_e32 v165, v143, v138
	v_fma_f32 v167, -v136, v165, v143
	v_fmac_f32_e32 v165, v167, v138
	v_fma_f32 v136, -v136, v165, v143
	v_div_fmas_f32 v136, v136, v138, v165
	v_div_fixup_f32 v185, v136, v185, 1.0
	v_div_scale_f32 v136, s[46:47], v184, v184, 1.0
	v_rcp_f32_e32 v138, v136
	s_nop 0
	v_fma_f32 v143, -v136, v138, 1.0
	v_fmac_f32_e32 v138, v143, v138
	v_div_scale_f32 v143, vcc, 1.0, v184, 1.0
	v_mul_f32_e32 v165, v143, v138
	v_fma_f32 v167, -v136, v165, v143
	v_fmac_f32_e32 v165, v167, v138
	v_fma_f32 v136, -v136, v165, v143
	v_div_fmas_f32 v136, v136, v138, v165
	v_div_fixup_f32 v184, v136, v184, 1.0
	v_pk_mul_f32 v[182:183], v[184:185], v[182:183]
	v_pk_mul_f32 v[184:185], v[46:47], v[148:149] op_sel_hi:[1,0]
	v_lshlrev_b32_e32 v136, 16, v137
	v_mul_f32_e32 v138, 0xbfb8aa3b, v184
	v_exp_f32_e32 v186, v138
	v_mul_f32_e32 v138, 0xbfb8aa3b, v185
	v_exp_f32_e32 v187, v138
	v_and_b32_e32 v137, 0xffff0000, v137
	v_pk_mul_f32 v[136:137], v[142:143], v[136:137] op_sel_hi:[0,1]
	v_pk_mul_f32 v[136:137], v[134:135], v[136:137]
	s_nop 0
	v_pk_mul_f32 v[136:137], v[184:185], v[136:137]
	v_pk_add_f32 v[184:185], v[186:187], 1.0 op_sel_hi:[1,0]
	s_nop 0
	v_div_scale_f32 v138, s[46:47], v185, v185, 1.0
	v_rcp_f32_e32 v143, v138
	s_nop 0
	v_fma_f32 v165, -v138, v143, 1.0
	v_fmac_f32_e32 v143, v165, v143
	v_div_scale_f32 v165, vcc, 1.0, v185, 1.0
	v_mul_f32_e32 v167, v165, v143
	v_fma_f32 v186, -v138, v167, v165
	v_fmac_f32_e32 v167, v186, v143
	v_fma_f32 v138, -v138, v167, v165
	v_div_fmas_f32 v138, v138, v143, v167
	v_div_fixup_f32 v185, v138, v185, 1.0
	v_div_scale_f32 v138, s[46:47], v184, v184, 1.0
	v_rcp_f32_e32 v143, v138
	s_nop 0
	v_fma_f32 v165, -v138, v143, 1.0
	v_fmac_f32_e32 v143, v165, v143
	v_div_scale_f32 v165, vcc, 1.0, v184, 1.0
	v_mul_f32_e32 v167, v165, v143
	v_fma_f32 v186, -v138, v167, v165
	v_fmac_f32_e32 v167, v186, v143
	v_fma_f32 v138, -v138, v167, v165
	v_div_fmas_f32 v138, v138, v143, v167
	v_div_fixup_f32 v184, v138, v184, 1.0
	v_pk_mul_f32 v[184:185], v[184:185], v[136:137]
	v_lshlrev_b32_e32 v136, 16, v139
	v_and_b32_e32 v137, 0xffff0000, v139
	v_pk_mul_f32 v[138:139], v[42:43], v[148:149] op_sel_hi:[1,0]
	s_nop 0
	v_mul_f32_e32 v143, 0xbfb8aa3b, v138
	v_pk_mul_f32 v[136:137], v[142:143], v[136:137] op_sel_hi:[0,1]
	v_pk_mul_f32 v[136:137], v[130:131], v[136:137]
	v_exp_f32_e32 v186, v143
	v_pk_mul_f32 v[136:137], v[138:139], v[136:137]
	v_mul_f32_e32 v138, 0xbfb8aa3b, v139
	v_exp_f32_e32 v187, v138
	s_nop 0
	v_pk_add_f32 v[138:139], v[186:187], 1.0 op_sel_hi:[1,0]
	s_nop 0
	v_div_scale_f32 v142, s[46:47], v139, v139, 1.0
	v_rcp_f32_e32 v143, v142
	s_nop 0
	v_fma_f32 v148, -v142, v143, 1.0
	v_fmac_f32_e32 v143, v148, v143
	v_div_scale_f32 v148, vcc, 1.0, v139, 1.0
	v_mul_f32_e32 v165, v148, v143
	v_fma_f32 v167, -v142, v165, v148
	v_fmac_f32_e32 v165, v167, v143
	v_fma_f32 v142, -v142, v165, v148
	v_div_fmas_f32 v142, v142, v143, v165
	v_div_fixup_f32 v139, v142, v139, 1.0
	v_div_scale_f32 v142, s[46:47], v138, v138, 1.0
	v_rcp_f32_e32 v143, v142
	s_nop 0
	v_fma_f32 v148, -v142, v143, 1.0
	v_fmac_f32_e32 v143, v148, v143
	v_div_scale_f32 v148, vcc, 1.0, v138, 1.0
	v_mul_f32_e32 v165, v148, v143
	v_fma_f32 v167, -v142, v165, v148
	v_fmac_f32_e32 v165, v167, v143
	v_fma_f32 v142, -v142, v165, v148
	v_div_fmas_f32 v142, v142, v143, v165
	v_div_fixup_f32 v138, v142, v138, 1.0
	v_pk_mul_f32 v[142:143], v[138:139], v[136:137]
	v_cvt_pk_bf16_f32 v136, v168, v169
	v_cvt_pk_bf16_f32 v137, v184, v185
	v_cvt_pk_bf16_f32 v138, v182, v183
	v_cvt_pk_bf16_f32 v139, v142, v143
	global_store_dwordx4 v[170:171], v[136:139], off offset:256
	s_and_b64 vcc, exec, s[44:45]
	s_nop 0
	v_lshl_add_u64 v[138:139], v[198:199], 2, v[188:189]
	global_load_dwordx4 v[168:171], v[138:139], off
	global_load_dwordx4 v[232:235], v[138:139], off offset:16
	global_load_dwordx4 v[242:245], v[172:173], off offset:256
	global_load_dword v246, v[140:141], off offset:192
	s_waitcnt vmcnt(0)
	v_mov_b32_e32 v136, v169
	v_mov_b32_e32 v137, v170
	v_mov_b32_e32 v169, v171
	v_pk_add_f32 v[136:137], v[136:137], v[168:169]
	s_nop 0
	v_pk_add_f32 v[136:137], v[136:137], v[136:137] op_sel:[0,1] op_sel_hi:[1,0]
	s_cbranch_vccnz .LBB0_246
	v_mov_b64_e32 v[168:169], v[232:233]
	v_mov_b64_e32 v[170:171], v[234:235]
	s_mov_b32 s26, 0x3b000000
	v_mov_b32_e32 v138, v169
	v_mov_b32_e32 v139, v170
	v_mov_b32_e32 v169, v171
	v_pk_add_f32 v[138:139], v[138:139], v[168:169]
	s_nop 0
	v_add_f32_e32 v137, v138, v139
	v_add_f32_e32 v136, v136, v137
; DI unsigned pk(float lo, float hi) { f32x2 v = {lo, hi}; bf2_t b = __builtin_convertvector(v, bf2_t); return __builtin_bit_cast(unsigned, b); }
; DI float bflo(unsigned w) { return __uint_as_float(w << 16); }
; DI float bfhi(unsigned w) { return __uint_as_float(w & 0xffff0000u); }
; DI float sigmoidf_(float x) { return 1.0f / (1.0f + __expf(-x)); }
; DI void gemm_epilogue(const GemmDesc& g, f32x4 (&acc)[2][2][4][2], int brow, int bcol, int wr, int wc, int fr, int fq) {
;     ...
;           const int row = rowb + ai * HALF + m * 16;
;           float rs;
;           { const float* sp = g.f0 + (size_t)row * 32 + head * 8;
;             const f32x4 s0 = gld<f32x4>(sp); float ssum = (s0[0] + s0[1]) + (s0[2] + s0[3]);
;             if (g.dvshift == 9) { const f32x4 s1 = gld<f32x4>(sp + 4); ssum += (s1[0] + s1[1]) + (s1[2] + s1[3]); }
;             rs = rsqrtf(ssum * (g.dvshift == 9 ? (1.0f / 512.0f) : (1.0f / 256.0f)) + EPS); }
;           bf16_t* op = g.o0 + (size_t)row * N + col;
;           const u32x4 ow = gld<u32x4>(op);
;           const float ru = gld<float>(g.rowscale + row);
;           const f32x4 v0 = acc[ai][bj][m][0] * ru, v1 = acc[ai][bj][m][1] * ru;
;           float o[8] = {bflo(ow.x), bfhi(ow.x), bflo(ow.y), bfhi(ow.y), bflo(ow.z), bfhi(ow.z), bflo(ow.w), bfhi(ow.w)};
; #pragma unroll
;           for (int j = 0; j < 4; ++j) { o[j] = o[j] * rs * g0[j] * v0[j] * sigmoidf_(v0[j]); o[4 + j] = o[4 + j] * rs * g1[j] * v1[j] * sigmoidf_(v1[j]); }
;           u32x4 w; w.x = pk(o[0], o[1]); w.y = pk(o[2], o[3]); w.z = pk(o[4], o[5]); w.w = pk(o[6], o[7]);
;           gst<u32x4>(op, w);
;         }
.LBB0_246:
	v_fma_f32 v136, s26, v136, v204
	v_cmp_gt_f32_e32 vcc, s33, v136
	v_mul_f32_e32 v137, 0x4b800000, v136
	s_nop 0
	v_cndmask_b32_e32 v136, v136, v137, vcc
	v_rsq_f32_e32 v136, v136
	s_nop 0
	v_mul_f32_e32 v137, 0x45800000, v136
	v_cndmask_b32_e32 v142, v136, v137, vcc
	v_mov_b64_e32 v[136:137], v[242:243]
	v_mov_b64_e32 v[138:139], v[244:245]
	v_mov_b32_e32 v148, v246
	v_lshlrev_b32_e32 v168, 16, v136
	v_pk_mul_f32 v[170:171], v[36:37], v[148:149] op_sel_hi:[1,0]
	v_and_b32_e32 v169, 0xffff0000, v136
	v_mul_f32_e32 v136, 0xbfb8aa3b, v170
	v_exp_f32_e32 v182, v136
	v_mul_f32_e32 v136, 0xbfb8aa3b, v171
	v_exp_f32_e32 v183, v136
	v_pk_mul_f32 v[168:169], v[142:143], v[168:169] op_sel_hi:[0,1]
	v_pk_mul_f32 v[168:169], v[132:133], v[168:169]
	s_nop 0
	v_pk_mul_f32 v[168:169], v[170:171], v[168:169]
	v_pk_add_f32 v[170:171], v[182:183], 1.0 op_sel_hi:[1,0]
	s_nop 0
	v_div_scale_f32 v136, s[26:27], v171, v171, 1.0
	v_rcp_f32_e32 v143, v136
	s_nop 0
	v_fma_f32 v165, -v136, v143, 1.0
	v_fmac_f32_e32 v143, v165, v143
	v_div_scale_f32 v165, vcc, 1.0, v171, 1.0
	v_mul_f32_e32 v167, v165, v143
	v_fma_f32 v182, -v136, v167, v165
	v_fmac_f32_e32 v167, v182, v143
	v_fma_f32 v136, -v136, v167, v165
	v_div_fmas_f32 v136, v136, v143, v167
	v_div_fixup_f32 v171, v136, v171, 1.0
	v_div_scale_f32 v136, s[26:27], v170, v170, 1.0
	v_rcp_f32_e32 v143, v136
	s_nop 0
	v_fma_f32 v165, -v136, v143, 1.0
	v_fmac_f32_e32 v143, v165, v143
	v_div_scale_f32 v165, vcc, 1.0, v170, 1.0
	v_mul_f32_e32 v167, v165, v143
	v_fma_f32 v182, -v136, v167, v165
	v_fmac_f32_e32 v167, v182, v143
	v_fma_f32 v136, -v136, v167, v165
	v_div_fmas_f32 v136, v136, v143, v167
	v_pk_mul_f32 v[182:183], v[32:33], v[148:149] op_sel_hi:[1,0]
	v_div_fixup_f32 v170, v136, v170, 1.0
	v_mul_f32_e32 v136, 0xbfb8aa3b, v182
	v_exp_f32_e32 v184, v136
	v_mul_f32_e32 v136, 0xbfb8aa3b, v183
	v_exp_f32_e32 v185, v136
	v_pk_mul_f32 v[168:169], v[170:171], v[168:169]
	v_lshlrev_b32_e32 v170, 16, v138
	v_and_b32_e32 v171, 0xffff0000, v138
	v_pk_mul_f32 v[170:171], v[142:143], v[170:171] op_sel_hi:[0,1]
	v_pk_mul_f32 v[170:171], v[128:129], v[170:171]
	s_nop 0
	v_pk_mul_f32 v[170:171], v[182:183], v[170:171]
	v_pk_add_f32 v[182:183], v[184:185], 1.0 op_sel_hi:[1,0]
	s_nop 0
	v_div_scale_f32 v136, s[26:27], v183, v183, 1.0
	v_rcp_f32_e32 v138, v136
	s_nop 0
	v_fma_f32 v143, -v136, v138, 1.0
	v_fmac_f32_e32 v138, v143, v138
	v_div_scale_f32 v143, vcc, 1.0, v183, 1.0
	v_mul_f32_e32 v165, v143, v138
	v_fma_f32 v167, -v136, v165, v143
	v_fmac_f32_e32 v165, v167, v138
	v_fma_f32 v136, -v136, v165, v143
	v_div_fmas_f32 v136, v136, v138, v165
	v_div_fixup_f32 v183, v136, v183, 1.0
	v_div_scale_f32 v136, s[26:27], v182, v182, 1.0
	v_rcp_f32_e32 v138, v136
	s_nop 0
	v_fma_f32 v143, -v136, v138, 1.0
	v_fmac_f32_e32 v138, v143, v138
	v_div_scale_f32 v143, vcc, 1.0, v182, 1.0
	v_mul_f32_e32 v165, v143, v138
	v_fma_f32 v167, -v136, v165, v143
	v_fmac_f32_e32 v165, v167, v138
	v_fma_f32 v136, -v136, v165, v143
	v_div_fmas_f32 v136, v136, v138, v165
	v_div_fixup_f32 v182, v136, v182, 1.0
	v_pk_mul_f32 v[170:171], v[182:183], v[170:171]
	v_pk_mul_f32 v[182:183], v[38:39], v[148:149] op_sel_hi:[1,0]
	v_lshlrev_b32_e32 v136, 16, v137
	v_mul_f32_e32 v138, 0xbfb8aa3b, v182
	v_exp_f32_e32 v184, v138
	v_mul_f32_e32 v138, 0xbfb8aa3b, v183
	v_exp_f32_e32 v185, v138
	v_and_b32_e32 v137, 0xffff0000, v137
	v_pk_mul_f32 v[136:137], v[142:143], v[136:137] op_sel_hi:[0,1]
	v_pk_mul_f32 v[136:137], v[134:135], v[136:137]
	s_nop 0
	v_pk_mul_f32 v[136:137], v[182:183], v[136:137]
	v_pk_add_f32 v[182:183], v[184:185], 1.0 op_sel_hi:[1,0]
	s_nop 0
	v_div_scale_f32 v138, s[26:27], v183, v183, 1.0
	v_rcp_f32_e32 v143, v138
	s_nop 0
	v_fma_f32 v165, -v138, v143, 1.0
	v_fmac_f32_e32 v143, v165, v143
	v_div_scale_f32 v165, vcc, 1.0, v183, 1.0
	v_mul_f32_e32 v167, v165, v143
	v_fma_f32 v184, -v138, v167, v165
	v_fmac_f32_e32 v167, v184, v143
	v_fma_f32 v138, -v138, v167, v165
	v_div_fmas_f32 v138, v138, v143, v167
	v_div_fixup_f32 v183, v138, v183, 1.0
	v_div_scale_f32 v138, s[26:27], v182, v182, 1.0
	v_rcp_f32_e32 v143, v138
	s_nop 0
	v_fma_f32 v165, -v138, v143, 1.0
	v_fmac_f32_e32 v143, v165, v143
	v_div_scale_f32 v165, vcc, 1.0, v182, 1.0
	v_mul_f32_e32 v167, v165, v143
	v_fma_f32 v184, -v138, v167, v165
	v_fmac_f32_e32 v167, v184, v143
	v_fma_f32 v138, -v138, v167, v165
	v_div_fmas_f32 v138, v138, v143, v167
	v_div_fixup_f32 v182, v138, v182, 1.0
	v_pk_mul_f32 v[182:183], v[182:183], v[136:137]
	v_lshlrev_b32_e32 v136, 16, v139
	v_and_b32_e32 v137, 0xffff0000, v139
	v_pk_mul_f32 v[138:139], v[34:35], v[148:149] op_sel_hi:[1,0]
	s_nop 0
	v_mul_f32_e32 v143, 0xbfb8aa3b, v138
	v_pk_mul_f32 v[136:137], v[142:143], v[136:137] op_sel_hi:[0,1]
	v_pk_mul_f32 v[136:137], v[130:131], v[136:137]
	v_exp_f32_e32 v184, v143
	v_pk_mul_f32 v[136:137], v[138:139], v[136:137]
	v_mul_f32_e32 v138, 0xbfb8aa3b, v139
	v_exp_f32_e32 v185, v138
	s_nop 0
	v_pk_add_f32 v[138:139], v[184:185], 1.0 op_sel_hi:[1,0]
	s_nop 0
	v_div_scale_f32 v142, s[26:27], v139, v139, 1.0
	v_rcp_f32_e32 v143, v142
	s_nop 0
	v_fma_f32 v148, -v142, v143, 1.0
	v_fmac_f32_e32 v143, v148, v143
	v_div_scale_f32 v148, vcc, 1.0, v139, 1.0
	v_mul_f32_e32 v165, v148, v143
	v_fma_f32 v167, -v142, v165, v148
	v_fmac_f32_e32 v165, v167, v143
	v_fma_f32 v142, -v142, v165, v148
	v_div_fmas_f32 v142, v142, v143, v165
	v_div_fixup_f32 v139, v142, v139, 1.0
	v_div_scale_f32 v142, s[26:27], v138, v138, 1.0
	v_rcp_f32_e32 v143, v142
	s_mov_b32 s26, 0x3b800000
	s_mov_b32 s27, 0x3b800000
	v_fma_f32 v148, -v142, v143, 1.0
	v_fmac_f32_e32 v143, v148, v143
	v_div_scale_f32 v148, vcc, 1.0, v138, 1.0
	v_mul_f32_e32 v165, v148, v143
	v_fma_f32 v167, -v142, v165, v148
	v_fmac_f32_e32 v165, v167, v143
	v_fma_f32 v142, -v142, v165, v148
	v_div_fmas_f32 v142, v142, v143, v165
	v_div_fixup_f32 v138, v142, v138, 1.0
	v_pk_mul_f32 v[142:143], v[138:139], v[136:137]
	v_cvt_pk_bf16_f32 v136, v168, v169
	v_cvt_pk_bf16_f32 v137, v182, v183
	v_cvt_pk_bf16_f32 v138, v170, v171
	v_cvt_pk_bf16_f32 v139, v142, v143
	global_store_dwordx4 v[172:173], v[136:139], off offset:256
	s_and_b64 vcc, exec, s[44:45]
	s_nop 0
	v_lshl_add_u64 v[138:139], v[198:199], 2, v[190:191]
	global_load_dwordx4 v[168:171], v[138:139], off
	global_load_dwordx4 v[232:235], v[138:139], off offset:16
	global_load_dwordx4 v[242:245], v[174:175], off offset:256
	global_load_dword v246, v[140:141], off offset:512
	s_waitcnt vmcnt(0)
	v_mov_b32_e32 v136, v169
	v_mov_b32_e32 v137, v170
	v_mov_b32_e32 v169, v171
	v_pk_add_f32 v[136:137], v[136:137], v[168:169]
	s_nop 0
	v_pk_add_f32 v[136:137], v[136:137], v[136:137] op_sel:[0,1] op_sel_hi:[1,0]
	s_cbranch_vccnz .LBB0_248
	v_mov_b64_e32 v[168:169], v[232:233]
	v_mov_b64_e32 v[170:171], v[234:235]
	s_mov_b32 s27, 0x3b000000
	v_mov_b32_e32 v138, v169
	v_mov_b32_e32 v139, v170
	v_mov_b32_e32 v169, v171
	v_pk_add_f32 v[138:139], v[138:139], v[168:169]
	s_nop 0
	v_add_f32_e32 v137, v138, v139
	v_add_f32_e32 v136, v136, v137
; DI unsigned pk(float lo, float hi) { f32x2 v = {lo, hi}; bf2_t b = __builtin_convertvector(v, bf2_t); return __builtin_bit_cast(unsigned, b); }
; DI float bflo(unsigned w) { return __uint_as_float(w << 16); }
; DI float bfhi(unsigned w) { return __uint_as_float(w & 0xffff0000u); }
; DI float sigmoidf_(float x) { return 1.0f / (1.0f + __expf(-x)); }
; DI void gemm_epilogue(const GemmDesc& g, f32x4 (&acc)[2][2][4][2], int brow, int bcol, int wr, int wc, int fr, int fq) {
;     ...
;           const int row = rowb + ai * HALF + m * 16;
;           float rs;
;           { const float* sp = g.f0 + (size_t)row * 32 + head * 8;
;             const f32x4 s0 = gld<f32x4>(sp); float ssum = (s0[0] + s0[1]) + (s0[2] + s0[3]);
;             if (g.dvshift == 9) { const f32x4 s1 = gld<f32x4>(sp + 4); ssum += (s1[0] + s1[1]) + (s1[2] + s1[3]); }
;             rs = rsqrtf(ssum * (g.dvshift == 9 ? (1.0f / 512.0f) : (1.0f / 256.0f)) + EPS); }
;           bf16_t* op = g.o0 + (size_t)row * N + col;
;           const u32x4 ow = gld<u32x4>(op);
;           const float ru = gld<float>(g.rowscale + row);
;           const f32x4 v0 = acc[ai][bj][m][0] * ru, v1 = acc[ai][bj][m][1] * ru;
;           float o[8] = {bflo(ow.x), bfhi(ow.x), bflo(ow.y), bfhi(ow.y), bflo(ow.z), bfhi(ow.z), bflo(ow.w), bfhi(ow.w)};
; #pragma unroll
;           for (int j = 0; j < 4; ++j) { o[j] = o[j] * rs * g0[j] * v0[j] * sigmoidf_(v0[j]); o[4 + j] = o[4 + j] * rs * g1[j] * v1[j] * sigmoidf_(v1[j]); }
;           u32x4 w; w.x = pk(o[0], o[1]); w.y = pk(o[2], o[3]); w.z = pk(o[4], o[5]); w.w = pk(o[6], o[7]);
;           gst<u32x4>(op, w);
;         }
.LBB0_248:
	v_fma_f32 v136, s27, v136, v204
	v_cmp_gt_f32_e32 vcc, s33, v136
	v_mul_f32_e32 v137, 0x4b800000, v136
	s_nop 0
	v_cndmask_b32_e32 v136, v136, v137, vcc
	v_rsq_f32_e32 v136, v136
	s_nop 0
	v_mul_f32_e32 v137, 0x45800000, v136
	v_cndmask_b32_e32 v142, v136, v137, vcc
	v_mov_b64_e32 v[136:137], v[242:243]
	v_mov_b64_e32 v[138:139], v[244:245]
	v_mov_b32_e32 v148, v246
	v_lshlrev_b32_e32 v168, 16, v136
	v_pk_mul_f32 v[170:171], v[28:29], v[148:149] op_sel_hi:[1,0]
	v_and_b32_e32 v169, 0xffff0000, v136
	v_mul_f32_e32 v136, 0xbfb8aa3b, v170
	v_exp_f32_e32 v172, v136
	v_mul_f32_e32 v136, 0xbfb8aa3b, v171
	v_exp_f32_e32 v173, v136
	v_pk_mul_f32 v[168:169], v[142:143], v[168:169] op_sel_hi:[0,1]
	v_pk_mul_f32 v[168:169], v[132:133], v[168:169]
	s_nop 0
	v_pk_mul_f32 v[168:169], v[170:171], v[168:169]
	v_pk_add_f32 v[170:171], v[172:173], 1.0 op_sel_hi:[1,0]
	s_nop 0
	v_div_scale_f32 v136, s[46:47], v171, v171, 1.0
	v_rcp_f32_e32 v143, v136
	s_nop 0
	v_fma_f32 v165, -v136, v143, 1.0
	v_fmac_f32_e32 v143, v165, v143
	v_div_scale_f32 v165, vcc, 1.0, v171, 1.0
	v_mul_f32_e32 v167, v165, v143
	v_fma_f32 v172, -v136, v167, v165
	v_fmac_f32_e32 v167, v172, v143
	v_fma_f32 v136, -v136, v167, v165
	v_div_fmas_f32 v136, v136, v143, v167
	v_div_fixup_f32 v171, v136, v171, 1.0
	v_div_scale_f32 v136, s[46:47], v170, v170, 1.0
	v_rcp_f32_e32 v143, v136
	s_nop 0
	v_fma_f32 v165, -v136, v143, 1.0
	v_fmac_f32_e32 v143, v165, v143
	v_div_scale_f32 v165, vcc, 1.0, v170, 1.0
	v_mul_f32_e32 v167, v165, v143
	v_fma_f32 v172, -v136, v167, v165
	v_fmac_f32_e32 v167, v172, v143
	v_fma_f32 v136, -v136, v167, v165
	v_div_fmas_f32 v136, v136, v143, v167
	v_pk_mul_f32 v[172:173], v[24:25], v[148:149] op_sel_hi:[1,0]
	v_div_fixup_f32 v170, v136, v170, 1.0
	v_mul_f32_e32 v136, 0xbfb8aa3b, v172
	v_exp_f32_e32 v182, v136
	v_mul_f32_e32 v136, 0xbfb8aa3b, v173
	v_exp_f32_e32 v183, v136
	v_pk_mul_f32 v[168:169], v[170:171], v[168:169]
	v_lshlrev_b32_e32 v170, 16, v138
	v_and_b32_e32 v171, 0xffff0000, v138
	v_pk_mul_f32 v[170:171], v[142:143], v[170:171] op_sel_hi:[0,1]
	v_pk_mul_f32 v[170:171], v[128:129], v[170:171]
	s_nop 0
	v_pk_mul_f32 v[170:171], v[172:173], v[170:171]
	v_pk_add_f32 v[172:173], v[182:183], 1.0 op_sel_hi:[1,0]
	s_nop 0
	v_div_scale_f32 v136, s[46:47], v173, v173, 1.0
	v_rcp_f32_e32 v138, v136
	s_nop 0
	v_fma_f32 v143, -v136, v138, 1.0
	v_fmac_f32_e32 v138, v143, v138
	v_div_scale_f32 v143, vcc, 1.0, v173, 1.0
	v_mul_f32_e32 v165, v143, v138
	v_fma_f32 v167, -v136, v165, v143
	v_fmac_f32_e32 v165, v167, v138
	v_fma_f32 v136, -v136, v165, v143
	v_div_fmas_f32 v136, v136, v138, v165
	v_div_fixup_f32 v173, v136, v173, 1.0
	v_div_scale_f32 v136, s[46:47], v172, v172, 1.0
	v_rcp_f32_e32 v138, v136
	s_nop 0
	v_fma_f32 v143, -v136, v138, 1.0
	v_fmac_f32_e32 v138, v143, v138
	v_div_scale_f32 v143, vcc, 1.0, v172, 1.0
	v_mul_f32_e32 v165, v143, v138
	v_fma_f32 v167, -v136, v165, v143
	v_fmac_f32_e32 v165, v167, v138
	v_fma_f32 v136, -v136, v165, v143
	v_div_fmas_f32 v136, v136, v138, v165
	v_div_fixup_f32 v172, v136, v172, 1.0
	v_pk_mul_f32 v[170:171], v[172:173], v[170:171]
	v_pk_mul_f32 v[172:173], v[30:31], v[148:149] op_sel_hi:[1,0]
	v_lshlrev_b32_e32 v136, 16, v137
	v_mul_f32_e32 v138, 0xbfb8aa3b, v172
	v_exp_f32_e32 v182, v138
	v_mul_f32_e32 v138, 0xbfb8aa3b, v173
	v_exp_f32_e32 v183, v138
	v_and_b32_e32 v137, 0xffff0000, v137
	v_pk_mul_f32 v[136:137], v[142:143], v[136:137] op_sel_hi:[0,1]
	v_pk_mul_f32 v[136:137], v[134:135], v[136:137]
	s_nop 0
	v_pk_mul_f32 v[136:137], v[172:173], v[136:137]
	v_pk_add_f32 v[172:173], v[182:183], 1.0 op_sel_hi:[1,0]
	s_nop 0
	v_div_scale_f32 v138, s[46:47], v173, v173, 1.0
	v_rcp_f32_e32 v143, v138
	s_nop 0
	v_fma_f32 v165, -v138, v143, 1.0
	v_fmac_f32_e32 v143, v165, v143
	v_div_scale_f32 v165, vcc, 1.0, v173, 1.0
	v_mul_f32_e32 v167, v165, v143
	v_fma_f32 v182, -v138, v167, v165
	v_fmac_f32_e32 v167, v182, v143
	v_fma_f32 v138, -v138, v167, v165
	v_div_fmas_f32 v138, v138, v143, v167
	v_div_fixup_f32 v173, v138, v173, 1.0
	v_div_scale_f32 v138, s[46:47], v172, v172, 1.0
	v_rcp_f32_e32 v143, v138
	s_nop 0
	v_fma_f32 v165, -v138, v143, 1.0
	v_fmac_f32_e32 v143, v165, v143
	v_div_scale_f32 v165, vcc, 1.0, v172, 1.0
	v_mul_f32_e32 v167, v165, v143
	v_fma_f32 v182, -v138, v167, v165
	v_fmac_f32_e32 v167, v182, v143
	v_fma_f32 v138, -v138, v167, v165
	v_div_fmas_f32 v138, v138, v143, v167
	v_div_fixup_f32 v172, v138, v172, 1.0
	v_pk_mul_f32 v[172:173], v[172:173], v[136:137]
	v_lshlrev_b32_e32 v136, 16, v139
	v_and_b32_e32 v137, 0xffff0000, v139
	v_pk_mul_f32 v[138:139], v[26:27], v[148:149] op_sel_hi:[1,0]
	s_nop 0
	v_mul_f32_e32 v143, 0xbfb8aa3b, v138
	v_pk_mul_f32 v[136:137], v[142:143], v[136:137] op_sel_hi:[0,1]
	v_pk_mul_f32 v[136:137], v[130:131], v[136:137]
	v_exp_f32_e32 v182, v143
	v_pk_mul_f32 v[136:137], v[138:139], v[136:137]
	v_mul_f32_e32 v138, 0xbfb8aa3b, v139
	v_exp_f32_e32 v183, v138
	s_nop 0
	v_pk_add_f32 v[138:139], v[182:183], 1.0 op_sel_hi:[1,0]
	s_nop 0
	v_div_scale_f32 v142, s[46:47], v139, v139, 1.0
	v_rcp_f32_e32 v143, v142
	s_nop 0
	v_fma_f32 v148, -v142, v143, 1.0
	v_fmac_f32_e32 v143, v148, v143
	v_div_scale_f32 v148, vcc, 1.0, v139, 1.0
	v_mul_f32_e32 v165, v148, v143
	v_fma_f32 v167, -v142, v165, v148
	v_fmac_f32_e32 v165, v167, v143
	v_fma_f32 v142, -v142, v165, v148
	v_div_fmas_f32 v142, v142, v143, v165
	v_div_fixup_f32 v139, v142, v139, 1.0
	v_div_scale_f32 v142, s[46:47], v138, v138, 1.0
	v_rcp_f32_e32 v143, v142
	s_nop 0
	v_fma_f32 v148, -v142, v143, 1.0
	v_fmac_f32_e32 v143, v148, v143
	v_div_scale_f32 v148, vcc, 1.0, v138, 1.0
	v_mul_f32_e32 v165, v148, v143
	v_fma_f32 v167, -v142, v165, v148
	v_fmac_f32_e32 v165, v167, v143
	v_fma_f32 v142, -v142, v165, v148
	v_div_fmas_f32 v142, v142, v143, v165
	v_div_fixup_f32 v138, v142, v138, 1.0
	v_pk_mul_f32 v[142:143], v[138:139], v[136:137]
	v_cvt_pk_bf16_f32 v136, v168, v169
	v_cvt_pk_bf16_f32 v137, v172, v173
	v_cvt_pk_bf16_f32 v138, v170, v171
	v_cvt_pk_bf16_f32 v139, v142, v143
	global_store_dwordx4 v[174:175], v[136:139], off offset:256
	s_and_b64 vcc, exec, s[44:45]
	s_nop 0
	v_lshl_add_u64 v[138:139], v[198:199], 2, v[192:193]
	global_load_dwordx4 v[168:171], v[138:139], off
	global_load_dwordx4 v[232:235], v[138:139], off offset:16
	global_load_dwordx4 v[242:245], v[176:177], off offset:256
	global_load_dword v246, v[140:141], off offset:576
	s_waitcnt vmcnt(0)
	v_mov_b32_e32 v136, v169
	v_mov_b32_e32 v137, v170
	v_mov_b32_e32 v169, v171
	v_pk_add_f32 v[136:137], v[136:137], v[168:169]
	s_nop 0
	v_pk_add_f32 v[136:137], v[136:137], v[136:137] op_sel:[0,1] op_sel_hi:[1,0]
	s_cbranch_vccnz .LBB0_250
	v_mov_b64_e32 v[168:169], v[232:233]
	v_mov_b64_e32 v[170:171], v[234:235]
	s_mov_b32 s26, 0x3b000000
	v_mov_b32_e32 v138, v169
	v_mov_b32_e32 v139, v170
	v_mov_b32_e32 v169, v171
	v_pk_add_f32 v[138:139], v[138:139], v[168:169]
	s_nop 0
	v_add_f32_e32 v137, v138, v139
	v_add_f32_e32 v136, v136, v137
; DI unsigned pk(float lo, float hi) { f32x2 v = {lo, hi}; bf2_t b = __builtin_convertvector(v, bf2_t); return __builtin_bit_cast(unsigned, b); }
; DI float bflo(unsigned w) { return __uint_as_float(w << 16); }
; DI float bfhi(unsigned w) { return __uint_as_float(w & 0xffff0000u); }
; DI float sigmoidf_(float x) { return 1.0f / (1.0f + __expf(-x)); }
; DI void gemm_epilogue(const GemmDesc& g, f32x4 (&acc)[2][2][4][2], int brow, int bcol, int wr, int wc, int fr, int fq) {
;     ...
;           const int row = rowb + ai * HALF + m * 16;
;           float rs;
;           { const float* sp = g.f0 + (size_t)row * 32 + head * 8;
;             const f32x4 s0 = gld<f32x4>(sp); float ssum = (s0[0] + s0[1]) + (s0[2] + s0[3]);
;             if (g.dvshift == 9) { const f32x4 s1 = gld<f32x4>(sp + 4); ssum += (s1[0] + s1[1]) + (s1[2] + s1[3]); }
;             rs = rsqrtf(ssum * (g.dvshift == 9 ? (1.0f / 512.0f) : (1.0f / 256.0f)) + EPS); }
;           bf16_t* op = g.o0 + (size_t)row * N + col;
;           const u32x4 ow = gld<u32x4>(op);
;           const float ru = gld<float>(g.rowscale + row);
;           const f32x4 v0 = acc[ai][bj][m][0] * ru, v1 = acc[ai][bj][m][1] * ru;
;           float o[8] = {bflo(ow.x), bfhi(ow.x), bflo(ow.y), bfhi(ow.y), bflo(ow.z), bfhi(ow.z), bflo(ow.w), bfhi(ow.w)};
; #pragma unroll
;           for (int j = 0; j < 4; ++j) { o[j] = o[j] * rs * g0[j] * v0[j] * sigmoidf_(v0[j]); o[4 + j] = o[4 + j] * rs * g1[j] * v1[j] * sigmoidf_(v1[j]); }
;           u32x4 w; w.x = pk(o[0], o[1]); w.y = pk(o[2], o[3]); w.z = pk(o[4], o[5]); w.w = pk(o[6], o[7]);
;           gst<u32x4>(op, w);
;         }
.LBB0_250:
	v_fma_f32 v136, s26, v136, v204
	v_cmp_gt_f32_e32 vcc, s33, v136
	v_mul_f32_e32 v137, 0x4b800000, v136
	s_nop 0
	v_cndmask_b32_e32 v136, v136, v137, vcc
	v_rsq_f32_e32 v136, v136
	s_nop 0
	v_mul_f32_e32 v137, 0x45800000, v136
	v_cndmask_b32_e32 v142, v136, v137, vcc
	v_mov_b64_e32 v[136:137], v[242:243]
	v_mov_b64_e32 v[138:139], v[244:245]
	v_mov_b32_e32 v148, v246
	v_lshlrev_b32_e32 v168, 16, v136
	v_pk_mul_f32 v[170:171], v[20:21], v[148:149] op_sel_hi:[1,0]
	v_and_b32_e32 v169, 0xffff0000, v136
	v_mul_f32_e32 v136, 0xbfb8aa3b, v170
	v_exp_f32_e32 v172, v136
	v_mul_f32_e32 v136, 0xbfb8aa3b, v171
	v_exp_f32_e32 v173, v136
	v_pk_mul_f32 v[168:169], v[142:143], v[168:169] op_sel_hi:[0,1]
	v_pk_mul_f32 v[168:169], v[132:133], v[168:169]
	s_nop 0
	v_pk_mul_f32 v[168:169], v[170:171], v[168:169]
	v_pk_add_f32 v[170:171], v[172:173], 1.0 op_sel_hi:[1,0]
	s_nop 0
	v_div_scale_f32 v136, s[26:27], v171, v171, 1.0
	v_rcp_f32_e32 v143, v136
	s_nop 0
	v_fma_f32 v165, -v136, v143, 1.0
	v_fmac_f32_e32 v143, v165, v143
	v_div_scale_f32 v165, vcc, 1.0, v171, 1.0
	v_mul_f32_e32 v167, v165, v143
	v_fma_f32 v172, -v136, v167, v165
	v_fmac_f32_e32 v167, v172, v143
	v_fma_f32 v136, -v136, v167, v165
	v_div_fmas_f32 v136, v136, v143, v167
	v_div_fixup_f32 v171, v136, v171, 1.0
	v_div_scale_f32 v136, s[26:27], v170, v170, 1.0
	v_rcp_f32_e32 v143, v136
	s_nop 0
	v_fma_f32 v165, -v136, v143, 1.0
	v_fmac_f32_e32 v143, v165, v143
	v_div_scale_f32 v165, vcc, 1.0, v170, 1.0
	v_mul_f32_e32 v167, v165, v143
	v_fma_f32 v172, -v136, v167, v165
	v_fmac_f32_e32 v167, v172, v143
	v_fma_f32 v136, -v136, v167, v165
	v_div_fmas_f32 v136, v136, v143, v167
	v_pk_mul_f32 v[172:173], v[16:17], v[148:149] op_sel_hi:[1,0]
	v_div_fixup_f32 v170, v136, v170, 1.0
	v_mul_f32_e32 v136, 0xbfb8aa3b, v172
	v_exp_f32_e32 v174, v136
	v_mul_f32_e32 v136, 0xbfb8aa3b, v173
	v_exp_f32_e32 v175, v136
	v_pk_mul_f32 v[168:169], v[170:171], v[168:169]
	v_lshlrev_b32_e32 v170, 16, v138
	v_and_b32_e32 v171, 0xffff0000, v138
	v_pk_mul_f32 v[170:171], v[142:143], v[170:171] op_sel_hi:[0,1]
	v_pk_mul_f32 v[170:171], v[128:129], v[170:171]
	s_nop 0
	v_pk_mul_f32 v[170:171], v[172:173], v[170:171]
	v_pk_add_f32 v[172:173], v[174:175], 1.0 op_sel_hi:[1,0]
	s_nop 0
	v_div_scale_f32 v136, s[26:27], v173, v173, 1.0
	v_rcp_f32_e32 v138, v136
	s_nop 0
	v_fma_f32 v143, -v136, v138, 1.0
	v_fmac_f32_e32 v138, v143, v138
	v_div_scale_f32 v143, vcc, 1.0, v173, 1.0
	v_mul_f32_e32 v165, v143, v138
	v_fma_f32 v167, -v136, v165, v143
	v_fmac_f32_e32 v165, v167, v138
	v_fma_f32 v136, -v136, v165, v143
	v_div_fmas_f32 v136, v136, v138, v165
	v_div_fixup_f32 v173, v136, v173, 1.0
	v_div_scale_f32 v136, s[26:27], v172, v172, 1.0
	v_rcp_f32_e32 v138, v136
	s_nop 0
	v_fma_f32 v143, -v136, v138, 1.0
	v_fmac_f32_e32 v138, v143, v138
	v_div_scale_f32 v143, vcc, 1.0, v172, 1.0
	v_mul_f32_e32 v165, v143, v138
	v_fma_f32 v167, -v136, v165, v143
	v_fmac_f32_e32 v165, v167, v138
	v_fma_f32 v136, -v136, v165, v143
	v_div_fmas_f32 v136, v136, v138, v165
	v_div_fixup_f32 v172, v136, v172, 1.0
	v_pk_mul_f32 v[170:171], v[172:173], v[170:171]
	v_pk_mul_f32 v[172:173], v[22:23], v[148:149] op_sel_hi:[1,0]
	v_lshlrev_b32_e32 v136, 16, v137
	v_mul_f32_e32 v138, 0xbfb8aa3b, v172
	v_exp_f32_e32 v174, v138
	v_mul_f32_e32 v138, 0xbfb8aa3b, v173
	v_exp_f32_e32 v175, v138
	v_and_b32_e32 v137, 0xffff0000, v137
	v_pk_mul_f32 v[136:137], v[142:143], v[136:137] op_sel_hi:[0,1]
	v_pk_mul_f32 v[136:137], v[134:135], v[136:137]
	s_nop 0
	v_pk_mul_f32 v[136:137], v[172:173], v[136:137]
	v_pk_add_f32 v[172:173], v[174:175], 1.0 op_sel_hi:[1,0]
	s_nop 0
	v_div_scale_f32 v138, s[26:27], v173, v173, 1.0
	v_rcp_f32_e32 v143, v138
	s_nop 0
	v_fma_f32 v165, -v138, v143, 1.0
	v_fmac_f32_e32 v143, v165, v143
	v_div_scale_f32 v165, vcc, 1.0, v173, 1.0
	v_mul_f32_e32 v167, v165, v143
	v_fma_f32 v174, -v138, v167, v165
	v_fmac_f32_e32 v167, v174, v143
	v_fma_f32 v138, -v138, v167, v165
	v_div_fmas_f32 v138, v138, v143, v167
	v_div_fixup_f32 v173, v138, v173, 1.0
	v_div_scale_f32 v138, s[26:27], v172, v172, 1.0
	v_rcp_f32_e32 v143, v138
	s_nop 0
	v_fma_f32 v165, -v138, v143, 1.0
	v_fmac_f32_e32 v143, v165, v143
	v_div_scale_f32 v165, vcc, 1.0, v172, 1.0
	v_mul_f32_e32 v167, v165, v143
	v_fma_f32 v174, -v138, v167, v165
	v_fmac_f32_e32 v167, v174, v143
	v_fma_f32 v138, -v138, v167, v165
	v_div_fmas_f32 v138, v138, v143, v167
	v_div_fixup_f32 v172, v138, v172, 1.0
	v_pk_mul_f32 v[172:173], v[172:173], v[136:137]
	v_lshlrev_b32_e32 v136, 16, v139
	v_and_b32_e32 v137, 0xffff0000, v139
	v_pk_mul_f32 v[138:139], v[18:19], v[148:149] op_sel_hi:[1,0]
	s_nop 0
	v_mul_f32_e32 v143, 0xbfb8aa3b, v138
	v_pk_mul_f32 v[136:137], v[142:143], v[136:137] op_sel_hi:[0,1]
	v_pk_mul_f32 v[136:137], v[130:131], v[136:137]
	v_exp_f32_e32 v174, v143
	v_pk_mul_f32 v[136:137], v[138:139], v[136:137]
	v_mul_f32_e32 v138, 0xbfb8aa3b, v139
	v_exp_f32_e32 v175, v138
	s_nop 0
	v_pk_add_f32 v[138:139], v[174:175], 1.0 op_sel_hi:[1,0]
	s_nop 0
	v_div_scale_f32 v142, s[26:27], v139, v139, 1.0
	v_rcp_f32_e32 v143, v142
	s_nop 0
	v_fma_f32 v148, -v142, v143, 1.0
	v_fmac_f32_e32 v143, v148, v143
	v_div_scale_f32 v148, vcc, 1.0, v139, 1.0
	v_mul_f32_e32 v165, v148, v143
	v_fma_f32 v167, -v142, v165, v148
	v_fmac_f32_e32 v165, v167, v143
	v_fma_f32 v142, -v142, v165, v148
	v_div_fmas_f32 v142, v142, v143, v165
	v_div_fixup_f32 v139, v142, v139, 1.0
	v_div_scale_f32 v142, s[26:27], v138, v138, 1.0
	v_rcp_f32_e32 v143, v142
	s_mov_b32 s26, 0x3b800000
	s_mov_b32 s27, 0x3b800000
	v_fma_f32 v148, -v142, v143, 1.0
	v_fmac_f32_e32 v143, v148, v143
	v_div_scale_f32 v148, vcc, 1.0, v138, 1.0
	v_mul_f32_e32 v165, v148, v143
	v_fma_f32 v167, -v142, v165, v148
	v_fmac_f32_e32 v165, v167, v143
	v_fma_f32 v142, -v142, v165, v148
	v_div_fmas_f32 v142, v142, v143, v165
	v_div_fixup_f32 v138, v142, v138, 1.0
	v_pk_mul_f32 v[142:143], v[138:139], v[136:137]
	v_cvt_pk_bf16_f32 v136, v168, v169
	v_cvt_pk_bf16_f32 v137, v172, v173
	v_cvt_pk_bf16_f32 v138, v170, v171
	v_cvt_pk_bf16_f32 v139, v142, v143
	global_store_dwordx4 v[176:177], v[136:139], off offset:256
	s_and_b64 vcc, exec, s[44:45]
	s_nop 0
	v_lshl_add_u64 v[138:139], v[198:199], 2, v[194:195]
	global_load_dwordx4 v[168:171], v[138:139], off
	global_load_dwordx4 v[232:235], v[138:139], off offset:16
	global_load_dwordx4 v[242:245], v[178:179], off offset:256
	global_load_dword v246, v[140:141], off offset:640
	s_waitcnt vmcnt(0)
	v_mov_b32_e32 v136, v169
	v_mov_b32_e32 v137, v170
	v_mov_b32_e32 v169, v171
	v_pk_add_f32 v[136:137], v[136:137], v[168:169]
	s_nop 0
	v_pk_add_f32 v[136:137], v[136:137], v[136:137] op_sel:[0,1] op_sel_hi:[1,0]
	s_cbranch_vccnz .LBB0_252
	v_mov_b64_e32 v[168:169], v[232:233]
	v_mov_b64_e32 v[170:171], v[234:235]
	s_mov_b32 s27, 0x3b000000
	v_mov_b32_e32 v138, v169
	v_mov_b32_e32 v139, v170
	v_mov_b32_e32 v169, v171
	v_pk_add_f32 v[138:139], v[138:139], v[168:169]
	s_nop 0
	v_add_f32_e32 v137, v138, v139
	v_add_f32_e32 v136, v136, v137
; DI unsigned pk(float lo, float hi) { f32x2 v = {lo, hi}; bf2_t b = __builtin_convertvector(v, bf2_t); return __builtin_bit_cast(unsigned, b); }
; DI float bflo(unsigned w) { return __uint_as_float(w << 16); }
; DI float bfhi(unsigned w) { return __uint_as_float(w & 0xffff0000u); }
; DI float sigmoidf_(float x) { return 1.0f / (1.0f + __expf(-x)); }
; DI void gemm_epilogue(const GemmDesc& g, f32x4 (&acc)[2][2][4][2], int brow, int bcol, int wr, int wc, int fr, int fq) {
;     ...
;           const int row = rowb + ai * HALF + m * 16;
;           float rs;
;           { const float* sp = g.f0 + (size_t)row * 32 + head * 8;
;             const f32x4 s0 = gld<f32x4>(sp); float ssum = (s0[0] + s0[1]) + (s0[2] + s0[3]);
;             if (g.dvshift == 9) { const f32x4 s1 = gld<f32x4>(sp + 4); ssum += (s1[0] + s1[1]) + (s1[2] + s1[3]); }
;             rs = rsqrtf(ssum * (g.dvshift == 9 ? (1.0f / 512.0f) : (1.0f / 256.0f)) + EPS); }
;           bf16_t* op = g.o0 + (size_t)row * N + col;
;           const u32x4 ow = gld<u32x4>(op);
;           const float ru = gld<float>(g.rowscale + row);
;           const f32x4 v0 = acc[ai][bj][m][0] * ru, v1 = acc[ai][bj][m][1] * ru;
;           float o[8] = {bflo(ow.x), bfhi(ow.x), bflo(ow.y), bfhi(ow.y), bflo(ow.z), bfhi(ow.z), bflo(ow.w), bfhi(ow.w)};
; #pragma unroll
;           for (int j = 0; j < 4; ++j) { o[j] = o[j] * rs * g0[j] * v0[j] * sigmoidf_(v0[j]); o[4 + j] = o[4 + j] * rs * g1[j] * v1[j] * sigmoidf_(v1[j]); }
;           u32x4 w; w.x = pk(o[0], o[1]); w.y = pk(o[2], o[3]); w.z = pk(o[4], o[5]); w.w = pk(o[6], o[7]);
;           gst<u32x4>(op, w);
;         }
.LBB0_252:
	v_fma_f32 v136, s27, v136, v204
	v_cmp_gt_f32_e32 vcc, s33, v136
	v_mul_f32_e32 v137, 0x4b800000, v136
	s_nop 0
	v_cndmask_b32_e32 v136, v136, v137, vcc
	v_rsq_f32_e32 v136, v136
	s_nop 0
	v_mul_f32_e32 v137, 0x45800000, v136
	v_cndmask_b32_e32 v142, v136, v137, vcc
	v_mov_b64_e32 v[136:137], v[242:243]
	v_mov_b64_e32 v[138:139], v[244:245]
	v_mov_b32_e32 v148, v246
	v_lshlrev_b32_e32 v168, 16, v136
	v_pk_mul_f32 v[170:171], v[12:13], v[148:149] op_sel_hi:[1,0]
	v_and_b32_e32 v169, 0xffff0000, v136
	v_mul_f32_e32 v136, 0xbfb8aa3b, v170
	v_exp_f32_e32 v172, v136
	v_mul_f32_e32 v136, 0xbfb8aa3b, v171
	v_exp_f32_e32 v173, v136
	v_pk_mul_f32 v[168:169], v[142:143], v[168:169] op_sel_hi:[0,1]
	v_pk_mul_f32 v[168:169], v[132:133], v[168:169]
	s_nop 0
	v_pk_mul_f32 v[168:169], v[170:171], v[168:169]
	v_pk_add_f32 v[170:171], v[172:173], 1.0 op_sel_hi:[1,0]
	s_nop 0
	v_div_scale_f32 v136, s[46:47], v171, v171, 1.0
	v_rcp_f32_e32 v143, v136
	s_nop 0
	v_fma_f32 v165, -v136, v143, 1.0
	v_fmac_f32_e32 v143, v165, v143
	v_div_scale_f32 v165, vcc, 1.0, v171, 1.0
	v_mul_f32_e32 v167, v165, v143
	v_fma_f32 v172, -v136, v167, v165
	v_fmac_f32_e32 v167, v172, v143
	v_fma_f32 v136, -v136, v167, v165
	v_div_fmas_f32 v136, v136, v143, v167
	v_div_fixup_f32 v171, v136, v171, 1.0
	v_div_scale_f32 v136, s[46:47], v170, v170, 1.0
	v_rcp_f32_e32 v143, v136
	s_nop 0
	v_fma_f32 v165, -v136, v143, 1.0
	v_fmac_f32_e32 v143, v165, v143
	v_div_scale_f32 v165, vcc, 1.0, v170, 1.0
	v_mul_f32_e32 v167, v165, v143
	v_fma_f32 v172, -v136, v167, v165
	v_fmac_f32_e32 v167, v172, v143
	v_fma_f32 v136, -v136, v167, v165
	v_div_fmas_f32 v136, v136, v143, v167
	v_pk_mul_f32 v[172:173], v[8:9], v[148:149] op_sel_hi:[1,0]
	v_div_fixup_f32 v170, v136, v170, 1.0
	v_mul_f32_e32 v136, 0xbfb8aa3b, v172
	v_exp_f32_e32 v174, v136
	v_mul_f32_e32 v136, 0xbfb8aa3b, v173
	v_exp_f32_e32 v175, v136
	v_pk_mul_f32 v[168:169], v[170:171], v[168:169]
	v_lshlrev_b32_e32 v170, 16, v138
	v_and_b32_e32 v171, 0xffff0000, v138
	v_pk_mul_f32 v[170:171], v[142:143], v[170:171] op_sel_hi:[0,1]
	v_pk_mul_f32 v[170:171], v[128:129], v[170:171]
	s_nop 0
	v_pk_mul_f32 v[170:171], v[172:173], v[170:171]
	v_pk_add_f32 v[172:173], v[174:175], 1.0 op_sel_hi:[1,0]
	s_nop 0
	v_div_scale_f32 v136, s[46:47], v173, v173, 1.0
	v_rcp_f32_e32 v138, v136
	s_nop 0
	v_fma_f32 v143, -v136, v138, 1.0
	v_fmac_f32_e32 v138, v143, v138
	v_div_scale_f32 v143, vcc, 1.0, v173, 1.0
	v_mul_f32_e32 v165, v143, v138
	v_fma_f32 v167, -v136, v165, v143
	v_fmac_f32_e32 v165, v167, v138
	v_fma_f32 v136, -v136, v165, v143
	v_div_fmas_f32 v136, v136, v138, v165
	v_div_fixup_f32 v173, v136, v173, 1.0
	v_div_scale_f32 v136, s[46:47], v172, v172, 1.0
	v_rcp_f32_e32 v138, v136
	s_nop 0
	v_fma_f32 v143, -v136, v138, 1.0
	v_fmac_f32_e32 v138, v143, v138
	v_div_scale_f32 v143, vcc, 1.0, v172, 1.0
	v_mul_f32_e32 v165, v143, v138
	v_fma_f32 v167, -v136, v165, v143
	v_fmac_f32_e32 v165, v167, v138
	v_fma_f32 v136, -v136, v165, v143
	v_div_fmas_f32 v136, v136, v138, v165
	v_div_fixup_f32 v172, v136, v172, 1.0
	v_pk_mul_f32 v[170:171], v[172:173], v[170:171]
	v_pk_mul_f32 v[172:173], v[14:15], v[148:149] op_sel_hi:[1,0]
	v_lshlrev_b32_e32 v136, 16, v137
	v_mul_f32_e32 v138, 0xbfb8aa3b, v172
	v_exp_f32_e32 v174, v138
	v_mul_f32_e32 v138, 0xbfb8aa3b, v173
	v_exp_f32_e32 v175, v138
	v_and_b32_e32 v137, 0xffff0000, v137
	v_pk_mul_f32 v[136:137], v[142:143], v[136:137] op_sel_hi:[0,1]
	v_pk_mul_f32 v[136:137], v[134:135], v[136:137]
	s_nop 0
	v_pk_mul_f32 v[136:137], v[172:173], v[136:137]
	v_pk_add_f32 v[172:173], v[174:175], 1.0 op_sel_hi:[1,0]
	s_nop 0
	v_div_scale_f32 v138, s[46:47], v173, v173, 1.0
	v_rcp_f32_e32 v143, v138
	s_nop 0
	v_fma_f32 v165, -v138, v143, 1.0
	v_fmac_f32_e32 v143, v165, v143
	v_div_scale_f32 v165, vcc, 1.0, v173, 1.0
	v_mul_f32_e32 v167, v165, v143
	v_fma_f32 v174, -v138, v167, v165
	v_fmac_f32_e32 v167, v174, v143
	v_fma_f32 v138, -v138, v167, v165
	v_div_fmas_f32 v138, v138, v143, v167
	v_div_fixup_f32 v173, v138, v173, 1.0
	v_div_scale_f32 v138, s[46:47], v172, v172, 1.0
	v_rcp_f32_e32 v143, v138
	s_nop 0
	v_fma_f32 v165, -v138, v143, 1.0
	v_fmac_f32_e32 v143, v165, v143
	v_div_scale_f32 v165, vcc, 1.0, v172, 1.0
	v_mul_f32_e32 v167, v165, v143
	v_fma_f32 v174, -v138, v167, v165
	v_fmac_f32_e32 v167, v174, v143
	v_fma_f32 v138, -v138, v167, v165
	v_div_fmas_f32 v138, v138, v143, v167
	v_div_fixup_f32 v172, v138, v172, 1.0
	v_pk_mul_f32 v[172:173], v[172:173], v[136:137]
	v_lshlrev_b32_e32 v136, 16, v139
	v_and_b32_e32 v137, 0xffff0000, v139
	v_pk_mul_f32 v[138:139], v[10:11], v[148:149] op_sel_hi:[1,0]
	s_nop 0
	v_mul_f32_e32 v143, 0xbfb8aa3b, v138
	v_pk_mul_f32 v[136:137], v[142:143], v[136:137] op_sel_hi:[0,1]
	v_pk_mul_f32 v[136:137], v[130:131], v[136:137]
	v_exp_f32_e32 v174, v143
	v_pk_mul_f32 v[136:137], v[138:139], v[136:137]
	v_mul_f32_e32 v138, 0xbfb8aa3b, v139
	v_exp_f32_e32 v175, v138
	s_nop 0
	v_pk_add_f32 v[138:139], v[174:175], 1.0 op_sel_hi:[1,0]
	s_nop 0
	v_div_scale_f32 v142, s[46:47], v139, v139, 1.0
	v_rcp_f32_e32 v143, v142
	s_nop 0
	v_fma_f32 v148, -v142, v143, 1.0
	v_fmac_f32_e32 v143, v148, v143
	v_div_scale_f32 v148, vcc, 1.0, v139, 1.0
	v_mul_f32_e32 v165, v148, v143
	v_fma_f32 v167, -v142, v165, v148
	v_fmac_f32_e32 v165, v167, v143
	v_fma_f32 v142, -v142, v165, v148
	v_div_fmas_f32 v142, v142, v143, v165
	v_div_fixup_f32 v139, v142, v139, 1.0
	v_div_scale_f32 v142, s[46:47], v138, v138, 1.0
	v_rcp_f32_e32 v143, v142
	s_nop 0
	v_fma_f32 v148, -v142, v143, 1.0
	v_fmac_f32_e32 v143, v148, v143
	v_div_scale_f32 v148, vcc, 1.0, v138, 1.0
	v_mul_f32_e32 v165, v148, v143
	v_fma_f32 v167, -v142, v165, v148
	v_fmac_f32_e32 v165, v167, v143
	v_fma_f32 v142, -v142, v165, v148
	v_div_fmas_f32 v142, v142, v143, v165
	v_div_fixup_f32 v138, v142, v138, 1.0
	v_pk_mul_f32 v[142:143], v[138:139], v[136:137]
	v_cvt_pk_bf16_f32 v136, v168, v169
	v_cvt_pk_bf16_f32 v137, v172, v173
	v_cvt_pk_bf16_f32 v138, v170, v171
	v_cvt_pk_bf16_f32 v139, v142, v143
	global_store_dwordx4 v[178:179], v[136:139], off offset:256
	s_and_b64 vcc, exec, s[44:45]
	s_nop 0
	v_lshl_add_u64 v[138:139], v[198:199], 2, v[196:197]
	global_load_dwordx4 v[168:171], v[138:139], off
	global_load_dwordx4 v[232:235], v[138:139], off offset:16
	global_load_dwordx4 v[242:245], v[180:181], off offset:256
	global_load_dword v246, v[140:141], off offset:704
	s_waitcnt vmcnt(0)
	v_mov_b32_e32 v136, v169
	v_mov_b32_e32 v137, v170
	v_mov_b32_e32 v169, v171
	v_pk_add_f32 v[136:137], v[136:137], v[168:169]
	s_nop 0
	v_pk_add_f32 v[136:137], v[136:137], v[136:137] op_sel:[0,1] op_sel_hi:[1,0]
	s_cbranch_vccnz .LBB0_254
	v_mov_b64_e32 v[168:169], v[232:233]
	v_mov_b64_e32 v[170:171], v[234:235]
	s_mov_b32 s26, 0x3b000000
	v_mov_b32_e32 v138, v169
	v_mov_b32_e32 v139, v170
	v_mov_b32_e32 v169, v171
	v_pk_add_f32 v[138:139], v[138:139], v[168:169]
	s_nop 0
	v_add_f32_e32 v137, v138, v139
	v_add_f32_e32 v136, v136, v137
; DI unsigned pk(float lo, float hi) { f32x2 v = {lo, hi}; bf2_t b = __builtin_convertvector(v, bf2_t); return __builtin_bit_cast(unsigned, b); }
; DI float bflo(unsigned w) { return __uint_as_float(w << 16); }
; DI float bfhi(unsigned w) { return __uint_as_float(w & 0xffff0000u); }
; DI float sigmoidf_(float x) { return 1.0f / (1.0f + __expf(-x)); }
; DI void gemm_epilogue(const GemmDesc& g, f32x4 (&acc)[2][2][4][2], int brow, int bcol, int wr, int wc, int fr, int fq) {
;     ...
;           const int row = rowb + ai * HALF + m * 16;
;           float rs;
;           { const float* sp = g.f0 + (size_t)row * 32 + head * 8;
;             const f32x4 s0 = gld<f32x4>(sp); float ssum = (s0[0] + s0[1]) + (s0[2] + s0[3]);
;             if (g.dvshift == 9) { const f32x4 s1 = gld<f32x4>(sp + 4); ssum += (s1[0] + s1[1]) + (s1[2] + s1[3]); }
;             rs = rsqrtf(ssum * (g.dvshift == 9 ? (1.0f / 512.0f) : (1.0f / 256.0f)) + EPS); }
;           bf16_t* op = g.o0 + (size_t)row * N + col;
;           const u32x4 ow = gld<u32x4>(op);
;           const float ru = gld<float>(g.rowscale + row);
;           const f32x4 v0 = acc[ai][bj][m][0] * ru, v1 = acc[ai][bj][m][1] * ru;
;           float o[8] = {bflo(ow.x), bfhi(ow.x), bflo(ow.y), bfhi(ow.y), bflo(ow.z), bfhi(ow.z), bflo(ow.w), bfhi(ow.w)};
; #pragma unroll
;           for (int j = 0; j < 4; ++j) { o[j] = o[j] * rs * g0[j] * v0[j] * sigmoidf_(v0[j]); o[4 + j] = o[4 + j] * rs * g1[j] * v1[j] * sigmoidf_(v1[j]); }
;           u32x4 w; w.x = pk(o[0], o[1]); w.y = pk(o[2], o[3]); w.z = pk(o[4], o[5]); w.w = pk(o[6], o[7]);
;           gst<u32x4>(op, w);
;         }
.LBB0_254:
	v_fma_f32 v136, s26, v136, v204
	v_cmp_gt_f32_e32 vcc, s33, v136
	v_mul_f32_e32 v137, 0x4b800000, v136
	s_nop 0
	v_cndmask_b32_e32 v136, v136, v137, vcc
	v_rsq_f32_e32 v136, v136
	s_nop 0
	v_mul_f32_e32 v137, 0x45800000, v136
	v_cndmask_b32_e32 v142, v136, v137, vcc
	v_mov_b64_e32 v[136:137], v[242:243]
	v_mov_b64_e32 v[138:139], v[244:245]
	s_nop 0
	v_mov_b32_e32 v140, v246
	v_lshlrev_b32_e32 v168, 16, v136
	v_pk_mul_f32 v[170:171], v[4:5], v[140:141] op_sel_hi:[1,0]
	v_and_b32_e32 v169, 0xffff0000, v136
	v_mul_f32_e32 v136, 0xbfb8aa3b, v170
	v_exp_f32_e32 v172, v136
	v_mul_f32_e32 v136, 0xbfb8aa3b, v171
	v_exp_f32_e32 v173, v136
	v_pk_mul_f32 v[168:169], v[142:143], v[168:169] op_sel_hi:[0,1]
	v_pk_mul_f32 v[132:133], v[132:133], v[168:169]
	v_pk_add_f32 v[168:169], v[172:173], 1.0 op_sel_hi:[1,0]
	s_nop 0
	v_div_scale_f32 v136, s[26:27], v169, v169, 1.0
	v_rcp_f32_e32 v141, v136
	v_pk_mul_f32 v[132:133], v[170:171], v[132:133]
	v_fma_f32 v143, -v136, v141, 1.0
	v_fmac_f32_e32 v141, v143, v141
	v_div_scale_f32 v143, vcc, 1.0, v169, 1.0
	v_mul_f32_e32 v148, v143, v141
	v_fma_f32 v165, -v136, v148, v143
	v_fmac_f32_e32 v148, v165, v141
	v_fma_f32 v136, -v136, v148, v143
	v_div_fmas_f32 v136, v136, v141, v148
	v_div_fixup_f32 v169, v136, v169, 1.0
	v_div_scale_f32 v136, s[26:27], v168, v168, 1.0
	v_rcp_f32_e32 v141, v136
	s_nop 0
	v_fma_f32 v143, -v136, v141, 1.0
	v_fmac_f32_e32 v141, v143, v141
	v_div_scale_f32 v143, vcc, 1.0, v168, 1.0
	v_mul_f32_e32 v148, v143, v141
	v_fma_f32 v165, -v136, v148, v143
	v_fmac_f32_e32 v148, v165, v141
	v_fma_f32 v136, -v136, v148, v143
	v_div_fmas_f32 v136, v136, v141, v148
	v_pk_mul_f32 v[170:171], v[0:1], v[140:141] op_sel_hi:[1,0]
	v_div_fixup_f32 v168, v136, v168, 1.0
	v_mul_f32_e32 v136, 0xbfb8aa3b, v170
	v_exp_f32_e32 v172, v136
	v_mul_f32_e32 v136, 0xbfb8aa3b, v171
	v_exp_f32_e32 v173, v136
	v_pk_mul_f32 v[132:133], v[168:169], v[132:133]
	v_lshlrev_b32_e32 v168, 16, v138
	v_and_b32_e32 v169, 0xffff0000, v138
	v_pk_mul_f32 v[168:169], v[142:143], v[168:169] op_sel_hi:[0,1]
	v_pk_mul_f32 v[128:129], v[128:129], v[168:169]
	v_pk_add_f32 v[168:169], v[172:173], 1.0 op_sel_hi:[1,0]
	v_pk_mul_f32 v[128:129], v[170:171], v[128:129]
	v_div_scale_f32 v136, s[26:27], v169, v169, 1.0
	v_rcp_f32_e32 v138, v136
	s_nop 0
	v_fma_f32 v141, -v136, v138, 1.0
	v_fmac_f32_e32 v138, v141, v138
	v_div_scale_f32 v141, vcc, 1.0, v169, 1.0
	v_mul_f32_e32 v143, v141, v138
	v_fma_f32 v148, -v136, v143, v141
	v_fmac_f32_e32 v143, v148, v138
	v_fma_f32 v136, -v136, v143, v141
	v_div_fmas_f32 v136, v136, v138, v143
	v_div_fixup_f32 v169, v136, v169, 1.0
	v_div_scale_f32 v136, s[26:27], v168, v168, 1.0
	v_rcp_f32_e32 v138, v136
	s_nop 0
	v_fma_f32 v141, -v136, v138, 1.0
	v_fmac_f32_e32 v138, v141, v138
	v_div_scale_f32 v141, vcc, 1.0, v168, 1.0
	v_mul_f32_e32 v143, v141, v138
	v_fma_f32 v148, -v136, v143, v141
	v_fmac_f32_e32 v143, v148, v138
	v_fma_f32 v136, -v136, v143, v141
	v_div_fmas_f32 v136, v136, v138, v143
	v_div_fixup_f32 v168, v136, v168, 1.0
	v_lshlrev_b32_e32 v136, 16, v137
	v_and_b32_e32 v137, 0xffff0000, v137
	v_pk_mul_f32 v[128:129], v[168:169], v[128:129]
	v_pk_mul_f32 v[168:169], v[6:7], v[140:141] op_sel_hi:[1,0]
	v_pk_mul_f32 v[136:137], v[142:143], v[136:137] op_sel_hi:[0,1]
	v_mul_f32_e32 v138, 0xbfb8aa3b, v168
	v_pk_mul_f32 v[134:135], v[134:135], v[136:137]
	v_mul_f32_e32 v136, 0xbfb8aa3b, v169
	v_exp_f32_e32 v170, v138
	v_exp_f32_e32 v171, v136
	v_pk_mul_f32 v[134:135], v[168:169], v[134:135]
	v_pk_add_f32 v[136:137], v[170:171], 1.0 op_sel_hi:[1,0]
	s_nop 0
	v_div_scale_f32 v138, s[26:27], v137, v137, 1.0
	v_rcp_f32_e32 v141, v138
	s_nop 0
	v_fma_f32 v143, -v138, v141, 1.0
	v_fmac_f32_e32 v141, v143, v141
	v_div_scale_f32 v143, vcc, 1.0, v137, 1.0
	v_mul_f32_e32 v148, v143, v141
	v_fma_f32 v165, -v138, v148, v143
	v_fmac_f32_e32 v148, v165, v141
	v_fma_f32 v138, -v138, v148, v143
	v_div_fmas_f32 v138, v138, v141, v148
	v_div_fixup_f32 v137, v138, v137, 1.0
	v_div_scale_f32 v138, s[26:27], v136, v136, 1.0
	v_rcp_f32_e32 v141, v138
	s_nop 0
	v_fma_f32 v143, -v138, v141, 1.0
	v_fmac_f32_e32 v141, v143, v141
	v_div_scale_f32 v143, vcc, 1.0, v136, 1.0
	v_mul_f32_e32 v148, v143, v141
	v_fma_f32 v165, -v138, v148, v143
	v_fmac_f32_e32 v148, v165, v141
	v_fma_f32 v138, -v138, v148, v143
	v_div_fmas_f32 v138, v138, v141, v148
	v_div_fixup_f32 v136, v138, v136, 1.0
	v_pk_mul_f32 v[134:135], v[136:137], v[134:135]
	v_lshlrev_b32_e32 v136, 16, v139
	v_and_b32_e32 v137, 0xffff0000, v139
	v_pk_mul_f32 v[138:139], v[2:3], v[140:141] op_sel_hi:[1,0]
	v_pk_mul_f32 v[136:137], v[142:143], v[136:137] op_sel_hi:[0,1]
	v_mul_f32_e32 v140, 0xbfb8aa3b, v138
	v_pk_mul_f32 v[130:131], v[130:131], v[136:137]
	v_mul_f32_e32 v136, 0xbfb8aa3b, v139
	v_exp_f32_e32 v140, v140
	v_exp_f32_e32 v141, v136
	v_pk_mul_f32 v[130:131], v[138:139], v[130:131]
	v_pk_add_f32 v[136:137], v[140:141], 1.0 op_sel_hi:[1,0]
	s_nop 0
	v_div_scale_f32 v138, s[26:27], v137, v137, 1.0
	v_rcp_f32_e32 v139, v138
	s_nop 0
	v_fma_f32 v140, -v138, v139, 1.0
	v_fmac_f32_e32 v139, v140, v139
	v_div_scale_f32 v140, vcc, 1.0, v137, 1.0
	v_mul_f32_e32 v141, v140, v139
	v_fma_f32 v142, -v138, v141, v140
	v_fmac_f32_e32 v141, v142, v139
	v_fma_f32 v138, -v138, v141, v140
	v_div_fmas_f32 v138, v138, v139, v141
	v_div_fixup_f32 v137, v138, v137, 1.0
	v_div_scale_f32 v138, s[26:27], v136, v136, 1.0
	v_rcp_f32_e32 v139, v138
	s_nop 0
	v_fma_f32 v140, -v138, v139, 1.0
	v_fmac_f32_e32 v139, v140, v139
	v_div_scale_f32 v140, vcc, 1.0, v136, 1.0
	v_mul_f32_e32 v141, v140, v139
	v_fma_f32 v142, -v138, v141, v140
	v_fmac_f32_e32 v141, v142, v139
	v_fma_f32 v138, -v138, v141, v140
	v_div_fmas_f32 v138, v138, v139, v141
	v_div_fixup_f32 v136, v138, v136, 1.0
	v_pk_mul_f32 v[136:137], v[136:137], v[130:131]
	v_cvt_pk_bf16_f32 v130, v132, v133
	v_cvt_pk_bf16_f32 v131, v134, v135
	v_cvt_pk_bf16_f32 v132, v128, v129
	v_cvt_pk_bf16_f32 v133, v136, v137
	global_store_dwordx4 v[180:181], v[130:133], off offset:256
